# v94 + causal-mask skip and compaction in band loops + mid-block s_setprio flip pairs removed in all GEMM K-loops (stack of individually neutral, strictly-less-work edits)
# speedup vs baseline: 1.0011x; 1.0011x over previous
.LBB0_135:
	ds_read_b128 v[128:131], v182
	ds_read_b128 v[132:135], v182 offset:1024
	ds_read_b128 v[136:139], v182 offset:2048
	ds_read_b128 v[140:143], v182 offset:3072
	ds_read_b128 v[144:147], v183
	ds_read_b128 v[148:151], v183 offset:1024
	ds_read_b128 v[188:191], v183 offset:2048
	ds_read_b128 v[192:195], v183 offset:3072
	s_add_u32 s44, s38, 0xfffc0080
	s_addc_u32 s45, s39, -1
	s_cmp_eq_u32 s72, 12
	s_cselect_b32 s47, s12, s45
	s_cselect_b32 s46, s31, s44
	s_cselect_b32 s45, s29, s71
	s_cselect_b32 s44, s41, s43
	v_lshl_add_u64 v[176:177], s[38:39], 0, v[170:171]
	s_add_i32 m0, s54, 0xc000
	ds_read_b128 v[196:199], v184
	ds_read_b128 v[200:203], v184 offset:1024
	ds_read_b128 v[204:207], v184 offset:2048
	ds_read_b128 v[208:211], v184 offset:3072
	ds_read_b128 v[212:215], v184 offset:4096
	ds_read_b128 v[216:219], v184 offset:5120
	ds_read_b128 v[220:223], v184 offset:6144
	ds_read_b128 v[224:227], v184 offset:7168
	global_load_lds_dwordx4 v[176:177], off
	v_lshl_add_u64 v[176:177], s[38:39], 0, v[168:169]
	s_add_i32 m0, s54, 0xe000
	s_nop 0
	global_load_lds_dwordx4 v[176:177], off
	s_waitcnt vmcnt(8)
	s_waitcnt lgkmcnt(0)
	s_barrier
	s_setprio 1
	s_waitcnt lgkmcnt(0)
	v_mfma_f32_16x16x32_bf16 v[124:127], v[128:131], v[196:199], v[124:127]
	v_mfma_f32_16x16x32_bf16 v[120:123], v[136:139], v[196:199], v[120:123]
	v_mfma_f32_16x16x32_bf16 v[108:111], v[128:131], v[204:207], v[108:111]
	v_mfma_f32_16x16x32_bf16 v[104:107], v[136:139], v[204:207], v[104:107]
	v_mfma_f32_16x16x32_bf16 v[92:95], v[128:131], v[212:215], v[92:95]
	v_mfma_f32_16x16x32_bf16 v[88:91], v[136:139], v[212:215], v[88:91]
	v_mfma_f32_16x16x32_bf16 v[76:79], v[128:131], v[220:223], v[76:79]
	v_mfma_f32_16x16x32_bf16 v[72:75], v[136:139], v[220:223], v[72:75]
	v_mfma_f32_16x16x32_bf16 v[124:127], v[132:135], v[200:203], v[124:127]
	v_mfma_f32_16x16x32_bf16 v[120:123], v[140:143], v[200:203], v[120:123]
	v_mfma_f32_16x16x32_bf16 v[108:111], v[132:135], v[208:211], v[108:111]
	v_mfma_f32_16x16x32_bf16 v[104:107], v[140:143], v[208:211], v[104:107]
	v_mfma_f32_16x16x32_bf16 v[92:95], v[132:135], v[216:219], v[92:95]
	v_mfma_f32_16x16x32_bf16 v[88:91], v[140:143], v[216:219], v[88:91]
	v_mfma_f32_16x16x32_bf16 v[76:79], v[132:135], v[224:227], v[76:79]
	v_mfma_f32_16x16x32_bf16 v[72:75], v[140:143], v[224:227], v[72:75]
	v_mfma_f32_16x16x32_bf16 v[116:119], v[144:147], v[196:199], v[116:119]
	v_mfma_f32_16x16x32_bf16 v[112:115], v[188:191], v[196:199], v[112:115]
	v_mfma_f32_16x16x32_bf16 v[100:103], v[144:147], v[204:207], v[100:103]
	v_mfma_f32_16x16x32_bf16 v[96:99], v[188:191], v[204:207], v[96:99]
	v_mfma_f32_16x16x32_bf16 v[84:87], v[144:147], v[212:215], v[84:87]
	v_mfma_f32_16x16x32_bf16 v[80:83], v[188:191], v[212:215], v[80:83]
	v_mfma_f32_16x16x32_bf16 v[68:71], v[144:147], v[220:223], v[68:71]
	v_mfma_f32_16x16x32_bf16 v[64:67], v[188:191], v[220:223], v[64:67]
	v_mfma_f32_16x16x32_bf16 v[116:119], v[148:151], v[200:203], v[116:119]
	v_mfma_f32_16x16x32_bf16 v[112:115], v[192:195], v[200:203], v[112:115]
	v_mfma_f32_16x16x32_bf16 v[100:103], v[148:151], v[208:211], v[100:103]
	v_mfma_f32_16x16x32_bf16 v[96:99], v[192:195], v[208:211], v[96:99]
	v_mfma_f32_16x16x32_bf16 v[84:87], v[148:151], v[216:219], v[84:87]
	v_mfma_f32_16x16x32_bf16 v[80:83], v[192:195], v[216:219], v[80:83]
	v_mfma_f32_16x16x32_bf16 v[68:71], v[148:151], v[224:227], v[68:71]
	v_mfma_f32_16x16x32_bf16 v[64:67], v[192:195], v[224:227], v[64:67]
	s_setprio 0
	s_barrier
	s_add_i32 s73, s68, s53
	v_lshl_add_u64 v[176:177], s[44:45], 0, v[154:155]
	s_mov_b32 m0, s73
	ds_read_b128 v[196:199], v184 offset:16384
	ds_read_b128 v[200:203], v184 offset:17408
	ds_read_b128 v[204:207], v184 offset:18432
	ds_read_b128 v[208:211], v184 offset:19456
	ds_read_b128 v[212:215], v184 offset:20480
	ds_read_b128 v[216:219], v184 offset:21504
	ds_read_b128 v[220:223], v184 offset:22528
	ds_read_b128 v[224:227], v184 offset:23552
	global_load_lds_dwordx4 v[176:177], off
	s_add_i32 m0, s73, 0x2000
	s_add_u32 s74, s44, 0x40000
	v_lshl_add_u64 v[228:229], s[44:45], 0, v[158:159]
	s_addc_u32 s75, s45, 0
	s_add_i32 s73, s69, s53
	global_load_lds_dwordx4 v[228:229], off
	v_lshl_add_u64 v[230:231], s[74:75], 0, v[154:155]
	s_mov_b32 m0, s73
	v_lshl_add_u64 v[232:233], s[46:47], 0, v[156:157]
	global_load_lds_dwordx4 v[230:231], off
	v_lshl_add_u64 v[230:231], s[74:75], 0, v[158:159]
	s_add_i32 m0, s73, 0x2000
	s_nop 0
	global_load_lds_dwordx4 v[230:231], off
	v_lshl_add_u64 v[230:231], s[46:47], 0, v[152:153]
	s_mov_b32 m0, s54
	s_nop 0
	global_load_lds_dwordx4 v[230:231], off
	s_mov_b32 m0, s55
	s_nop 0
	global_load_lds_dwordx4 v[232:233], off
	s_waitcnt vmcnt(8)
	s_waitcnt lgkmcnt(0)
	s_barrier
	s_setprio 1
	s_waitcnt lgkmcnt(0)
	v_mfma_f32_16x16x32_bf16 v[60:63], v[128:131], v[196:199], v[60:63]
	v_mfma_f32_16x16x32_bf16 v[56:59], v[136:139], v[196:199], v[56:59]
	v_mfma_f32_16x16x32_bf16 v[44:47], v[128:131], v[204:207], v[44:47]
	v_mfma_f32_16x16x32_bf16 v[40:43], v[136:139], v[204:207], v[40:43]
	v_mfma_f32_16x16x32_bf16 v[28:31], v[128:131], v[212:215], v[28:31]
	v_mfma_f32_16x16x32_bf16 v[24:27], v[136:139], v[212:215], v[24:27]
	v_mfma_f32_16x16x32_bf16 v[12:15], v[128:131], v[220:223], v[12:15]
	v_mfma_f32_16x16x32_bf16 v[8:11], v[136:139], v[220:223], v[8:11]
	v_mfma_f32_16x16x32_bf16 v[60:63], v[132:135], v[200:203], v[60:63]
	v_mfma_f32_16x16x32_bf16 v[56:59], v[140:143], v[200:203], v[56:59]
	v_mfma_f32_16x16x32_bf16 v[44:47], v[132:135], v[208:211], v[44:47]
	v_mfma_f32_16x16x32_bf16 v[40:43], v[140:143], v[208:211], v[40:43]
	v_mfma_f32_16x16x32_bf16 v[28:31], v[132:135], v[216:219], v[28:31]
	v_mfma_f32_16x16x32_bf16 v[24:27], v[140:143], v[216:219], v[24:27]
	v_mfma_f32_16x16x32_bf16 v[12:15], v[132:135], v[224:227], v[12:15]
	v_mfma_f32_16x16x32_bf16 v[8:11], v[140:143], v[224:227], v[8:11]
	v_mfma_f32_16x16x32_bf16 v[52:55], v[144:147], v[196:199], v[52:55]
	v_mfma_f32_16x16x32_bf16 v[48:51], v[188:191], v[196:199], v[48:51]
	v_mfma_f32_16x16x32_bf16 v[36:39], v[144:147], v[204:207], v[36:39]
	v_mfma_f32_16x16x32_bf16 v[32:35], v[188:191], v[204:207], v[32:35]
	v_mfma_f32_16x16x32_bf16 v[20:23], v[144:147], v[212:215], v[20:23]
	v_mfma_f32_16x16x32_bf16 v[16:19], v[188:191], v[212:215], v[16:19]
	v_mfma_f32_16x16x32_bf16 v[4:7], v[144:147], v[220:223], v[4:7]
	v_mfma_f32_16x16x32_bf16 v[0:3], v[188:191], v[220:223], v[0:3]
	v_mfma_f32_16x16x32_bf16 v[52:55], v[148:151], v[200:203], v[52:55]
	v_mfma_f32_16x16x32_bf16 v[48:51], v[192:195], v[200:203], v[48:51]
	v_mfma_f32_16x16x32_bf16 v[36:39], v[148:151], v[208:211], v[36:39]
	v_mfma_f32_16x16x32_bf16 v[32:35], v[192:195], v[208:211], v[32:35]
	v_mfma_f32_16x16x32_bf16 v[20:23], v[148:151], v[216:219], v[20:23]
	v_mfma_f32_16x16x32_bf16 v[16:19], v[192:195], v[216:219], v[16:19]
	v_mfma_f32_16x16x32_bf16 v[4:7], v[148:151], v[224:227], v[4:7]
	v_mfma_f32_16x16x32_bf16 v[0:3], v[192:195], v[224:227], v[0:3]
	s_setprio 0
	s_barrier
	s_add_i32 s73, 0, 0x18000
	s_add_i32 s74, 0, 0x1c000
	v_add_u32_e32 v140, s73, v180
	v_add_u32_e32 v160, s74, v180
	ds_read_b128 v[128:131], v140
	ds_read_b128 v[132:135], v140 offset:1024
	ds_read_b128 v[136:139], v140 offset:2048
	ds_read_b128 v[140:143], v140 offset:3072
	ds_read_b128 v[144:147], v160
	ds_read_b128 v[148:151], v160 offset:1024
	ds_read_b128 v[188:191], v160 offset:2048
	ds_read_b128 v[192:195], v160 offset:3072
	s_add_u32 s46, s46, 0x40000
	s_addc_u32 s47, s47, 0
	s_mov_b32 m0, s56
	v_lshl_add_u64 v[234:235], s[46:47], 0, v[152:153]
	ds_read_b128 v[196:199], v184 offset:32768
	ds_read_b128 v[200:203], v184 offset:33792
	ds_read_b128 v[204:207], v184 offset:34816
	ds_read_b128 v[208:211], v184 offset:35840
	ds_read_b128 v[212:215], v184 offset:36864
	ds_read_b128 v[216:219], v184 offset:37888
	ds_read_b128 v[220:223], v184 offset:38912
	ds_read_b128 v[224:227], v184 offset:39936
	global_load_lds_dwordx4 v[234:235], off
	v_lshl_add_u64 v[234:235], s[46:47], 0, v[156:157]
	s_mov_b32 m0, s57
	s_nop 0
	global_load_lds_dwordx4 v[234:235], off
	s_waitcnt vmcnt(8)
	s_waitcnt lgkmcnt(0)
	s_barrier
	s_setprio 1
	s_waitcnt lgkmcnt(0)
	v_mfma_f32_16x16x32_bf16 v[124:127], v[128:131], v[196:199], v[124:127]
	v_mfma_f32_16x16x32_bf16 v[120:123], v[136:139], v[196:199], v[120:123]
	v_mfma_f32_16x16x32_bf16 v[108:111], v[128:131], v[204:207], v[108:111]
	v_mfma_f32_16x16x32_bf16 v[104:107], v[136:139], v[204:207], v[104:107]
	v_mfma_f32_16x16x32_bf16 v[92:95], v[128:131], v[212:215], v[92:95]
	v_mfma_f32_16x16x32_bf16 v[88:91], v[136:139], v[212:215], v[88:91]
	v_mfma_f32_16x16x32_bf16 v[76:79], v[128:131], v[220:223], v[76:79]
	v_mfma_f32_16x16x32_bf16 v[72:75], v[136:139], v[220:223], v[72:75]
	v_mfma_f32_16x16x32_bf16 v[124:127], v[132:135], v[200:203], v[124:127]
	v_mfma_f32_16x16x32_bf16 v[120:123], v[140:143], v[200:203], v[120:123]
	v_mfma_f32_16x16x32_bf16 v[108:111], v[132:135], v[208:211], v[108:111]
	v_mfma_f32_16x16x32_bf16 v[104:107], v[140:143], v[208:211], v[104:107]
	v_mfma_f32_16x16x32_bf16 v[92:95], v[132:135], v[216:219], v[92:95]
	v_mfma_f32_16x16x32_bf16 v[88:91], v[140:143], v[216:219], v[88:91]
	v_mfma_f32_16x16x32_bf16 v[76:79], v[132:135], v[224:227], v[76:79]
	v_mfma_f32_16x16x32_bf16 v[72:75], v[140:143], v[224:227], v[72:75]
	v_mfma_f32_16x16x32_bf16 v[116:119], v[144:147], v[196:199], v[116:119]
	v_mfma_f32_16x16x32_bf16 v[112:115], v[188:191], v[196:199], v[112:115]
	v_mfma_f32_16x16x32_bf16 v[100:103], v[144:147], v[204:207], v[100:103]
	v_mfma_f32_16x16x32_bf16 v[96:99], v[188:191], v[204:207], v[96:99]
	v_mfma_f32_16x16x32_bf16 v[84:87], v[144:147], v[212:215], v[84:87]
	v_mfma_f32_16x16x32_bf16 v[80:83], v[188:191], v[212:215], v[80:83]
	v_mfma_f32_16x16x32_bf16 v[68:71], v[144:147], v[220:223], v[68:71]
	v_mfma_f32_16x16x32_bf16 v[64:67], v[188:191], v[220:223], v[64:67]
	v_mfma_f32_16x16x32_bf16 v[116:119], v[148:151], v[200:203], v[116:119]
	v_mfma_f32_16x16x32_bf16 v[112:115], v[192:195], v[200:203], v[112:115]
	v_mfma_f32_16x16x32_bf16 v[100:103], v[148:151], v[208:211], v[100:103]
	v_mfma_f32_16x16x32_bf16 v[96:99], v[192:195], v[208:211], v[96:99]
	v_mfma_f32_16x16x32_bf16 v[84:87], v[148:151], v[216:219], v[84:87]
	v_mfma_f32_16x16x32_bf16 v[80:83], v[192:195], v[216:219], v[80:83]
	v_mfma_f32_16x16x32_bf16 v[68:71], v[148:151], v[224:227], v[68:71]
	v_mfma_f32_16x16x32_bf16 v[64:67], v[192:195], v[224:227], v[64:67]
	s_setprio 0
	s_barrier
	s_add_i32 s46, s73, s53
	v_lshl_add_u64 v[176:177], v[176:177], 0, s[22:23]
	s_mov_b32 m0, s46
	ds_read_b128 v[196:199], v184 offset:49152
	ds_read_b128 v[200:203], v184 offset:50176
	ds_read_b128 v[204:207], v184 offset:51200
	ds_read_b128 v[208:211], v184 offset:52224
	ds_read_b128 v[212:215], v184 offset:53248
	ds_read_b128 v[216:219], v184 offset:54272
	ds_read_b128 v[220:223], v184 offset:55296
	ds_read_b128 v[224:227], v184 offset:56320
	global_load_lds_dwordx4 v[176:177], off
	s_add_i32 m0, s46, 0x2000
	s_add_u32 s44, s44, 0x40080
	v_lshl_add_u64 v[176:177], v[228:229], 0, s[22:23]
	s_addc_u32 s45, s45, 0
	s_add_i32 s46, s74, s53
	global_load_lds_dwordx4 v[176:177], off
	v_lshl_add_u64 v[176:177], s[44:45], 0, v[154:155]
	s_mov_b32 m0, s46
	s_nop 0
	global_load_lds_dwordx4 v[176:177], off
	v_lshl_add_u64 v[176:177], s[44:45], 0, v[158:159]
	s_add_i32 m0, s46, 0x2000
	s_nop 0
	global_load_lds_dwordx4 v[176:177], off
	v_lshl_add_u64 v[176:177], v[230:231], 0, s[22:23]
	s_mov_b32 m0, s62
	s_nop 0
	global_load_lds_dwordx4 v[176:177], off
	v_lshl_add_u64 v[176:177], v[232:233], 0, s[22:23]
	s_mov_b32 m0, s63
	s_nop 0
	global_load_lds_dwordx4 v[176:177], off
	s_waitcnt vmcnt(8)
	s_waitcnt lgkmcnt(0)
	s_barrier
	s_setprio 1
	s_waitcnt lgkmcnt(0)
	v_mfma_f32_16x16x32_bf16 v[60:63], v[128:131], v[196:199], v[60:63]
	v_mfma_f32_16x16x32_bf16 v[56:59], v[136:139], v[196:199], v[56:59]
	v_mfma_f32_16x16x32_bf16 v[44:47], v[128:131], v[204:207], v[44:47]
	v_mfma_f32_16x16x32_bf16 v[40:43], v[136:139], v[204:207], v[40:43]
	v_mfma_f32_16x16x32_bf16 v[28:31], v[128:131], v[212:215], v[28:31]
	v_mfma_f32_16x16x32_bf16 v[24:27], v[136:139], v[212:215], v[24:27]
	v_mfma_f32_16x16x32_bf16 v[12:15], v[128:131], v[220:223], v[12:15]
	v_mfma_f32_16x16x32_bf16 v[8:11], v[136:139], v[220:223], v[8:11]
	v_mfma_f32_16x16x32_bf16 v[60:63], v[132:135], v[200:203], v[60:63]
	v_mfma_f32_16x16x32_bf16 v[56:59], v[140:143], v[200:203], v[56:59]
	v_mfma_f32_16x16x32_bf16 v[44:47], v[132:135], v[208:211], v[44:47]
	v_mfma_f32_16x16x32_bf16 v[40:43], v[140:143], v[208:211], v[40:43]
	v_mfma_f32_16x16x32_bf16 v[28:31], v[132:135], v[216:219], v[28:31]
	v_mfma_f32_16x16x32_bf16 v[24:27], v[140:143], v[216:219], v[24:27]
	v_mfma_f32_16x16x32_bf16 v[12:15], v[132:135], v[224:227], v[12:15]
	v_mfma_f32_16x16x32_bf16 v[8:11], v[140:143], v[224:227], v[8:11]
	v_mfma_f32_16x16x32_bf16 v[52:55], v[144:147], v[196:199], v[52:55]
	v_mfma_f32_16x16x32_bf16 v[48:51], v[188:191], v[196:199], v[48:51]
	v_mfma_f32_16x16x32_bf16 v[36:39], v[144:147], v[204:207], v[36:39]
	v_mfma_f32_16x16x32_bf16 v[32:35], v[188:191], v[204:207], v[32:35]
	v_mfma_f32_16x16x32_bf16 v[20:23], v[144:147], v[212:215], v[20:23]
	v_mfma_f32_16x16x32_bf16 v[16:19], v[188:191], v[212:215], v[16:19]
	v_mfma_f32_16x16x32_bf16 v[4:7], v[144:147], v[220:223], v[4:7]
	v_mfma_f32_16x16x32_bf16 v[0:3], v[188:191], v[220:223], v[0:3]
	v_mfma_f32_16x16x32_bf16 v[52:55], v[148:151], v[200:203], v[52:55]
	v_mfma_f32_16x16x32_bf16 v[48:51], v[192:195], v[200:203], v[48:51]
	v_mfma_f32_16x16x32_bf16 v[36:39], v[148:151], v[208:211], v[36:39]
	v_mfma_f32_16x16x32_bf16 v[32:35], v[192:195], v[208:211], v[32:35]
	v_mfma_f32_16x16x32_bf16 v[20:23], v[148:151], v[216:219], v[20:23]
	v_mfma_f32_16x16x32_bf16 v[16:19], v[192:195], v[216:219], v[16:19]
	v_mfma_f32_16x16x32_bf16 v[4:7], v[148:151], v[224:227], v[4:7]
	v_mfma_f32_16x16x32_bf16 v[0:3], v[192:195], v[224:227], v[0:3]
	s_setprio 0
	s_barrier
	s_add_i32 s72, s72, 2
	s_add_u32 s43, s43, 0x100
	s_addc_u32 s71, s71, 0
	s_add_u32 s38, s38, 0x100
	s_addc_u32 s39, s39, 0
	s_cmp_gt_u32 s72, 13
	s_cbranch_scc0 .LBB0_135
	s_and_b64 vcc, exec, s[24:25]
	s_cbranch_vccz .LBB0_138
	s_barrier

.LBB0_724:
	ds_read_b128 v[0:3], v143
	ds_read_b128 v[4:7], v143 offset:1024
	ds_read_b128 v[8:11], v143 offset:2048
	ds_read_b128 v[12:15], v143 offset:3072
	ds_read_b128 v[16:19], v144
	ds_read_b128 v[20:23], v144 offset:1024
	ds_read_b128 v[24:27], v144 offset:2048
	ds_read_b128 v[28:31], v144 offset:3072
	s_ashr_i32 s39, s38, 31
	s_lshl_b64 s[40:41], s[38:39], 17
	s_add_u32 s40, s57, s40
	s_addc_u32 s41, s58, s41
	s_and_b64 s[44:45], s[42:43], exec
	s_cselect_b32 s53, s41, s47
	s_cselect_b32 s52, s40, s46
	s_ashr_i32 s37, s36, 31
	s_lshl_b64 s[44:45], s[36:37], 17
	s_add_u32 s44, s19, s44
	s_addc_u32 s45, s56, s45
	s_and_b64 s[50:51], s[42:43], exec
	s_cselect_b32 s51, s45, s49
	s_cselect_b32 s50, s44, s48
	s_add_u32 s72, s46, 0x10080
	s_addc_u32 s73, s47, 0
	s_mov_b32 m0, s67
	v_lshl_add_u64 v[64:65], s[72:73], 0, v[128:129]
	ds_read_b128 v[32:35], v145
	ds_read_b128 v[36:39], v145 offset:1024
	ds_read_b128 v[40:43], v145 offset:2048
	ds_read_b128 v[44:47], v145 offset:3072
	ds_read_b128 v[48:51], v145 offset:4096
	ds_read_b128 v[52:55], v145 offset:5120
	ds_read_b128 v[56:59], v145 offset:6144
	ds_read_b128 v[60:63], v145 offset:7168
	global_load_lds_dwordx4 v[64:65], off
	v_lshl_add_u64 v[64:65], s[72:73], 0, v[132:133]
	s_mov_b32 m0, s68
	s_nop 0
	global_load_lds_dwordx4 v[64:65], off
	s_waitcnt vmcnt(8)
	s_waitcnt lgkmcnt(0)
	s_barrier
	s_setprio 1
	s_waitcnt lgkmcnt(0)
	v_mfma_f32_16x16x32_bf16 v[64:67], v[0:3], v[32:35], 0
	v_mfma_f32_16x16x32_bf16 v[68:71], v[8:11], v[32:35], 0
	v_mfma_f32_16x16x32_bf16 v[72:75], v[0:3], v[40:43], 0
	v_mfma_f32_16x16x32_bf16 v[76:79], v[8:11], v[40:43], 0
	v_mfma_f32_16x16x32_bf16 v[80:83], v[0:3], v[48:51], 0
	v_mfma_f32_16x16x32_bf16 v[84:87], v[8:11], v[48:51], 0
	v_mfma_f32_16x16x32_bf16 v[88:91], v[0:3], v[56:59], 0
	v_mfma_f32_16x16x32_bf16 v[92:95], v[8:11], v[56:59], 0
	v_mfma_f32_16x16x32_bf16 v[64:67], v[4:7], v[36:39], v[64:67]
	v_mfma_f32_16x16x32_bf16 v[68:71], v[12:15], v[36:39], v[68:71]
	v_mfma_f32_16x16x32_bf16 v[72:75], v[4:7], v[44:47], v[72:75]
	v_mfma_f32_16x16x32_bf16 v[76:79], v[12:15], v[44:47], v[76:79]
	v_mfma_f32_16x16x32_bf16 v[80:83], v[4:7], v[52:55], v[80:83]
	v_mfma_f32_16x16x32_bf16 v[84:87], v[12:15], v[52:55], v[84:87]
	v_mfma_f32_16x16x32_bf16 v[88:91], v[4:7], v[60:63], v[88:91]
	v_mfma_f32_16x16x32_bf16 v[92:95], v[12:15], v[60:63], v[92:95]
	v_mfma_f32_16x16x32_bf16 v[96:99], v[16:19], v[32:35], 0
	v_mfma_f32_16x16x32_bf16 v[32:35], v[24:27], v[32:35], 0
	v_mfma_f32_16x16x32_bf16 v[96:99], v[20:23], v[36:39], v[96:99]
	v_mfma_f32_16x16x32_bf16 v[32:35], v[28:31], v[36:39], v[32:35]
	v_mfma_f32_16x16x32_bf16 v[36:39], v[16:19], v[40:43], 0
	v_mfma_f32_16x16x32_bf16 v[40:43], v[24:27], v[40:43], 0
	v_mfma_f32_16x16x32_bf16 v[36:39], v[20:23], v[44:47], v[36:39]
	v_mfma_f32_16x16x32_bf16 v[40:43], v[28:31], v[44:47], v[40:43]
	v_mfma_f32_16x16x32_bf16 v[44:47], v[16:19], v[48:51], 0
	v_mfma_f32_16x16x32_bf16 v[48:51], v[24:27], v[48:51], 0
	v_mfma_f32_16x16x32_bf16 v[44:47], v[20:23], v[52:55], v[44:47]
	v_mfma_f32_16x16x32_bf16 v[48:51], v[28:31], v[52:55], v[48:51]
	v_mfma_f32_16x16x32_bf16 v[52:55], v[16:19], v[56:59], 0
	v_mfma_f32_16x16x32_bf16 v[56:59], v[24:27], v[56:59], 0
	v_mfma_f32_16x16x32_bf16 v[52:55], v[20:23], v[60:63], v[52:55]
	v_mfma_f32_16x16x32_bf16 v[56:59], v[28:31], v[60:63], v[56:59]
	s_setprio 0
	s_barrier
	v_lshl_add_u64 v[138:139], s[48:49], 0, v[130:131]
	s_mov_b32 m0, s69
	v_lshl_add_u64 v[146:147], v[138:139], 0, s[26:27]
	v_lshl_add_u64 v[210:211], s[48:49], 0, v[134:135]
	s_add_u32 s72, s48, 0x10100
	ds_read_b128 v[60:63], v145 offset:16384
	ds_read_b128 v[100:103], v145 offset:17408
	ds_read_b128 v[104:107], v145 offset:18432
	ds_read_b128 v[108:111], v145 offset:19456
	ds_read_b128 v[112:115], v145 offset:20480
	ds_read_b128 v[116:119], v145 offset:21504
	ds_read_b128 v[120:123], v145 offset:22528
	ds_read_b128 v[124:127], v145 offset:23552
	global_load_lds_dwordx4 v[146:147], off
	v_lshl_add_u64 v[146:147], v[210:211], 0, s[26:27]
	s_mov_b32 m0, s70
	s_addc_u32 s73, s49, 0
	s_add_i32 s31, s66, s59
	global_load_lds_dwordx4 v[146:147], off
	v_lshl_add_u64 v[146:147], s[72:73], 0, v[130:131]
	s_mov_b32 m0, s31
	s_add_i32 s37, s31, 0x2000
	global_load_lds_dwordx4 v[146:147], off
	v_lshl_add_u64 v[146:147], s[72:73], 0, v[134:135]
	s_mov_b32 m0, s37
	v_lshl_add_u64 v[212:213], s[46:47], 0, v[128:129]
	global_load_lds_dwordx4 v[146:147], off
	v_lshl_add_u64 v[146:147], v[212:213], 0, s[26:27]
	s_mov_b32 m0, s35
	v_lshl_add_u64 v[214:215], s[46:47], 0, v[132:133]
	global_load_lds_dwordx4 v[146:147], off
	v_lshl_add_u64 v[146:147], v[214:215], 0, s[26:27]
	s_mov_b32 m0, s60
	s_nop 0
	global_load_lds_dwordx4 v[146:147], off
	s_waitcnt vmcnt(8)
	s_waitcnt lgkmcnt(0)
	s_barrier
	s_setprio 1
	s_waitcnt lgkmcnt(0)
	v_mfma_f32_16x16x32_bf16 v[146:149], v[0:3], v[60:63], 0
	v_mfma_f32_16x16x32_bf16 v[154:157], v[0:3], v[104:107], 0
	v_mfma_f32_16x16x32_bf16 v[162:165], v[0:3], v[112:115], 0
	v_mfma_f32_16x16x32_bf16 v[0:3], v[0:3], v[120:123], 0
	v_mfma_f32_16x16x32_bf16 v[146:149], v[4:7], v[100:103], v[146:149]
	v_mfma_f32_16x16x32_bf16 v[154:157], v[4:7], v[108:111], v[154:157]
	v_mfma_f32_16x16x32_bf16 v[162:165], v[4:7], v[116:119], v[162:165]
	v_mfma_f32_16x16x32_bf16 v[0:3], v[4:7], v[124:127], v[0:3]
	v_mfma_f32_16x16x32_bf16 v[4:7], v[8:11], v[120:123], 0
	v_mfma_f32_16x16x32_bf16 v[150:153], v[8:11], v[60:63], 0
	v_mfma_f32_16x16x32_bf16 v[158:161], v[8:11], v[104:107], 0
	v_mfma_f32_16x16x32_bf16 v[166:169], v[8:11], v[112:115], 0
	v_mfma_f32_16x16x32_bf16 v[4:7], v[12:15], v[124:127], v[4:7]
	v_mfma_f32_16x16x32_bf16 v[150:153], v[12:15], v[100:103], v[150:153]
	v_mfma_f32_16x16x32_bf16 v[158:161], v[12:15], v[108:111], v[158:161]
	v_mfma_f32_16x16x32_bf16 v[166:169], v[12:15], v[116:119], v[166:169]
	v_mfma_f32_16x16x32_bf16 v[8:11], v[16:19], v[60:63], 0
	v_mfma_f32_16x16x32_bf16 v[12:15], v[24:27], v[60:63], 0
	v_mfma_f32_16x16x32_bf16 v[8:11], v[20:23], v[100:103], v[8:11]
	v_mfma_f32_16x16x32_bf16 v[12:15], v[28:31], v[100:103], v[12:15]
	v_mfma_f32_16x16x32_bf16 v[60:63], v[16:19], v[104:107], 0
	v_mfma_f32_16x16x32_bf16 v[100:103], v[24:27], v[104:107], 0
	v_mfma_f32_16x16x32_bf16 v[104:107], v[16:19], v[112:115], 0
	v_mfma_f32_16x16x32_bf16 v[16:19], v[16:19], v[120:123], 0
	v_mfma_f32_16x16x32_bf16 v[60:63], v[20:23], v[108:111], v[60:63]
	v_mfma_f32_16x16x32_bf16 v[100:103], v[28:31], v[108:111], v[100:103]
	v_mfma_f32_16x16x32_bf16 v[104:107], v[20:23], v[116:119], v[104:107]
	v_mfma_f32_16x16x32_bf16 v[108:111], v[24:27], v[112:115], 0
	v_mfma_f32_16x16x32_bf16 v[16:19], v[20:23], v[124:127], v[16:19]
	v_mfma_f32_16x16x32_bf16 v[20:23], v[24:27], v[120:123], 0
	v_mfma_f32_16x16x32_bf16 v[108:111], v[28:31], v[116:119], v[108:111]
	v_mfma_f32_16x16x32_bf16 v[20:23], v[28:31], v[124:127], v[20:23]
	s_setprio 0
	s_barrier
	s_add_i32 s71, 0, 0x18000
	s_add_i32 s74, 0, 0x1c000
	v_add_u32_e32 v222, s71, v141
	v_add_u32_e32 v230, s74, v141
	ds_read_b128 v[24:27], v222
	ds_read_b128 v[28:31], v222 offset:1024
	ds_read_b128 v[112:115], v222 offset:2048
	ds_read_b128 v[116:119], v222 offset:3072
	ds_read_b128 v[120:123], v230
	ds_read_b128 v[124:127], v230 offset:1024
	ds_read_b128 v[170:173], v230 offset:2048
	ds_read_b128 v[174:177], v230 offset:3072
	s_add_u32 s72, s46, 0x10100
	s_addc_u32 s73, s47, 0
	s_mov_b32 m0, s61
	v_lshl_add_u64 v[216:217], s[72:73], 0, v[128:129]
	ds_read_b128 v[178:181], v145 offset:32768
	ds_read_b128 v[182:185], v145 offset:33792
	ds_read_b128 v[186:189], v145 offset:34816
	ds_read_b128 v[190:193], v145 offset:35840
	ds_read_b128 v[194:197], v145 offset:36864
	ds_read_b128 v[198:201], v145 offset:37888
	ds_read_b128 v[202:205], v145 offset:38912
	ds_read_b128 v[206:209], v145 offset:39936
	global_load_lds_dwordx4 v[216:217], off
	v_lshl_add_u64 v[216:217], s[72:73], 0, v[132:133]
	s_mov_b32 m0, s62
	s_nop 0
	global_load_lds_dwordx4 v[216:217], off
	s_waitcnt vmcnt(8)
	s_waitcnt lgkmcnt(0)
	s_barrier
	s_setprio 1
	s_waitcnt lgkmcnt(0)
	v_mfma_f32_16x16x32_bf16 v[64:67], v[24:27], v[178:181], v[64:67]
	v_mfma_f32_16x16x32_bf16 v[68:71], v[112:115], v[178:181], v[68:71]
	v_mfma_f32_16x16x32_bf16 v[72:75], v[24:27], v[186:189], v[72:75]
	v_mfma_f32_16x16x32_bf16 v[76:79], v[112:115], v[186:189], v[76:79]
	v_mfma_f32_16x16x32_bf16 v[80:83], v[24:27], v[194:197], v[80:83]
	v_mfma_f32_16x16x32_bf16 v[84:87], v[112:115], v[194:197], v[84:87]
	v_mfma_f32_16x16x32_bf16 v[88:91], v[24:27], v[202:205], v[88:91]
	v_mfma_f32_16x16x32_bf16 v[92:95], v[112:115], v[202:205], v[92:95]
	v_mfma_f32_16x16x32_bf16 v[64:67], v[28:31], v[182:185], v[64:67]
	v_mfma_f32_16x16x32_bf16 v[68:71], v[116:119], v[182:185], v[68:71]
	v_mfma_f32_16x16x32_bf16 v[72:75], v[28:31], v[190:193], v[72:75]
	v_mfma_f32_16x16x32_bf16 v[76:79], v[116:119], v[190:193], v[76:79]
	v_mfma_f32_16x16x32_bf16 v[80:83], v[28:31], v[198:201], v[80:83]
	v_mfma_f32_16x16x32_bf16 v[84:87], v[116:119], v[198:201], v[84:87]
	v_mfma_f32_16x16x32_bf16 v[88:91], v[28:31], v[206:209], v[88:91]
	v_mfma_f32_16x16x32_bf16 v[92:95], v[116:119], v[206:209], v[92:95]
	v_mfma_f32_16x16x32_bf16 v[96:99], v[120:123], v[178:181], v[96:99]
	v_mfma_f32_16x16x32_bf16 v[32:35], v[170:173], v[178:181], v[32:35]
	v_mfma_f32_16x16x32_bf16 v[36:39], v[120:123], v[186:189], v[36:39]
	v_mfma_f32_16x16x32_bf16 v[40:43], v[170:173], v[186:189], v[40:43]
	v_mfma_f32_16x16x32_bf16 v[44:47], v[120:123], v[194:197], v[44:47]
	v_mfma_f32_16x16x32_bf16 v[48:51], v[170:173], v[194:197], v[48:51]
	v_mfma_f32_16x16x32_bf16 v[52:55], v[120:123], v[202:205], v[52:55]
	v_mfma_f32_16x16x32_bf16 v[56:59], v[170:173], v[202:205], v[56:59]
	v_mfma_f32_16x16x32_bf16 v[96:99], v[124:127], v[182:185], v[96:99]
	v_mfma_f32_16x16x32_bf16 v[32:35], v[174:177], v[182:185], v[32:35]
	v_mfma_f32_16x16x32_bf16 v[36:39], v[124:127], v[190:193], v[36:39]
	v_mfma_f32_16x16x32_bf16 v[40:43], v[174:177], v[190:193], v[40:43]
	v_mfma_f32_16x16x32_bf16 v[44:47], v[124:127], v[198:201], v[44:47]
	v_mfma_f32_16x16x32_bf16 v[48:51], v[174:177], v[198:201], v[48:51]
	v_mfma_f32_16x16x32_bf16 v[52:55], v[124:127], v[206:209], v[52:55]
	v_mfma_f32_16x16x32_bf16 v[56:59], v[174:177], v[206:209], v[56:59]
	s_setprio 0
	s_barrier
	s_add_i32 s71, s71, s59
	s_add_i32 s39, s71, 0x2000
	v_lshl_add_u64 v[138:139], v[138:139], 0, s[28:29]
	s_mov_b32 m0, s71
	s_add_u32 s72, s48, 0x10180
	ds_read_b128 v[178:181], v145 offset:49152
	ds_read_b128 v[182:185], v145 offset:50176
	ds_read_b128 v[186:189], v145 offset:51200
	ds_read_b128 v[190:193], v145 offset:52224
	ds_read_b128 v[194:197], v145 offset:53248
	ds_read_b128 v[198:201], v145 offset:54272
	ds_read_b128 v[202:205], v145 offset:55296
	ds_read_b128 v[206:209], v145 offset:56320
	global_load_lds_dwordx4 v[138:139], off
	v_lshl_add_u64 v[138:139], v[210:211], 0, s[28:29]
	s_mov_b32 m0, s39
	s_addc_u32 s73, s49, 0
	s_add_i32 s48, s74, s59
	global_load_lds_dwordx4 v[138:139], off
	v_lshl_add_u64 v[138:139], s[72:73], 0, v[130:131]
	s_mov_b32 m0, s48
	s_add_i32 s49, s48, 0x2000
	global_load_lds_dwordx4 v[138:139], off
	v_lshl_add_u64 v[138:139], s[72:73], 0, v[134:135]
	s_mov_b32 m0, s49
	s_nop 0
	global_load_lds_dwordx4 v[138:139], off
	v_lshl_add_u64 v[138:139], v[212:213], 0, s[28:29]
	s_mov_b32 m0, s63
	s_nop 0
	global_load_lds_dwordx4 v[138:139], off
	v_lshl_add_u64 v[138:139], v[214:215], 0, s[28:29]
	s_mov_b32 m0, s64
	s_nop 0
	global_load_lds_dwordx4 v[138:139], off
	s_waitcnt vmcnt(8)
	s_waitcnt lgkmcnt(0)
	s_barrier
	s_setprio 1
	s_waitcnt lgkmcnt(0)
	v_mfma_f32_16x16x32_bf16 v[0:3], v[24:27], v[202:205], v[0:3]
	v_mfma_f32_16x16x32_bf16 v[4:7], v[112:115], v[202:205], v[4:7]
	v_mfma_f32_16x16x32_bf16 v[146:149], v[24:27], v[178:181], v[146:149]
	v_mfma_f32_16x16x32_bf16 v[150:153], v[112:115], v[178:181], v[150:153]
	v_mfma_f32_16x16x32_bf16 v[154:157], v[24:27], v[186:189], v[154:157]
	v_mfma_f32_16x16x32_bf16 v[158:161], v[112:115], v[186:189], v[158:161]
	v_mfma_f32_16x16x32_bf16 v[162:165], v[24:27], v[194:197], v[162:165]
	v_mfma_f32_16x16x32_bf16 v[166:169], v[112:115], v[194:197], v[166:169]
	v_mfma_f32_16x16x32_bf16 v[0:3], v[28:31], v[206:209], v[0:3]
	v_mfma_f32_16x16x32_bf16 v[4:7], v[116:119], v[206:209], v[4:7]
	v_mfma_f32_16x16x32_bf16 v[146:149], v[28:31], v[182:185], v[146:149]
	v_mfma_f32_16x16x32_bf16 v[150:153], v[116:119], v[182:185], v[150:153]
	v_mfma_f32_16x16x32_bf16 v[154:157], v[28:31], v[190:193], v[154:157]
	v_mfma_f32_16x16x32_bf16 v[158:161], v[116:119], v[190:193], v[158:161]
	v_mfma_f32_16x16x32_bf16 v[162:165], v[28:31], v[198:201], v[162:165]
	v_mfma_f32_16x16x32_bf16 v[166:169], v[116:119], v[198:201], v[166:169]
	v_mfma_f32_16x16x32_bf16 v[8:11], v[120:123], v[178:181], v[8:11]
	v_mfma_f32_16x16x32_bf16 v[12:15], v[170:173], v[178:181], v[12:15]
	v_mfma_f32_16x16x32_bf16 v[24:27], v[120:123], v[186:189], v[60:63]
	v_mfma_f32_16x16x32_bf16 v[28:31], v[170:173], v[186:189], v[100:103]
	v_mfma_f32_16x16x32_bf16 v[60:63], v[120:123], v[194:197], v[104:107]
	v_mfma_f32_16x16x32_bf16 v[100:103], v[170:173], v[194:197], v[108:111]
	v_mfma_f32_16x16x32_bf16 v[16:19], v[120:123], v[202:205], v[16:19]
	v_mfma_f32_16x16x32_bf16 v[20:23], v[170:173], v[202:205], v[20:23]
	v_mfma_f32_16x16x32_bf16 v[8:11], v[124:127], v[182:185], v[8:11]
	v_mfma_f32_16x16x32_bf16 v[12:15], v[174:177], v[182:185], v[12:15]
	v_mfma_f32_16x16x32_bf16 v[24:27], v[124:127], v[190:193], v[24:27]
	v_mfma_f32_16x16x32_bf16 v[28:31], v[174:177], v[190:193], v[28:31]
	v_mfma_f32_16x16x32_bf16 v[60:63], v[124:127], v[198:201], v[60:63]
	v_mfma_f32_16x16x32_bf16 v[100:103], v[174:177], v[198:201], v[100:103]
	v_mfma_f32_16x16x32_bf16 v[16:19], v[124:127], v[206:209], v[16:19]
	v_mfma_f32_16x16x32_bf16 v[20:23], v[174:177], v[206:209], v[20:23]
	s_setprio 0
	s_barrier
	ds_read_b128 v[104:107], v143
	ds_read_b128 v[108:111], v143 offset:1024
	ds_read_b128 v[112:115], v143 offset:2048
	ds_read_b128 v[116:119], v143 offset:3072
	ds_read_b128 v[120:123], v144
	ds_read_b128 v[124:127], v144 offset:1024
	ds_read_b128 v[170:173], v144 offset:2048
	ds_read_b128 v[174:177], v144 offset:3072
	s_add_u32 s46, s46, 0x10180
	s_addc_u32 s47, s47, 0
	s_mov_b32 m0, s67
	v_lshl_add_u64 v[138:139], s[46:47], 0, v[128:129]
	ds_read_b128 v[178:181], v145
	ds_read_b128 v[182:185], v145 offset:1024
	ds_read_b128 v[186:189], v145 offset:2048
	ds_read_b128 v[190:193], v145 offset:3072
	ds_read_b128 v[194:197], v145 offset:4096
	ds_read_b128 v[198:201], v145 offset:5120
	ds_read_b128 v[202:205], v145 offset:6144
	ds_read_b128 v[206:209], v145 offset:7168
	global_load_lds_dwordx4 v[138:139], off
	v_lshl_add_u64 v[138:139], s[46:47], 0, v[132:133]
	s_mov_b32 m0, s68
	s_nop 0
	global_load_lds_dwordx4 v[138:139], off
	s_waitcnt vmcnt(8)
	s_waitcnt lgkmcnt(0)
	s_barrier
	s_setprio 1
	s_waitcnt lgkmcnt(0)
	v_mfma_f32_16x16x32_bf16 v[88:91], v[104:107], v[202:205], v[88:91]
	v_mfma_f32_16x16x32_bf16 v[64:67], v[104:107], v[178:181], v[64:67]
	v_mfma_f32_16x16x32_bf16 v[68:71], v[112:115], v[178:181], v[68:71]
	v_mfma_f32_16x16x32_bf16 v[72:75], v[104:107], v[186:189], v[72:75]
	v_mfma_f32_16x16x32_bf16 v[76:79], v[112:115], v[186:189], v[76:79]
	v_mfma_f32_16x16x32_bf16 v[80:83], v[104:107], v[194:197], v[80:83]
	v_mfma_f32_16x16x32_bf16 v[84:87], v[112:115], v[194:197], v[84:87]
	v_mfma_f32_16x16x32_bf16 v[210:213], v[108:111], v[206:209], v[88:91]
	v_mfma_f32_16x16x32_bf16 v[88:91], v[112:115], v[202:205], v[92:95]
	v_mfma_f32_16x16x32_bf16 v[64:67], v[108:111], v[182:185], v[64:67]
	v_mfma_f32_16x16x32_bf16 v[68:71], v[116:119], v[182:185], v[68:71]
	v_mfma_f32_16x16x32_bf16 v[72:75], v[108:111], v[190:193], v[72:75]
	v_mfma_f32_16x16x32_bf16 v[76:79], v[116:119], v[190:193], v[76:79]
	v_mfma_f32_16x16x32_bf16 v[80:83], v[108:111], v[198:201], v[80:83]
	v_mfma_f32_16x16x32_bf16 v[84:87], v[116:119], v[198:201], v[84:87]
	v_mfma_f32_16x16x32_bf16 v[92:95], v[116:119], v[206:209], v[88:91]
	v_mfma_f32_16x16x32_bf16 v[48:51], v[170:173], v[194:197], v[48:51]
	v_mfma_f32_16x16x32_bf16 v[88:91], v[120:123], v[178:181], v[96:99]
	v_mfma_f32_16x16x32_bf16 v[32:35], v[170:173], v[178:181], v[32:35]
	v_mfma_f32_16x16x32_bf16 v[36:39], v[120:123], v[186:189], v[36:39]
	v_mfma_f32_16x16x32_bf16 v[40:43], v[170:173], v[186:189], v[40:43]
	v_mfma_f32_16x16x32_bf16 v[44:47], v[120:123], v[194:197], v[44:47]
	v_mfma_f32_16x16x32_bf16 v[178:181], v[174:177], v[198:201], v[48:51]
	v_mfma_f32_16x16x32_bf16 v[48:51], v[120:123], v[202:205], v[52:55]
	v_mfma_f32_16x16x32_bf16 v[32:35], v[174:177], v[182:185], v[32:35]
	v_mfma_f32_16x16x32_bf16 v[36:39], v[124:127], v[190:193], v[36:39]
	v_mfma_f32_16x16x32_bf16 v[40:43], v[174:177], v[190:193], v[40:43]
	v_mfma_f32_16x16x32_bf16 v[44:47], v[124:127], v[198:201], v[44:47]
	v_mfma_f32_16x16x32_bf16 v[52:55], v[124:127], v[206:209], v[48:51]
	v_mfma_f32_16x16x32_bf16 v[48:51], v[170:173], v[202:205], v[56:59]
	v_mfma_f32_16x16x32_bf16 v[214:217], v[124:127], v[182:185], v[88:91]
	v_mfma_f32_16x16x32_bf16 v[182:185], v[174:177], v[206:209], v[48:51]
	s_setprio 0
	s_barrier
	s_mov_b32 m0, s69
	v_lshl_add_u64 v[138:139], s[50:51], 0, v[130:131]
	s_add_u32 s46, s50, 0x10000
	s_nop 0
	ds_read_b128 v[48:51], v145 offset:16384
	ds_read_b128 v[56:59], v145 offset:17408
	ds_read_b128 v[88:91], v145 offset:18432
	ds_read_b128 v[96:99], v145 offset:19456
	ds_read_b128 v[186:189], v145 offset:20480
	ds_read_b128 v[190:193], v145 offset:21504
	ds_read_b128 v[194:197], v145 offset:22528
	ds_read_b128 v[198:201], v145 offset:23552
	global_load_lds_dwordx4 v[138:139], off
	v_lshl_add_u64 v[250:251], s[50:51], 0, v[134:135]
	s_mov_b32 m0, s70
	s_addc_u32 s47, s51, 0
	global_load_lds_dwordx4 v[250:251], off
	v_lshl_add_u64 v[202:203], s[46:47], 0, v[130:131]
	s_mov_b32 m0, s31
	v_lshl_add_u64 v[252:253], s[52:53], 0, v[128:129]
	global_load_lds_dwordx4 v[202:203], off
	v_lshl_add_u64 v[202:203], s[46:47], 0, v[134:135]
	s_mov_b32 m0, s37
	v_lshl_add_u64 v[254:255], s[52:53], 0, v[132:133]
	global_load_lds_dwordx4 v[202:203], off
	s_mov_b32 m0, s35
	s_nop 0
	global_load_lds_dwordx4 v[252:253], off
	s_mov_b32 m0, s60
	s_nop 0
	global_load_lds_dwordx4 v[254:255], off
	s_waitcnt vmcnt(8)
	s_waitcnt lgkmcnt(0)
	s_barrier
	s_setprio 1
	s_waitcnt lgkmcnt(0)
	v_mfma_f32_16x16x32_bf16 v[0:3], v[104:107], v[194:197], v[0:3]
	v_mfma_f32_16x16x32_bf16 v[4:7], v[112:115], v[194:197], v[4:7]
	v_mfma_f32_16x16x32_bf16 v[146:149], v[104:107], v[48:51], v[146:149]
	v_mfma_f32_16x16x32_bf16 v[150:153], v[112:115], v[48:51], v[150:153]
	v_mfma_f32_16x16x32_bf16 v[154:157], v[104:107], v[88:91], v[154:157]
	v_mfma_f32_16x16x32_bf16 v[158:161], v[112:115], v[88:91], v[158:161]
	v_mfma_f32_16x16x32_bf16 v[162:165], v[104:107], v[186:189], v[162:165]
	v_mfma_f32_16x16x32_bf16 v[166:169], v[112:115], v[186:189], v[166:169]
	v_mfma_f32_16x16x32_bf16 v[0:3], v[108:111], v[198:201], v[0:3]
	v_mfma_f32_16x16x32_bf16 v[4:7], v[116:119], v[198:201], v[4:7]
	v_mfma_f32_16x16x32_bf16 v[146:149], v[108:111], v[56:59], v[146:149]
	v_mfma_f32_16x16x32_bf16 v[150:153], v[116:119], v[56:59], v[150:153]
	v_mfma_f32_16x16x32_bf16 v[154:157], v[108:111], v[96:99], v[154:157]
	v_mfma_f32_16x16x32_bf16 v[158:161], v[116:119], v[96:99], v[158:161]
	v_mfma_f32_16x16x32_bf16 v[162:165], v[108:111], v[190:193], v[162:165]
	v_mfma_f32_16x16x32_bf16 v[166:169], v[116:119], v[190:193], v[166:169]
	v_mfma_f32_16x16x32_bf16 v[8:11], v[120:123], v[48:51], v[8:11]
	v_mfma_f32_16x16x32_bf16 v[202:205], v[124:127], v[56:59], v[8:11]
	v_mfma_f32_16x16x32_bf16 v[8:11], v[170:173], v[48:51], v[12:15]
	v_mfma_f32_16x16x32_bf16 v[12:15], v[174:177], v[56:59], v[8:11]
	v_mfma_f32_16x16x32_bf16 v[8:11], v[120:123], v[88:91], v[24:27]
	v_mfma_f32_16x16x32_bf16 v[206:209], v[124:127], v[96:99], v[8:11]
	v_mfma_f32_16x16x32_bf16 v[8:11], v[170:173], v[88:91], v[28:31]
	v_mfma_f32_16x16x32_bf16 v[28:31], v[174:177], v[96:99], v[8:11]
	v_mfma_f32_16x16x32_bf16 v[8:11], v[120:123], v[186:189], v[60:63]
	v_mfma_f32_16x16x32_bf16 v[218:221], v[124:127], v[190:193], v[8:11]
	v_mfma_f32_16x16x32_bf16 v[8:11], v[170:173], v[186:189], v[100:103]
	v_mfma_f32_16x16x32_bf16 v[186:189], v[174:177], v[190:193], v[8:11]
	v_mfma_f32_16x16x32_bf16 v[8:11], v[120:123], v[194:197], v[16:19]
	v_mfma_f32_16x16x32_bf16 v[190:193], v[124:127], v[198:201], v[8:11]
	v_mfma_f32_16x16x32_bf16 v[8:11], v[170:173], v[194:197], v[20:23]
	v_mfma_f32_16x16x32_bf16 v[170:173], v[174:177], v[198:201], v[8:11]
	s_setprio 0
	s_barrier
	s_nop 4
	ds_read_b128 v[8:11], v222
	ds_read_b128 v[20:23], v222 offset:1024
	ds_read_b128 v[174:177], v222 offset:2048
	ds_read_b128 v[194:197], v222 offset:3072
	ds_read_b128 v[198:201], v230
	ds_read_b128 v[222:225], v230 offset:1024
	ds_read_b128 v[226:229], v230 offset:2048
	ds_read_b128 v[230:233], v230 offset:3072
	s_add_u32 s46, s52, 0x10000
	s_addc_u32 s47, s53, 0
	s_mov_b32 m0, s61
	v_lshl_add_u64 v[48:49], s[46:47], 0, v[128:129]
	ds_read_b128 v[16:19], v145 offset:32768
	ds_read_b128 v[24:27], v145 offset:33792
	ds_read_b128 v[60:63], v145 offset:34816
	ds_read_b128 v[100:103], v145 offset:35840
	ds_read_b128 v[234:237], v145 offset:36864
	ds_read_b128 v[238:241], v145 offset:37888
	ds_read_b128 v[242:245], v145 offset:38912
	ds_read_b128 v[246:249], v145 offset:39936
	global_load_lds_dwordx4 v[48:49], off
	v_lshl_add_u64 v[48:49], s[46:47], 0, v[132:133]
	s_mov_b32 m0, s62
	s_nop 0
	global_load_lds_dwordx4 v[48:49], off
	s_waitcnt vmcnt(8)
	s_waitcnt lgkmcnt(0)
	s_barrier
	s_setprio 1
	s_waitcnt lgkmcnt(0)
	v_mfma_f32_16x16x32_bf16 v[48:51], v[8:11], v[16:19], v[64:67]
	v_mfma_f32_16x16x32_bf16 v[120:123], v[20:23], v[24:27], v[48:51]
	v_mfma_f32_16x16x32_bf16 v[48:51], v[174:177], v[16:19], v[68:71]
	v_mfma_f32_16x16x32_bf16 v[112:115], v[194:197], v[24:27], v[48:51]
	v_mfma_f32_16x16x32_bf16 v[48:51], v[8:11], v[60:63], v[72:75]
	v_mfma_f32_16x16x32_bf16 v[104:107], v[20:23], v[100:103], v[48:51]
	v_mfma_f32_16x16x32_bf16 v[48:51], v[174:177], v[60:63], v[76:79]
	v_mfma_f32_16x16x32_bf16 v[96:99], v[194:197], v[100:103], v[48:51]
	v_mfma_f32_16x16x32_bf16 v[48:51], v[8:11], v[234:237], v[80:83]
	v_mfma_f32_16x16x32_bf16 v[88:91], v[20:23], v[238:241], v[48:51]
	v_mfma_f32_16x16x32_bf16 v[48:51], v[174:177], v[234:237], v[84:87]
	v_mfma_f32_16x16x32_bf16 v[80:83], v[194:197], v[238:241], v[48:51]
	v_mfma_f32_16x16x32_bf16 v[48:51], v[8:11], v[242:245], v[210:213]
	v_mfma_f32_16x16x32_bf16 v[56:59], v[20:23], v[246:249], v[48:51]
	v_mfma_f32_16x16x32_bf16 v[48:51], v[174:177], v[242:245], v[92:95]
	v_mfma_f32_16x16x32_bf16 v[48:51], v[194:197], v[246:249], v[48:51]
	v_mfma_f32_16x16x32_bf16 v[64:67], v[198:201], v[16:19], v[214:217]
	v_mfma_f32_16x16x32_bf16 v[16:19], v[226:229], v[16:19], v[32:35]
	v_mfma_f32_16x16x32_bf16 v[116:119], v[230:233], v[24:27], v[16:19]
	v_mfma_f32_16x16x32_bf16 v[16:19], v[198:201], v[60:63], v[36:39]
	v_mfma_f32_16x16x32_bf16 v[108:111], v[222:225], v[100:103], v[16:19]
	v_mfma_f32_16x16x32_bf16 v[16:19], v[226:229], v[60:63], v[40:43]
	v_mfma_f32_16x16x32_bf16 v[100:103], v[230:233], v[100:103], v[16:19]
	v_mfma_f32_16x16x32_bf16 v[16:19], v[198:201], v[234:237], v[44:47]
	v_mfma_f32_16x16x32_bf16 v[92:95], v[222:225], v[238:241], v[16:19]
	v_mfma_f32_16x16x32_bf16 v[16:19], v[226:229], v[234:237], v[178:181]
	v_mfma_f32_16x16x32_bf16 v[84:87], v[230:233], v[238:241], v[16:19]
	v_mfma_f32_16x16x32_bf16 v[16:19], v[198:201], v[242:245], v[52:55]
	v_mfma_f32_16x16x32_bf16 v[60:63], v[222:225], v[246:249], v[16:19]
	v_mfma_f32_16x16x32_bf16 v[16:19], v[226:229], v[242:245], v[182:185]
	v_mfma_f32_16x16x32_bf16 v[124:127], v[222:225], v[24:27], v[64:67]
	v_mfma_f32_16x16x32_bf16 v[52:55], v[230:233], v[246:249], v[16:19]
	s_setprio 0
	s_barrier
	s_mov_b32 m0, s71
	s_nop 2
	v_lshl_add_u64 v[16:17], v[138:139], 0, s[20:21]
	s_add_u32 s46, s50, 0x10080
	ds_read_b128 v[36:39], v145 offset:49152
	ds_read_b128 v[44:47], v145 offset:50176
	ds_read_b128 v[178:181], v145 offset:51200
	ds_read_b128 v[182:185], v145 offset:52224
	ds_read_b128 v[210:213], v145 offset:53248
	ds_read_b128 v[214:217], v145 offset:54272
	ds_read_b128 v[234:237], v145 offset:55296
	ds_read_b128 v[238:241], v145 offset:56320
	global_load_lds_dwordx4 v[16:17], off
	v_lshl_add_u64 v[16:17], v[250:251], 0, s[20:21]
	s_mov_b32 m0, s39
	s_addc_u32 s47, s51, 0
	global_load_lds_dwordx4 v[16:17], off
	v_lshl_add_u64 v[16:17], s[46:47], 0, v[130:131]
	s_mov_b32 m0, s48
	s_nop 0
	global_load_lds_dwordx4 v[16:17], off
	v_lshl_add_u64 v[16:17], s[46:47], 0, v[134:135]
	s_mov_b32 m0, s49
	s_nop 0
	global_load_lds_dwordx4 v[16:17], off
	v_lshl_add_u64 v[16:17], v[252:253], 0, s[20:21]
	s_mov_b32 m0, s63
	s_nop 0
	global_load_lds_dwordx4 v[16:17], off
	v_lshl_add_u64 v[16:17], v[254:255], 0, s[20:21]
	s_mov_b32 m0, s64
	s_nop 0
	global_load_lds_dwordx4 v[16:17], off
	s_waitcnt vmcnt(8)
	s_waitcnt lgkmcnt(0)
	s_barrier
	s_setprio 1
	s_waitcnt lgkmcnt(0)
	v_mfma_f32_16x16x32_bf16 v[16:19], v[8:11], v[36:39], v[146:149]
	v_mfma_f32_16x16x32_bf16 v[72:75], v[20:23], v[44:47], v[16:19]
	v_mfma_f32_16x16x32_bf16 v[16:19], v[174:177], v[36:39], v[150:153]
	v_mfma_f32_16x16x32_bf16 v[64:67], v[194:197], v[44:47], v[16:19]
	v_mfma_f32_16x16x32_bf16 v[16:19], v[8:11], v[178:181], v[154:157]
	v_mfma_f32_16x16x32_bf16 v[40:43], v[20:23], v[182:185], v[16:19]
	v_mfma_f32_16x16x32_bf16 v[16:19], v[174:177], v[178:181], v[158:161]
	v_mfma_f32_16x16x32_bf16 v[32:35], v[194:197], v[182:185], v[16:19]
	v_mfma_f32_16x16x32_bf16 v[16:19], v[8:11], v[210:213], v[162:165]
	v_mfma_f32_16x16x32_bf16 v[0:3], v[8:11], v[234:237], v[0:3]
	v_mfma_f32_16x16x32_bf16 v[24:27], v[20:23], v[214:217], v[16:19]
	v_mfma_f32_16x16x32_bf16 v[16:19], v[174:177], v[210:213], v[166:169]
	v_mfma_f32_16x16x32_bf16 v[8:11], v[20:23], v[238:241], v[0:3]
	v_mfma_f32_16x16x32_bf16 v[0:3], v[174:177], v[234:237], v[4:7]
	v_mfma_f32_16x16x32_bf16 v[16:19], v[194:197], v[214:217], v[16:19]
	v_mfma_f32_16x16x32_bf16 v[0:3], v[194:197], v[238:241], v[0:3]
	v_mfma_f32_16x16x32_bf16 v[4:7], v[198:201], v[36:39], v[202:205]
	v_mfma_f32_16x16x32_bf16 v[76:79], v[222:225], v[44:47], v[4:7]
	v_mfma_f32_16x16x32_bf16 v[4:7], v[226:229], v[36:39], v[12:15]
	v_mfma_f32_16x16x32_bf16 v[68:71], v[230:233], v[44:47], v[4:7]
	v_mfma_f32_16x16x32_bf16 v[4:7], v[198:201], v[178:181], v[206:209]
	v_mfma_f32_16x16x32_bf16 v[44:47], v[222:225], v[182:185], v[4:7]
	v_mfma_f32_16x16x32_bf16 v[4:7], v[226:229], v[178:181], v[28:31]
	v_mfma_f32_16x16x32_bf16 v[36:39], v[230:233], v[182:185], v[4:7]
	v_mfma_f32_16x16x32_bf16 v[4:7], v[198:201], v[210:213], v[218:221]
	v_mfma_f32_16x16x32_bf16 v[28:31], v[222:225], v[214:217], v[4:7]
	v_mfma_f32_16x16x32_bf16 v[4:7], v[226:229], v[210:213], v[186:189]
	v_mfma_f32_16x16x32_bf16 v[20:23], v[230:233], v[214:217], v[4:7]
	v_mfma_f32_16x16x32_bf16 v[4:7], v[198:201], v[234:237], v[190:193]
	v_mfma_f32_16x16x32_bf16 v[12:15], v[222:225], v[238:241], v[4:7]
	v_mfma_f32_16x16x32_bf16 v[4:7], v[226:229], v[234:237], v[170:173]
	v_mfma_f32_16x16x32_bf16 v[4:7], v[230:233], v[238:241], v[4:7]
	s_setprio 0
	s_barrier
	s_andn2_b64 vcc, exec, s[22:23]
	s_cbranch_vccnz .LBB0_726
	s_barrier

.LBB0_750:
	v_add_u32_e32 v1, s75, v163
	ds_read_b128 v[146:149], v1
	ds_read_b128 v[150:153], v1 offset:1024
	ds_read_b128 v[154:157], v1 offset:2048
	ds_read_b128 v[158:161], v1 offset:3072
	v_add_u32_e32 v1, s76, v163
	ds_read_b128 v[166:169], v1
	ds_read_b128 v[170:173], v1 offset:1024
	ds_read_b128 v[174:177], v1 offset:2048
	ds_read_b128 v[178:181], v1 offset:3072
	s_add_u32 s52, s50, 0xfffe0080
	s_addc_u32 s53, s51, -1
	s_cmp_eq_u32 s82, 4
	s_cselect_b32 s55, s41, s53
	s_cselect_b32 s54, s49, s52
	s_cselect_b32 s53, s39, s81
	s_cselect_b32 s52, s79, s80
	v_lshl_add_u64 v[2:3], s[50:51], 0, v[142:143]
	s_add_i32 m0, s64, 0xc000
	ds_read_b128 v[182:185], v165
	ds_read_b128 v[186:189], v165 offset:1024
	ds_read_b128 v[190:193], v165 offset:2048
	ds_read_b128 v[194:197], v165 offset:3072
	ds_read_b128 v[198:201], v165 offset:4096
	ds_read_b128 v[202:205], v165 offset:5120
	ds_read_b128 v[206:209], v165 offset:6144
	ds_read_b128 v[210:213], v165 offset:7168
	global_load_lds_dwordx4 v[2:3], off
	v_lshl_add_u64 v[2:3], s[50:51], 0, v[140:141]
	s_add_i32 m0, s64, 0xe000
	s_nop 0
	global_load_lds_dwordx4 v[2:3], off
	s_waitcnt vmcnt(8)
	s_waitcnt lgkmcnt(0)
	s_barrier
	s_setprio 1
	s_waitcnt lgkmcnt(0)
	v_mfma_f32_16x16x32_bf16 v[128:131], v[146:149], v[182:185], v[128:131]
	v_mfma_f32_16x16x32_bf16 v[124:127], v[154:157], v[182:185], v[124:127]
	v_mfma_f32_16x16x32_bf16 v[120:123], v[146:149], v[190:193], v[120:123]
	v_mfma_f32_16x16x32_bf16 v[116:119], v[154:157], v[190:193], v[116:119]
	v_mfma_f32_16x16x32_bf16 v[112:115], v[146:149], v[198:201], v[112:115]
	v_mfma_f32_16x16x32_bf16 v[108:111], v[154:157], v[198:201], v[108:111]
	v_mfma_f32_16x16x32_bf16 v[104:107], v[146:149], v[206:209], v[104:107]
	v_mfma_f32_16x16x32_bf16 v[100:103], v[154:157], v[206:209], v[100:103]
	v_mfma_f32_16x16x32_bf16 v[128:131], v[150:153], v[186:189], v[128:131]
	v_mfma_f32_16x16x32_bf16 v[124:127], v[158:161], v[186:189], v[124:127]
	v_mfma_f32_16x16x32_bf16 v[120:123], v[150:153], v[194:197], v[120:123]
	v_mfma_f32_16x16x32_bf16 v[116:119], v[158:161], v[194:197], v[116:119]
	v_mfma_f32_16x16x32_bf16 v[112:115], v[150:153], v[202:205], v[112:115]
	v_mfma_f32_16x16x32_bf16 v[108:111], v[158:161], v[202:205], v[108:111]
	v_mfma_f32_16x16x32_bf16 v[104:107], v[150:153], v[210:213], v[104:107]
	v_mfma_f32_16x16x32_bf16 v[100:103], v[158:161], v[210:213], v[100:103]
	v_mfma_f32_16x16x32_bf16 v[96:99], v[166:169], v[182:185], v[96:99]
	v_mfma_f32_16x16x32_bf16 v[92:95], v[174:177], v[182:185], v[92:95]
	v_mfma_f32_16x16x32_bf16 v[88:91], v[166:169], v[190:193], v[88:91]
	v_mfma_f32_16x16x32_bf16 v[84:87], v[174:177], v[190:193], v[84:87]
	v_mfma_f32_16x16x32_bf16 v[80:83], v[166:169], v[198:201], v[80:83]
	v_mfma_f32_16x16x32_bf16 v[76:79], v[174:177], v[198:201], v[76:79]
	v_mfma_f32_16x16x32_bf16 v[72:75], v[166:169], v[206:209], v[72:75]
	v_mfma_f32_16x16x32_bf16 v[68:71], v[174:177], v[206:209], v[68:71]
	v_mfma_f32_16x16x32_bf16 v[96:99], v[170:173], v[186:189], v[96:99]
	v_mfma_f32_16x16x32_bf16 v[92:95], v[178:181], v[186:189], v[92:95]
	v_mfma_f32_16x16x32_bf16 v[88:91], v[170:173], v[194:197], v[88:91]
	v_mfma_f32_16x16x32_bf16 v[84:87], v[178:181], v[194:197], v[84:87]
	v_mfma_f32_16x16x32_bf16 v[80:83], v[170:173], v[202:205], v[80:83]
	v_mfma_f32_16x16x32_bf16 v[76:79], v[178:181], v[202:205], v[76:79]
	v_mfma_f32_16x16x32_bf16 v[72:75], v[170:173], v[210:213], v[72:75]
	v_mfma_f32_16x16x32_bf16 v[68:71], v[178:181], v[210:213], v[68:71]
	s_setprio 0
	s_barrier
	s_add_i32 s83, s75, s63
	v_lshl_add_u64 v[214:215], s[52:53], 0, v[134:135]
	s_mov_b32 m0, s83
	ds_read_b128 v[182:185], v165 offset:16384
	ds_read_b128 v[186:189], v165 offset:17408
	ds_read_b128 v[190:193], v165 offset:18432
	ds_read_b128 v[194:197], v165 offset:19456
	ds_read_b128 v[198:201], v165 offset:20480
	ds_read_b128 v[202:205], v165 offset:21504
	ds_read_b128 v[206:209], v165 offset:22528
	ds_read_b128 v[210:213], v165 offset:23552
	global_load_lds_dwordx4 v[214:215], off
	s_add_i32 m0, s83, 0x2000
	s_add_u32 s84, s52, 0x20000
	v_lshl_add_u64 v[216:217], s[52:53], 0, v[138:139]
	s_addc_u32 s85, s53, 0
	s_add_i32 s83, s76, s63
	global_load_lds_dwordx4 v[216:217], off
	v_lshl_add_u64 v[2:3], s[84:85], 0, v[134:135]
	s_mov_b32 m0, s83
	v_lshl_add_u64 v[218:219], s[54:55], 0, v[132:133]
	global_load_lds_dwordx4 v[2:3], off
	v_lshl_add_u64 v[2:3], s[84:85], 0, v[138:139]
	s_add_i32 m0, s83, 0x2000
	v_lshl_add_u64 v[220:221], s[54:55], 0, v[136:137]
	global_load_lds_dwordx4 v[2:3], off
	s_mov_b32 m0, s64
	s_nop 0
	global_load_lds_dwordx4 v[218:219], off
	s_mov_b32 m0, s65
	s_nop 0
	global_load_lds_dwordx4 v[220:221], off
	s_waitcnt vmcnt(8)
	s_waitcnt lgkmcnt(0)
	s_barrier
	s_setprio 1
	s_waitcnt lgkmcnt(0)
	v_mfma_f32_16x16x32_bf16 v[64:67], v[146:149], v[182:185], v[64:67]
	v_mfma_f32_16x16x32_bf16 v[60:63], v[154:157], v[182:185], v[60:63]
	v_mfma_f32_16x16x32_bf16 v[56:59], v[146:149], v[190:193], v[56:59]
	v_mfma_f32_16x16x32_bf16 v[52:55], v[154:157], v[190:193], v[52:55]
	v_mfma_f32_16x16x32_bf16 v[48:51], v[146:149], v[198:201], v[48:51]
	v_mfma_f32_16x16x32_bf16 v[44:47], v[154:157], v[198:201], v[44:47]
	v_mfma_f32_16x16x32_bf16 v[40:43], v[146:149], v[206:209], v[40:43]
	v_mfma_f32_16x16x32_bf16 v[36:39], v[154:157], v[206:209], v[36:39]
	v_mfma_f32_16x16x32_bf16 v[64:67], v[150:153], v[186:189], v[64:67]
	v_mfma_f32_16x16x32_bf16 v[60:63], v[158:161], v[186:189], v[60:63]
	v_mfma_f32_16x16x32_bf16 v[56:59], v[150:153], v[194:197], v[56:59]
	v_mfma_f32_16x16x32_bf16 v[52:55], v[158:161], v[194:197], v[52:55]
	v_mfma_f32_16x16x32_bf16 v[48:51], v[150:153], v[202:205], v[48:51]
	v_mfma_f32_16x16x32_bf16 v[44:47], v[158:161], v[202:205], v[44:47]
	v_mfma_f32_16x16x32_bf16 v[40:43], v[150:153], v[210:213], v[40:43]
	v_mfma_f32_16x16x32_bf16 v[36:39], v[158:161], v[210:213], v[36:39]
	v_mfma_f32_16x16x32_bf16 v[32:35], v[166:169], v[182:185], v[32:35]
	v_mfma_f32_16x16x32_bf16 v[28:31], v[174:177], v[182:185], v[28:31]
	v_mfma_f32_16x16x32_bf16 v[24:27], v[166:169], v[190:193], v[24:27]
	v_mfma_f32_16x16x32_bf16 v[20:23], v[174:177], v[190:193], v[20:23]
	v_mfma_f32_16x16x32_bf16 v[16:19], v[166:169], v[198:201], v[16:19]
	v_mfma_f32_16x16x32_bf16 v[12:15], v[174:177], v[198:201], v[12:15]
	v_mfma_f32_16x16x32_bf16 v[8:11], v[166:169], v[206:209], v[8:11]
	v_mfma_f32_16x16x32_bf16 v[2:5], v[174:177], v[206:209], v[4:7]
	v_mfma_f32_16x16x32_bf16 v[32:35], v[170:173], v[186:189], v[32:35]
	v_mfma_f32_16x16x32_bf16 v[28:31], v[178:181], v[186:189], v[28:31]
	v_mfma_f32_16x16x32_bf16 v[24:27], v[170:173], v[194:197], v[24:27]
	v_mfma_f32_16x16x32_bf16 v[20:23], v[178:181], v[194:197], v[20:23]
	v_mfma_f32_16x16x32_bf16 v[16:19], v[170:173], v[202:205], v[16:19]
	v_mfma_f32_16x16x32_bf16 v[12:15], v[178:181], v[202:205], v[12:15]
	v_mfma_f32_16x16x32_bf16 v[8:11], v[170:173], v[210:213], v[8:11]
	v_mfma_f32_16x16x32_bf16 v[2:5], v[178:181], v[210:213], v[2:5]
	s_setprio 0
	s_barrier
	s_add_i32 s83, 0, 0x18000
	v_add_u32_e32 v1, s83, v163
	s_add_i32 s84, 0, 0x1c000
	ds_read_b128 v[146:149], v1
	ds_read_b128 v[150:153], v1 offset:1024
	ds_read_b128 v[154:157], v1 offset:2048
	ds_read_b128 v[158:161], v1 offset:3072
	v_add_u32_e32 v1, s84, v163
	ds_read_b128 v[166:169], v1
	ds_read_b128 v[170:173], v1 offset:1024
	ds_read_b128 v[174:177], v1 offset:2048
	ds_read_b128 v[178:181], v1 offset:3072
	s_add_u32 s54, s54, 0x20000
	s_addc_u32 s55, s55, 0
	s_mov_b32 m0, s66
	v_lshl_add_u64 v[6:7], s[54:55], 0, v[132:133]
	ds_read_b128 v[182:185], v165 offset:32768
	ds_read_b128 v[186:189], v165 offset:33792
	ds_read_b128 v[190:193], v165 offset:34816
	ds_read_b128 v[194:197], v165 offset:35840
	ds_read_b128 v[198:201], v165 offset:36864
	ds_read_b128 v[202:205], v165 offset:37888
	ds_read_b128 v[206:209], v165 offset:38912
	ds_read_b128 v[210:213], v165 offset:39936
	global_load_lds_dwordx4 v[6:7], off
	v_lshl_add_u64 v[6:7], s[54:55], 0, v[136:137]
	s_mov_b32 m0, s67
	s_nop 0
	global_load_lds_dwordx4 v[6:7], off
	s_waitcnt vmcnt(8)
	s_waitcnt lgkmcnt(0)
	s_barrier
	s_setprio 1
	s_waitcnt lgkmcnt(0)
	v_mfma_f32_16x16x32_bf16 v[128:131], v[146:149], v[182:185], v[128:131]
	v_mfma_f32_16x16x32_bf16 v[124:127], v[154:157], v[182:185], v[124:127]
	v_mfma_f32_16x16x32_bf16 v[120:123], v[146:149], v[190:193], v[120:123]
	v_mfma_f32_16x16x32_bf16 v[116:119], v[154:157], v[190:193], v[116:119]
	v_mfma_f32_16x16x32_bf16 v[112:115], v[146:149], v[198:201], v[112:115]
	v_mfma_f32_16x16x32_bf16 v[108:111], v[154:157], v[198:201], v[108:111]
	v_mfma_f32_16x16x32_bf16 v[104:107], v[146:149], v[206:209], v[104:107]
	v_mfma_f32_16x16x32_bf16 v[100:103], v[154:157], v[206:209], v[100:103]
	v_mfma_f32_16x16x32_bf16 v[128:131], v[150:153], v[186:189], v[128:131]
	v_mfma_f32_16x16x32_bf16 v[124:127], v[158:161], v[186:189], v[124:127]
	v_mfma_f32_16x16x32_bf16 v[120:123], v[150:153], v[194:197], v[120:123]
	v_mfma_f32_16x16x32_bf16 v[116:119], v[158:161], v[194:197], v[116:119]
	v_mfma_f32_16x16x32_bf16 v[112:115], v[150:153], v[202:205], v[112:115]
	v_mfma_f32_16x16x32_bf16 v[108:111], v[158:161], v[202:205], v[108:111]
	v_mfma_f32_16x16x32_bf16 v[104:107], v[150:153], v[210:213], v[104:107]
	v_mfma_f32_16x16x32_bf16 v[100:103], v[158:161], v[210:213], v[100:103]
	v_mfma_f32_16x16x32_bf16 v[96:99], v[166:169], v[182:185], v[96:99]
	v_mfma_f32_16x16x32_bf16 v[92:95], v[174:177], v[182:185], v[92:95]
	v_mfma_f32_16x16x32_bf16 v[88:91], v[166:169], v[190:193], v[88:91]
	v_mfma_f32_16x16x32_bf16 v[84:87], v[174:177], v[190:193], v[84:87]
	v_mfma_f32_16x16x32_bf16 v[80:83], v[166:169], v[198:201], v[80:83]
	v_mfma_f32_16x16x32_bf16 v[76:79], v[174:177], v[198:201], v[76:79]
	v_mfma_f32_16x16x32_bf16 v[72:75], v[166:169], v[206:209], v[72:75]
	v_mfma_f32_16x16x32_bf16 v[68:71], v[174:177], v[206:209], v[68:71]
	v_mfma_f32_16x16x32_bf16 v[96:99], v[170:173], v[186:189], v[96:99]
	v_mfma_f32_16x16x32_bf16 v[92:95], v[178:181], v[186:189], v[92:95]
	v_mfma_f32_16x16x32_bf16 v[88:91], v[170:173], v[194:197], v[88:91]
	v_mfma_f32_16x16x32_bf16 v[84:87], v[178:181], v[194:197], v[84:87]
	v_mfma_f32_16x16x32_bf16 v[80:83], v[170:173], v[202:205], v[80:83]
	v_mfma_f32_16x16x32_bf16 v[76:79], v[178:181], v[202:205], v[76:79]
	v_mfma_f32_16x16x32_bf16 v[72:75], v[170:173], v[210:213], v[72:75]
	v_mfma_f32_16x16x32_bf16 v[68:71], v[178:181], v[210:213], v[68:71]
	s_setprio 0
	s_barrier
	s_add_i32 s54, s83, s63
	v_lshl_add_u64 v[6:7], v[214:215], 0, s[26:27]
	s_mov_b32 m0, s54
	ds_read_b128 v[182:185], v165 offset:49152
	ds_read_b128 v[186:189], v165 offset:50176
	ds_read_b128 v[190:193], v165 offset:51200
	ds_read_b128 v[194:197], v165 offset:52224
	ds_read_b128 v[198:201], v165 offset:53248
	ds_read_b128 v[202:205], v165 offset:54272
	ds_read_b128 v[206:209], v165 offset:55296
	ds_read_b128 v[210:213], v165 offset:56320
	global_load_lds_dwordx4 v[6:7], off
	s_add_i32 m0, s54, 0x2000
	s_add_u32 s52, s52, 0x20080
	v_lshl_add_u64 v[6:7], v[216:217], 0, s[26:27]
	s_addc_u32 s53, s53, 0
	s_add_i32 s54, s84, s63
	global_load_lds_dwordx4 v[6:7], off
	v_lshl_add_u64 v[6:7], s[52:53], 0, v[134:135]
	s_mov_b32 m0, s54
	s_nop 0
	global_load_lds_dwordx4 v[6:7], off
	v_lshl_add_u64 v[6:7], s[52:53], 0, v[138:139]
	s_add_i32 m0, s54, 0x2000
	s_nop 0
	global_load_lds_dwordx4 v[6:7], off
	v_lshl_add_u64 v[6:7], v[218:219], 0, s[26:27]
	s_mov_b32 m0, s72
	s_nop 0
	global_load_lds_dwordx4 v[6:7], off
	v_lshl_add_u64 v[6:7], v[220:221], 0, s[26:27]
	s_mov_b32 m0, s73
	s_nop 0
	global_load_lds_dwordx4 v[6:7], off
	s_waitcnt vmcnt(8)
	s_waitcnt lgkmcnt(0)
	s_barrier
	s_setprio 1
	s_waitcnt lgkmcnt(0)
	v_mfma_f32_16x16x32_bf16 v[64:67], v[146:149], v[182:185], v[64:67]
	v_mfma_f32_16x16x32_bf16 v[60:63], v[154:157], v[182:185], v[60:63]
	v_mfma_f32_16x16x32_bf16 v[56:59], v[146:149], v[190:193], v[56:59]
	v_mfma_f32_16x16x32_bf16 v[52:55], v[154:157], v[190:193], v[52:55]
	v_mfma_f32_16x16x32_bf16 v[48:51], v[146:149], v[198:201], v[48:51]
	v_mfma_f32_16x16x32_bf16 v[44:47], v[154:157], v[198:201], v[44:47]
	v_mfma_f32_16x16x32_bf16 v[40:43], v[146:149], v[206:209], v[40:43]
	v_mfma_f32_16x16x32_bf16 v[36:39], v[154:157], v[206:209], v[36:39]
	v_mfma_f32_16x16x32_bf16 v[64:67], v[150:153], v[186:189], v[64:67]
	v_mfma_f32_16x16x32_bf16 v[60:63], v[158:161], v[186:189], v[60:63]
	v_mfma_f32_16x16x32_bf16 v[56:59], v[150:153], v[194:197], v[56:59]
	v_mfma_f32_16x16x32_bf16 v[52:55], v[158:161], v[194:197], v[52:55]
	v_mfma_f32_16x16x32_bf16 v[48:51], v[150:153], v[202:205], v[48:51]
	v_mfma_f32_16x16x32_bf16 v[44:47], v[158:161], v[202:205], v[44:47]
	v_mfma_f32_16x16x32_bf16 v[40:43], v[150:153], v[210:213], v[40:43]
	v_mfma_f32_16x16x32_bf16 v[36:39], v[158:161], v[210:213], v[36:39]
	v_mfma_f32_16x16x32_bf16 v[32:35], v[166:169], v[182:185], v[32:35]
	v_mfma_f32_16x16x32_bf16 v[28:31], v[174:177], v[182:185], v[28:31]
	v_mfma_f32_16x16x32_bf16 v[24:27], v[166:169], v[190:193], v[24:27]
	v_mfma_f32_16x16x32_bf16 v[20:23], v[174:177], v[190:193], v[20:23]
	v_mfma_f32_16x16x32_bf16 v[16:19], v[166:169], v[198:201], v[16:19]
	v_mfma_f32_16x16x32_bf16 v[12:15], v[174:177], v[198:201], v[12:15]
	v_mfma_f32_16x16x32_bf16 v[6:9], v[166:169], v[206:209], v[8:11]
	v_mfma_f32_16x16x32_bf16 v[2:5], v[174:177], v[206:209], v[2:5]
	v_mfma_f32_16x16x32_bf16 v[32:35], v[170:173], v[186:189], v[32:35]
	v_mfma_f32_16x16x32_bf16 v[28:31], v[178:181], v[186:189], v[28:31]
	v_mfma_f32_16x16x32_bf16 v[24:27], v[170:173], v[194:197], v[24:27]
	v_mfma_f32_16x16x32_bf16 v[20:23], v[178:181], v[194:197], v[20:23]
	v_mfma_f32_16x16x32_bf16 v[16:19], v[170:173], v[202:205], v[16:19]
	v_mfma_f32_16x16x32_bf16 v[12:15], v[178:181], v[202:205], v[12:15]
	v_mfma_f32_16x16x32_bf16 v[8:11], v[170:173], v[210:213], v[6:9]
	v_mfma_f32_16x16x32_bf16 v[4:7], v[178:181], v[210:213], v[2:5]
	s_setprio 0
	s_barrier
	s_add_i32 s82, s82, 2
	s_add_u32 s80, s80, 0x100
	s_addc_u32 s81, s81, 0
	s_add_u32 s50, s50, 0x100
	s_addc_u32 s51, s51, 0
	s_cmp_gt_u32 s82, 5
	s_cbranch_scc0 .LBB0_750
	s_and_b64 vcc, exec, s[28:29]
	s_cbranch_vccz .LBB0_753
	s_barrier

.LBB0_934:
	ds_read_b128 v[138:141], v145
	ds_read_b128 v[148:151], v145 offset:1024
	ds_read_b128 v[152:155], v145 offset:2048
	ds_read_b128 v[156:159], v145 offset:3072
	ds_read_b128 v[160:163], v146
	ds_read_b128 v[164:167], v146 offset:1024
	ds_read_b128 v[168:171], v146 offset:2048
	ds_read_b128 v[172:175], v146 offset:3072
	s_add_u32 s50, s48, 0xfffc0080
	s_addc_u32 s51, s49, -1
	s_cmp_eq_u32 s72, 12
	s_cselect_b32 s53, s37, s51
	s_cselect_b32 s52, s68, s50
	s_cselect_b32 s51, s35, s71
	s_cselect_b32 s50, s69, s70
	v_lshl_add_u64 v[208:209], s[48:49], 0, v[134:135]
	s_add_i32 m0, s45, 0xc000
	ds_read_b128 v[176:179], v147
	ds_read_b128 v[180:183], v147 offset:1024
	ds_read_b128 v[184:187], v147 offset:2048
	ds_read_b128 v[188:191], v147 offset:3072
	ds_read_b128 v[192:195], v147 offset:4096
	ds_read_b128 v[196:199], v147 offset:5120
	ds_read_b128 v[200:203], v147 offset:6144
	ds_read_b128 v[204:207], v147 offset:7168
	global_load_lds_dwordx4 v[208:209], off
	v_lshl_add_u64 v[208:209], s[48:49], 0, v[132:133]
	s_add_i32 m0, s45, 0xe000
	s_nop 0
	global_load_lds_dwordx4 v[208:209], off
	s_waitcnt vmcnt(8)
	s_waitcnt lgkmcnt(0)
	s_barrier
	s_setprio 1
	s_waitcnt lgkmcnt(0)
	v_mfma_f32_16x16x32_bf16 v[124:127], v[138:141], v[176:179], v[124:127]
	v_mfma_f32_16x16x32_bf16 v[120:123], v[152:155], v[176:179], v[120:123]
	v_mfma_f32_16x16x32_bf16 v[108:111], v[138:141], v[184:187], v[108:111]
	v_mfma_f32_16x16x32_bf16 v[104:107], v[152:155], v[184:187], v[104:107]
	v_mfma_f32_16x16x32_bf16 v[92:95], v[138:141], v[192:195], v[92:95]
	v_mfma_f32_16x16x32_bf16 v[88:91], v[152:155], v[192:195], v[88:91]
	v_mfma_f32_16x16x32_bf16 v[76:79], v[138:141], v[200:203], v[76:79]
	v_mfma_f32_16x16x32_bf16 v[72:75], v[152:155], v[200:203], v[72:75]
	v_mfma_f32_16x16x32_bf16 v[124:127], v[148:151], v[180:183], v[124:127]
	v_mfma_f32_16x16x32_bf16 v[120:123], v[156:159], v[180:183], v[120:123]
	v_mfma_f32_16x16x32_bf16 v[108:111], v[148:151], v[188:191], v[108:111]
	v_mfma_f32_16x16x32_bf16 v[104:107], v[156:159], v[188:191], v[104:107]
	v_mfma_f32_16x16x32_bf16 v[92:95], v[148:151], v[196:199], v[92:95]
	v_mfma_f32_16x16x32_bf16 v[88:91], v[156:159], v[196:199], v[88:91]
	v_mfma_f32_16x16x32_bf16 v[76:79], v[148:151], v[204:207], v[76:79]
	v_mfma_f32_16x16x32_bf16 v[72:75], v[156:159], v[204:207], v[72:75]
	v_mfma_f32_16x16x32_bf16 v[116:119], v[160:163], v[176:179], v[116:119]
	v_mfma_f32_16x16x32_bf16 v[112:115], v[168:171], v[176:179], v[112:115]
	v_mfma_f32_16x16x32_bf16 v[100:103], v[160:163], v[184:187], v[100:103]
	v_mfma_f32_16x16x32_bf16 v[96:99], v[168:171], v[184:187], v[96:99]
	v_mfma_f32_16x16x32_bf16 v[84:87], v[160:163], v[192:195], v[84:87]
	v_mfma_f32_16x16x32_bf16 v[80:83], v[168:171], v[192:195], v[80:83]
	v_mfma_f32_16x16x32_bf16 v[68:71], v[160:163], v[200:203], v[68:71]
	v_mfma_f32_16x16x32_bf16 v[64:67], v[168:171], v[200:203], v[64:67]
	v_mfma_f32_16x16x32_bf16 v[116:119], v[164:167], v[180:183], v[116:119]
	v_mfma_f32_16x16x32_bf16 v[112:115], v[172:175], v[180:183], v[112:115]
	v_mfma_f32_16x16x32_bf16 v[100:103], v[164:167], v[188:191], v[100:103]
	v_mfma_f32_16x16x32_bf16 v[96:99], v[172:175], v[188:191], v[96:99]
	v_mfma_f32_16x16x32_bf16 v[84:87], v[164:167], v[196:199], v[84:87]
	v_mfma_f32_16x16x32_bf16 v[80:83], v[172:175], v[196:199], v[80:83]
	v_mfma_f32_16x16x32_bf16 v[68:71], v[164:167], v[204:207], v[68:71]
	v_mfma_f32_16x16x32_bf16 v[64:67], v[172:175], v[204:207], v[64:67]
	s_setprio 0
	s_barrier
	s_add_i32 s73, s66, s58
	v_lshl_add_u64 v[208:209], s[50:51], 0, v[128:129]
	s_mov_b32 m0, s73
	ds_read_b128 v[176:179], v147 offset:16384
	ds_read_b128 v[180:183], v147 offset:17408
	ds_read_b128 v[184:187], v147 offset:18432
	ds_read_b128 v[188:191], v147 offset:19456
	ds_read_b128 v[192:195], v147 offset:20480
	ds_read_b128 v[196:199], v147 offset:21504
	ds_read_b128 v[200:203], v147 offset:22528
	ds_read_b128 v[204:207], v147 offset:23552
	global_load_lds_dwordx4 v[208:209], off
	s_add_i32 m0, s73, 0x2000
	s_add_u32 s74, s50, 0x40000
	v_lshl_add_u64 v[210:211], s[50:51], 0, v[130:131]
	s_addc_u32 s75, s51, 0
	s_add_i32 s73, s67, s58
	global_load_lds_dwordx4 v[210:211], off
	v_lshl_add_u64 v[212:213], s[74:75], 0, v[128:129]
	s_mov_b32 m0, s73
	v_lshl_add_u64 v[214:215], s[52:53], 0, v[130:131]
	global_load_lds_dwordx4 v[212:213], off
	v_lshl_add_u64 v[212:213], s[74:75], 0, v[130:131]
	s_add_i32 m0, s73, 0x2000
	s_nop 0
	global_load_lds_dwordx4 v[212:213], off
	v_lshl_add_u64 v[212:213], s[52:53], 0, v[128:129]
	s_mov_b32 m0, s45
	s_nop 0
	global_load_lds_dwordx4 v[212:213], off
	s_mov_b32 m0, s47
	s_nop 0
	global_load_lds_dwordx4 v[214:215], off
	s_waitcnt vmcnt(8)
	s_waitcnt lgkmcnt(0)
	s_barrier
	s_setprio 1
	s_waitcnt lgkmcnt(0)
	v_mfma_f32_16x16x32_bf16 v[60:63], v[138:141], v[176:179], v[60:63]
	v_mfma_f32_16x16x32_bf16 v[56:59], v[152:155], v[176:179], v[56:59]
	v_mfma_f32_16x16x32_bf16 v[44:47], v[138:141], v[184:187], v[44:47]
	v_mfma_f32_16x16x32_bf16 v[40:43], v[152:155], v[184:187], v[40:43]
	v_mfma_f32_16x16x32_bf16 v[28:31], v[138:141], v[192:195], v[28:31]
	v_mfma_f32_16x16x32_bf16 v[24:27], v[152:155], v[192:195], v[24:27]
	v_mfma_f32_16x16x32_bf16 v[12:15], v[138:141], v[200:203], v[12:15]
	v_mfma_f32_16x16x32_bf16 v[8:11], v[152:155], v[200:203], v[8:11]
	v_mfma_f32_16x16x32_bf16 v[60:63], v[148:151], v[180:183], v[60:63]
	v_mfma_f32_16x16x32_bf16 v[56:59], v[156:159], v[180:183], v[56:59]
	v_mfma_f32_16x16x32_bf16 v[44:47], v[148:151], v[188:191], v[44:47]
	v_mfma_f32_16x16x32_bf16 v[40:43], v[156:159], v[188:191], v[40:43]
	v_mfma_f32_16x16x32_bf16 v[28:31], v[148:151], v[196:199], v[28:31]
	v_mfma_f32_16x16x32_bf16 v[24:27], v[156:159], v[196:199], v[24:27]
	v_mfma_f32_16x16x32_bf16 v[12:15], v[148:151], v[204:207], v[12:15]
	v_mfma_f32_16x16x32_bf16 v[8:11], v[156:159], v[204:207], v[8:11]
	v_mfma_f32_16x16x32_bf16 v[52:55], v[160:163], v[176:179], v[52:55]
	v_mfma_f32_16x16x32_bf16 v[48:51], v[168:171], v[176:179], v[48:51]
	v_mfma_f32_16x16x32_bf16 v[36:39], v[160:163], v[184:187], v[36:39]
	v_mfma_f32_16x16x32_bf16 v[32:35], v[168:171], v[184:187], v[32:35]
	v_mfma_f32_16x16x32_bf16 v[20:23], v[160:163], v[192:195], v[20:23]
	v_mfma_f32_16x16x32_bf16 v[16:19], v[168:171], v[192:195], v[16:19]
	v_mfma_f32_16x16x32_bf16 v[4:7], v[160:163], v[200:203], v[4:7]
	v_mfma_f32_16x16x32_bf16 v[0:3], v[168:171], v[200:203], v[0:3]
	v_mfma_f32_16x16x32_bf16 v[52:55], v[164:167], v[180:183], v[52:55]
	v_mfma_f32_16x16x32_bf16 v[48:51], v[172:175], v[180:183], v[48:51]
	v_mfma_f32_16x16x32_bf16 v[36:39], v[164:167], v[188:191], v[36:39]
	v_mfma_f32_16x16x32_bf16 v[32:35], v[172:175], v[188:191], v[32:35]
	v_mfma_f32_16x16x32_bf16 v[20:23], v[164:167], v[196:199], v[20:23]
	v_mfma_f32_16x16x32_bf16 v[16:19], v[172:175], v[196:199], v[16:19]
	v_mfma_f32_16x16x32_bf16 v[4:7], v[164:167], v[204:207], v[4:7]
	v_mfma_f32_16x16x32_bf16 v[0:3], v[172:175], v[204:207], v[0:3]
	s_setprio 0
	s_barrier
	s_add_i32 s73, 0, 0x18000
	s_add_i32 s74, 0, 0x1c000
	v_add_u32_e32 v156, s73, v143
	v_add_u32_e32 v172, s74, v143
	ds_read_b128 v[138:141], v156
	ds_read_b128 v[148:151], v156 offset:1024
	ds_read_b128 v[152:155], v156 offset:2048
	ds_read_b128 v[156:159], v156 offset:3072
	ds_read_b128 v[160:163], v172
	ds_read_b128 v[164:167], v172 offset:1024
	ds_read_b128 v[168:171], v172 offset:2048
	ds_read_b128 v[172:175], v172 offset:3072
	s_add_u32 s52, s52, 0x40000
	s_addc_u32 s53, s53, 0
	s_mov_b32 m0, s59
	v_lshl_add_u64 v[216:217], s[52:53], 0, v[128:129]
	ds_read_b128 v[176:179], v147 offset:32768
	ds_read_b128 v[180:183], v147 offset:33792
	ds_read_b128 v[184:187], v147 offset:34816
	ds_read_b128 v[188:191], v147 offset:35840
	ds_read_b128 v[192:195], v147 offset:36864
	ds_read_b128 v[196:199], v147 offset:37888
	ds_read_b128 v[200:203], v147 offset:38912
	ds_read_b128 v[204:207], v147 offset:39936
	global_load_lds_dwordx4 v[216:217], off
	v_lshl_add_u64 v[216:217], s[52:53], 0, v[130:131]
	s_mov_b32 m0, s60
	s_nop 0
	global_load_lds_dwordx4 v[216:217], off
	s_waitcnt vmcnt(8)
	s_waitcnt lgkmcnt(0)
	s_barrier
	s_setprio 1
	s_waitcnt lgkmcnt(0)
	v_mfma_f32_16x16x32_bf16 v[124:127], v[138:141], v[176:179], v[124:127]
	v_mfma_f32_16x16x32_bf16 v[120:123], v[152:155], v[176:179], v[120:123]
	v_mfma_f32_16x16x32_bf16 v[108:111], v[138:141], v[184:187], v[108:111]
	v_mfma_f32_16x16x32_bf16 v[104:107], v[152:155], v[184:187], v[104:107]
	v_mfma_f32_16x16x32_bf16 v[92:95], v[138:141], v[192:195], v[92:95]
	v_mfma_f32_16x16x32_bf16 v[88:91], v[152:155], v[192:195], v[88:91]
	v_mfma_f32_16x16x32_bf16 v[76:79], v[138:141], v[200:203], v[76:79]
	v_mfma_f32_16x16x32_bf16 v[72:75], v[152:155], v[200:203], v[72:75]
	v_mfma_f32_16x16x32_bf16 v[124:127], v[148:151], v[180:183], v[124:127]
	v_mfma_f32_16x16x32_bf16 v[120:123], v[156:159], v[180:183], v[120:123]
	v_mfma_f32_16x16x32_bf16 v[108:111], v[148:151], v[188:191], v[108:111]
	v_mfma_f32_16x16x32_bf16 v[104:107], v[156:159], v[188:191], v[104:107]
	v_mfma_f32_16x16x32_bf16 v[92:95], v[148:151], v[196:199], v[92:95]
	v_mfma_f32_16x16x32_bf16 v[88:91], v[156:159], v[196:199], v[88:91]
	v_mfma_f32_16x16x32_bf16 v[76:79], v[148:151], v[204:207], v[76:79]
	v_mfma_f32_16x16x32_bf16 v[72:75], v[156:159], v[204:207], v[72:75]
	v_mfma_f32_16x16x32_bf16 v[116:119], v[160:163], v[176:179], v[116:119]
	v_mfma_f32_16x16x32_bf16 v[112:115], v[168:171], v[176:179], v[112:115]
	v_mfma_f32_16x16x32_bf16 v[100:103], v[160:163], v[184:187], v[100:103]
	v_mfma_f32_16x16x32_bf16 v[96:99], v[168:171], v[184:187], v[96:99]
	v_mfma_f32_16x16x32_bf16 v[84:87], v[160:163], v[192:195], v[84:87]
	v_mfma_f32_16x16x32_bf16 v[80:83], v[168:171], v[192:195], v[80:83]
	v_mfma_f32_16x16x32_bf16 v[68:71], v[160:163], v[200:203], v[68:71]
	v_mfma_f32_16x16x32_bf16 v[64:67], v[168:171], v[200:203], v[64:67]
	v_mfma_f32_16x16x32_bf16 v[116:119], v[164:167], v[180:183], v[116:119]
	v_mfma_f32_16x16x32_bf16 v[112:115], v[172:175], v[180:183], v[112:115]
	v_mfma_f32_16x16x32_bf16 v[100:103], v[164:167], v[188:191], v[100:103]
	v_mfma_f32_16x16x32_bf16 v[96:99], v[172:175], v[188:191], v[96:99]
	v_mfma_f32_16x16x32_bf16 v[84:87], v[164:167], v[196:199], v[84:87]
	v_mfma_f32_16x16x32_bf16 v[80:83], v[172:175], v[196:199], v[80:83]
	v_mfma_f32_16x16x32_bf16 v[68:71], v[164:167], v[204:207], v[68:71]
	v_mfma_f32_16x16x32_bf16 v[64:67], v[172:175], v[204:207], v[64:67]
	s_setprio 0
	s_barrier
	s_add_i32 s52, s73, s58
	v_lshl_add_u64 v[208:209], v[208:209], 0, s[28:29]
	s_mov_b32 m0, s52
	ds_read_b128 v[176:179], v147 offset:49152
	ds_read_b128 v[180:183], v147 offset:50176
	ds_read_b128 v[184:187], v147 offset:51200
	ds_read_b128 v[188:191], v147 offset:52224
	ds_read_b128 v[192:195], v147 offset:53248
	ds_read_b128 v[196:199], v147 offset:54272
	ds_read_b128 v[200:203], v147 offset:55296
	ds_read_b128 v[204:207], v147 offset:56320
	global_load_lds_dwordx4 v[208:209], off
	s_add_i32 m0, s52, 0x2000
	s_add_u32 s50, s50, 0x40080
	v_lshl_add_u64 v[208:209], v[210:211], 0, s[28:29]
	s_addc_u32 s51, s51, 0
	s_add_i32 s52, s74, s58
	global_load_lds_dwordx4 v[208:209], off
	v_lshl_add_u64 v[208:209], s[50:51], 0, v[128:129]
	s_mov_b32 m0, s52
	s_nop 0
	global_load_lds_dwordx4 v[208:209], off
	v_lshl_add_u64 v[208:209], s[50:51], 0, v[130:131]
	s_add_i32 m0, s52, 0x2000
	s_nop 0
	global_load_lds_dwordx4 v[208:209], off
	v_lshl_add_u64 v[208:209], v[212:213], 0, s[28:29]
	s_mov_b32 m0, s62
	s_nop 0
	global_load_lds_dwordx4 v[208:209], off
	v_lshl_add_u64 v[208:209], v[214:215], 0, s[28:29]
	s_mov_b32 m0, s63
	s_nop 0
	global_load_lds_dwordx4 v[208:209], off
	s_waitcnt vmcnt(8)
	s_waitcnt lgkmcnt(0)
	s_barrier
	s_setprio 1
	s_waitcnt lgkmcnt(0)
	v_mfma_f32_16x16x32_bf16 v[60:63], v[138:141], v[176:179], v[60:63]
	v_mfma_f32_16x16x32_bf16 v[56:59], v[152:155], v[176:179], v[56:59]
	v_mfma_f32_16x16x32_bf16 v[44:47], v[138:141], v[184:187], v[44:47]
	v_mfma_f32_16x16x32_bf16 v[40:43], v[152:155], v[184:187], v[40:43]
	v_mfma_f32_16x16x32_bf16 v[28:31], v[138:141], v[192:195], v[28:31]
	v_mfma_f32_16x16x32_bf16 v[24:27], v[152:155], v[192:195], v[24:27]
	v_mfma_f32_16x16x32_bf16 v[12:15], v[138:141], v[200:203], v[12:15]
	v_mfma_f32_16x16x32_bf16 v[8:11], v[152:155], v[200:203], v[8:11]
	v_mfma_f32_16x16x32_bf16 v[60:63], v[148:151], v[180:183], v[60:63]
	v_mfma_f32_16x16x32_bf16 v[56:59], v[156:159], v[180:183], v[56:59]
	v_mfma_f32_16x16x32_bf16 v[44:47], v[148:151], v[188:191], v[44:47]
	v_mfma_f32_16x16x32_bf16 v[40:43], v[156:159], v[188:191], v[40:43]
	v_mfma_f32_16x16x32_bf16 v[28:31], v[148:151], v[196:199], v[28:31]
	v_mfma_f32_16x16x32_bf16 v[24:27], v[156:159], v[196:199], v[24:27]
	v_mfma_f32_16x16x32_bf16 v[12:15], v[148:151], v[204:207], v[12:15]
	v_mfma_f32_16x16x32_bf16 v[8:11], v[156:159], v[204:207], v[8:11]
	v_mfma_f32_16x16x32_bf16 v[52:55], v[160:163], v[176:179], v[52:55]
	v_mfma_f32_16x16x32_bf16 v[48:51], v[168:171], v[176:179], v[48:51]
	v_mfma_f32_16x16x32_bf16 v[36:39], v[160:163], v[184:187], v[36:39]
	v_mfma_f32_16x16x32_bf16 v[32:35], v[168:171], v[184:187], v[32:35]
	v_mfma_f32_16x16x32_bf16 v[20:23], v[160:163], v[192:195], v[20:23]
	v_mfma_f32_16x16x32_bf16 v[16:19], v[168:171], v[192:195], v[16:19]
	v_mfma_f32_16x16x32_bf16 v[4:7], v[160:163], v[200:203], v[4:7]
	v_mfma_f32_16x16x32_bf16 v[0:3], v[168:171], v[200:203], v[0:3]
	v_mfma_f32_16x16x32_bf16 v[52:55], v[164:167], v[180:183], v[52:55]
	v_mfma_f32_16x16x32_bf16 v[48:51], v[172:175], v[180:183], v[48:51]
	v_mfma_f32_16x16x32_bf16 v[36:39], v[164:167], v[188:191], v[36:39]
	v_mfma_f32_16x16x32_bf16 v[32:35], v[172:175], v[188:191], v[32:35]
	v_mfma_f32_16x16x32_bf16 v[20:23], v[164:167], v[196:199], v[20:23]
	v_mfma_f32_16x16x32_bf16 v[16:19], v[172:175], v[196:199], v[16:19]
	v_mfma_f32_16x16x32_bf16 v[4:7], v[164:167], v[204:207], v[4:7]
	v_mfma_f32_16x16x32_bf16 v[0:3], v[172:175], v[204:207], v[0:3]
	s_setprio 0
	s_barrier
	s_add_i32 s72, s72, 2
	s_add_u32 s70, s70, 0x100
	s_addc_u32 s71, s71, 0
	s_add_u32 s48, s48, 0x100
	s_addc_u32 s49, s49, 0
	s_cmp_gt_u32 s72, 13
	s_cbranch_scc0 .LBB0_934
	s_and_b64 vcc, exec, s[30:31]
	s_cbranch_vccz .LBB0_937
	s_barrier

.LBB0_958:
	ds_read_b128 v[138:141], v145
	ds_read_b128 v[148:151], v145 offset:1024
	ds_read_b128 v[152:155], v145 offset:2048
	ds_read_b128 v[156:159], v145 offset:3072
	ds_read_b128 v[160:163], v146
	ds_read_b128 v[164:167], v146 offset:1024
	ds_read_b128 v[168:171], v146 offset:2048
	ds_read_b128 v[172:175], v146 offset:3072
	s_add_u32 s44, s42, 0xfffc0080
	s_addc_u32 s45, s43, -1
	s_cmp_eq_u32 s64, 12
	s_cselect_b32 s47, s17, s45
	s_cselect_b32 s46, s31, s44
	s_cselect_b32 s45, s35, s63
	s_cselect_b32 s44, s61, s62
	v_lshl_add_u64 v[208:209], s[42:43], 0, v[134:135]
	s_add_i32 m0, s19, 0xc000
	ds_read_b128 v[176:179], v147
	ds_read_b128 v[180:183], v147 offset:1024
	ds_read_b128 v[184:187], v147 offset:2048
	ds_read_b128 v[188:191], v147 offset:3072
	ds_read_b128 v[192:195], v147 offset:4096
	ds_read_b128 v[196:199], v147 offset:5120
	ds_read_b128 v[200:203], v147 offset:6144
	ds_read_b128 v[204:207], v147 offset:7168
	global_load_lds_dwordx4 v[208:209], off
	v_lshl_add_u64 v[208:209], s[42:43], 0, v[132:133]
	s_add_i32 m0, s19, 0xe000
	s_nop 0
	global_load_lds_dwordx4 v[208:209], off
	s_waitcnt vmcnt(8)
	s_waitcnt lgkmcnt(0)
	s_barrier
	s_setprio 1
	s_waitcnt lgkmcnt(0)
	v_mfma_f32_16x16x32_bf16 v[124:127], v[138:141], v[176:179], v[124:127]
	v_mfma_f32_16x16x32_bf16 v[120:123], v[152:155], v[176:179], v[120:123]
	v_mfma_f32_16x16x32_bf16 v[112:115], v[138:141], v[184:187], v[112:115]
	v_mfma_f32_16x16x32_bf16 v[104:107], v[152:155], v[184:187], v[104:107]
	v_mfma_f32_16x16x32_bf16 v[96:99], v[138:141], v[192:195], v[96:99]
	v_mfma_f32_16x16x32_bf16 v[88:91], v[152:155], v[192:195], v[88:91]
	v_mfma_f32_16x16x32_bf16 v[80:83], v[138:141], v[200:203], v[80:83]
	v_mfma_f32_16x16x32_bf16 v[72:75], v[152:155], v[200:203], v[72:75]
	v_mfma_f32_16x16x32_bf16 v[124:127], v[148:151], v[180:183], v[124:127]
	v_mfma_f32_16x16x32_bf16 v[120:123], v[156:159], v[180:183], v[120:123]
	v_mfma_f32_16x16x32_bf16 v[112:115], v[148:151], v[188:191], v[112:115]
	v_mfma_f32_16x16x32_bf16 v[104:107], v[156:159], v[188:191], v[104:107]
	v_mfma_f32_16x16x32_bf16 v[96:99], v[148:151], v[196:199], v[96:99]
	v_mfma_f32_16x16x32_bf16 v[88:91], v[156:159], v[196:199], v[88:91]
	v_mfma_f32_16x16x32_bf16 v[80:83], v[148:151], v[204:207], v[80:83]
	v_mfma_f32_16x16x32_bf16 v[72:75], v[156:159], v[204:207], v[72:75]
	v_mfma_f32_16x16x32_bf16 v[116:119], v[160:163], v[176:179], v[116:119]
	v_mfma_f32_16x16x32_bf16 v[108:111], v[168:171], v[176:179], v[108:111]
	v_mfma_f32_16x16x32_bf16 v[100:103], v[160:163], v[184:187], v[100:103]
	v_mfma_f32_16x16x32_bf16 v[92:95], v[168:171], v[184:187], v[92:95]
	v_mfma_f32_16x16x32_bf16 v[84:87], v[160:163], v[192:195], v[84:87]
	v_mfma_f32_16x16x32_bf16 v[76:79], v[168:171], v[192:195], v[76:79]
	v_mfma_f32_16x16x32_bf16 v[68:71], v[160:163], v[200:203], v[68:71]
	v_mfma_f32_16x16x32_bf16 v[64:67], v[168:171], v[200:203], v[64:67]
	v_mfma_f32_16x16x32_bf16 v[116:119], v[164:167], v[180:183], v[116:119]
	v_mfma_f32_16x16x32_bf16 v[108:111], v[172:175], v[180:183], v[108:111]
	v_mfma_f32_16x16x32_bf16 v[100:103], v[164:167], v[188:191], v[100:103]
	v_mfma_f32_16x16x32_bf16 v[92:95], v[172:175], v[188:191], v[92:95]
	v_mfma_f32_16x16x32_bf16 v[84:87], v[164:167], v[196:199], v[84:87]
	v_mfma_f32_16x16x32_bf16 v[76:79], v[172:175], v[196:199], v[76:79]
	v_mfma_f32_16x16x32_bf16 v[68:71], v[164:167], v[204:207], v[68:71]
	v_mfma_f32_16x16x32_bf16 v[64:67], v[172:175], v[204:207], v[64:67]
	s_setprio 0
	s_barrier
	s_add_i32 s65, s59, s48
	v_lshl_add_u64 v[208:209], s[44:45], 0, v[128:129]
	s_mov_b32 m0, s65
	ds_read_b128 v[176:179], v147 offset:16384
	ds_read_b128 v[180:183], v147 offset:17408
	ds_read_b128 v[184:187], v147 offset:18432
	ds_read_b128 v[188:191], v147 offset:19456
	ds_read_b128 v[192:195], v147 offset:20480
	ds_read_b128 v[196:199], v147 offset:21504
	ds_read_b128 v[200:203], v147 offset:22528
	ds_read_b128 v[204:207], v147 offset:23552
	global_load_lds_dwordx4 v[208:209], off
	s_add_i32 m0, s65, 0x2000
	s_add_u32 s66, s44, 0x40000
	v_lshl_add_u64 v[210:211], s[44:45], 0, v[130:131]
	s_addc_u32 s67, s45, 0
	s_add_i32 s65, s60, s48
	global_load_lds_dwordx4 v[210:211], off
	v_lshl_add_u64 v[212:213], s[66:67], 0, v[128:129]
	s_mov_b32 m0, s65
	v_lshl_add_u64 v[214:215], s[46:47], 0, v[130:131]
	global_load_lds_dwordx4 v[212:213], off
	v_lshl_add_u64 v[212:213], s[66:67], 0, v[130:131]
	s_add_i32 m0, s65, 0x2000
	s_nop 0
	global_load_lds_dwordx4 v[212:213], off
	v_lshl_add_u64 v[212:213], s[46:47], 0, v[128:129]
	s_mov_b32 m0, s19
	s_nop 0
	global_load_lds_dwordx4 v[212:213], off
	s_mov_b32 m0, s49
	s_nop 0
	global_load_lds_dwordx4 v[214:215], off
	s_waitcnt vmcnt(8)
	s_waitcnt lgkmcnt(0)
	s_barrier
	s_setprio 1
	s_waitcnt lgkmcnt(0)
	v_mfma_f32_16x16x32_bf16 v[60:63], v[138:141], v[176:179], v[60:63]
	v_mfma_f32_16x16x32_bf16 v[56:59], v[152:155], v[176:179], v[56:59]
	v_mfma_f32_16x16x32_bf16 v[48:51], v[138:141], v[184:187], v[48:51]
	v_mfma_f32_16x16x32_bf16 v[40:43], v[152:155], v[184:187], v[40:43]
	v_mfma_f32_16x16x32_bf16 v[32:35], v[138:141], v[192:195], v[32:35]
	v_mfma_f32_16x16x32_bf16 v[24:27], v[152:155], v[192:195], v[24:27]
	v_mfma_f32_16x16x32_bf16 v[16:19], v[138:141], v[200:203], v[16:19]
	v_mfma_f32_16x16x32_bf16 v[8:11], v[152:155], v[200:203], v[8:11]
	v_mfma_f32_16x16x32_bf16 v[60:63], v[148:151], v[180:183], v[60:63]
	v_mfma_f32_16x16x32_bf16 v[56:59], v[156:159], v[180:183], v[56:59]
	v_mfma_f32_16x16x32_bf16 v[48:51], v[148:151], v[188:191], v[48:51]
	v_mfma_f32_16x16x32_bf16 v[40:43], v[156:159], v[188:191], v[40:43]
	v_mfma_f32_16x16x32_bf16 v[32:35], v[148:151], v[196:199], v[32:35]
	v_mfma_f32_16x16x32_bf16 v[24:27], v[156:159], v[196:199], v[24:27]
	v_mfma_f32_16x16x32_bf16 v[16:19], v[148:151], v[204:207], v[16:19]
	v_mfma_f32_16x16x32_bf16 v[8:11], v[156:159], v[204:207], v[8:11]
	v_mfma_f32_16x16x32_bf16 v[52:55], v[160:163], v[176:179], v[52:55]
	v_mfma_f32_16x16x32_bf16 v[44:47], v[168:171], v[176:179], v[44:47]
	v_mfma_f32_16x16x32_bf16 v[36:39], v[160:163], v[184:187], v[36:39]
	v_mfma_f32_16x16x32_bf16 v[28:31], v[168:171], v[184:187], v[28:31]
	v_mfma_f32_16x16x32_bf16 v[20:23], v[160:163], v[192:195], v[20:23]
	v_mfma_f32_16x16x32_bf16 v[12:15], v[168:171], v[192:195], v[12:15]
	v_mfma_f32_16x16x32_bf16 v[4:7], v[160:163], v[200:203], v[4:7]
	v_mfma_f32_16x16x32_bf16 v[0:3], v[168:171], v[200:203], v[0:3]
	v_mfma_f32_16x16x32_bf16 v[52:55], v[164:167], v[180:183], v[52:55]
	v_mfma_f32_16x16x32_bf16 v[44:47], v[172:175], v[180:183], v[44:47]
	v_mfma_f32_16x16x32_bf16 v[36:39], v[164:167], v[188:191], v[36:39]
	v_mfma_f32_16x16x32_bf16 v[28:31], v[172:175], v[188:191], v[28:31]
	v_mfma_f32_16x16x32_bf16 v[20:23], v[164:167], v[196:199], v[20:23]
	v_mfma_f32_16x16x32_bf16 v[12:15], v[172:175], v[196:199], v[12:15]
	v_mfma_f32_16x16x32_bf16 v[4:7], v[164:167], v[204:207], v[4:7]
	v_mfma_f32_16x16x32_bf16 v[0:3], v[172:175], v[204:207], v[0:3]
	s_setprio 0
	s_barrier
	s_add_i32 s65, 0, 0x18000
	s_add_i32 s66, 0, 0x1c000
	v_add_u32_e32 v156, s65, v143
	v_add_u32_e32 v172, s66, v143
	ds_read_b128 v[138:141], v156
	ds_read_b128 v[148:151], v156 offset:1024
	ds_read_b128 v[152:155], v156 offset:2048
	ds_read_b128 v[156:159], v156 offset:3072
	ds_read_b128 v[160:163], v172
	ds_read_b128 v[164:167], v172 offset:1024
	ds_read_b128 v[168:171], v172 offset:2048
	ds_read_b128 v[172:175], v172 offset:3072
	s_add_u32 s46, s46, 0x40000
	s_addc_u32 s47, s47, 0
	s_mov_b32 m0, s50
	v_lshl_add_u64 v[216:217], s[46:47], 0, v[128:129]
	ds_read_b128 v[176:179], v147 offset:32768
	ds_read_b128 v[180:183], v147 offset:33792
	ds_read_b128 v[184:187], v147 offset:34816
	ds_read_b128 v[188:191], v147 offset:35840
	ds_read_b128 v[192:195], v147 offset:36864
	ds_read_b128 v[196:199], v147 offset:37888
	ds_read_b128 v[200:203], v147 offset:38912
	ds_read_b128 v[204:207], v147 offset:39936
	global_load_lds_dwordx4 v[216:217], off
	v_lshl_add_u64 v[216:217], s[46:47], 0, v[130:131]
	s_mov_b32 m0, s51
	s_nop 0
	global_load_lds_dwordx4 v[216:217], off
	s_waitcnt vmcnt(8)
	s_waitcnt lgkmcnt(0)
	s_barrier
	s_setprio 1
	s_waitcnt lgkmcnt(0)
	v_mfma_f32_16x16x32_bf16 v[124:127], v[138:141], v[176:179], v[124:127]
	v_mfma_f32_16x16x32_bf16 v[120:123], v[152:155], v[176:179], v[120:123]
	v_mfma_f32_16x16x32_bf16 v[112:115], v[138:141], v[184:187], v[112:115]
	v_mfma_f32_16x16x32_bf16 v[104:107], v[152:155], v[184:187], v[104:107]
	v_mfma_f32_16x16x32_bf16 v[96:99], v[138:141], v[192:195], v[96:99]
	v_mfma_f32_16x16x32_bf16 v[88:91], v[152:155], v[192:195], v[88:91]
	v_mfma_f32_16x16x32_bf16 v[80:83], v[138:141], v[200:203], v[80:83]
	v_mfma_f32_16x16x32_bf16 v[72:75], v[152:155], v[200:203], v[72:75]
	v_mfma_f32_16x16x32_bf16 v[124:127], v[148:151], v[180:183], v[124:127]
	v_mfma_f32_16x16x32_bf16 v[120:123], v[156:159], v[180:183], v[120:123]
	v_mfma_f32_16x16x32_bf16 v[112:115], v[148:151], v[188:191], v[112:115]
	v_mfma_f32_16x16x32_bf16 v[104:107], v[156:159], v[188:191], v[104:107]
	v_mfma_f32_16x16x32_bf16 v[96:99], v[148:151], v[196:199], v[96:99]
	v_mfma_f32_16x16x32_bf16 v[88:91], v[156:159], v[196:199], v[88:91]
	v_mfma_f32_16x16x32_bf16 v[80:83], v[148:151], v[204:207], v[80:83]
	v_mfma_f32_16x16x32_bf16 v[72:75], v[156:159], v[204:207], v[72:75]
	v_mfma_f32_16x16x32_bf16 v[116:119], v[160:163], v[176:179], v[116:119]
	v_mfma_f32_16x16x32_bf16 v[108:111], v[168:171], v[176:179], v[108:111]
	v_mfma_f32_16x16x32_bf16 v[100:103], v[160:163], v[184:187], v[100:103]
	v_mfma_f32_16x16x32_bf16 v[92:95], v[168:171], v[184:187], v[92:95]
	v_mfma_f32_16x16x32_bf16 v[84:87], v[160:163], v[192:195], v[84:87]
	v_mfma_f32_16x16x32_bf16 v[76:79], v[168:171], v[192:195], v[76:79]
	v_mfma_f32_16x16x32_bf16 v[68:71], v[160:163], v[200:203], v[68:71]
	v_mfma_f32_16x16x32_bf16 v[64:67], v[168:171], v[200:203], v[64:67]
	v_mfma_f32_16x16x32_bf16 v[116:119], v[164:167], v[180:183], v[116:119]
	v_mfma_f32_16x16x32_bf16 v[108:111], v[172:175], v[180:183], v[108:111]
	v_mfma_f32_16x16x32_bf16 v[100:103], v[164:167], v[188:191], v[100:103]
	v_mfma_f32_16x16x32_bf16 v[92:95], v[172:175], v[188:191], v[92:95]
	v_mfma_f32_16x16x32_bf16 v[84:87], v[164:167], v[196:199], v[84:87]
	v_mfma_f32_16x16x32_bf16 v[76:79], v[172:175], v[196:199], v[76:79]
	v_mfma_f32_16x16x32_bf16 v[68:71], v[164:167], v[204:207], v[68:71]
	v_mfma_f32_16x16x32_bf16 v[64:67], v[172:175], v[204:207], v[64:67]
	s_setprio 0
	s_barrier
	s_add_i32 s46, s65, s48
	v_lshl_add_u64 v[208:209], v[208:209], 0, s[26:27]
	s_mov_b32 m0, s46
	ds_read_b128 v[176:179], v147 offset:49152
	ds_read_b128 v[180:183], v147 offset:50176
	ds_read_b128 v[184:187], v147 offset:51200
	ds_read_b128 v[188:191], v147 offset:52224
	ds_read_b128 v[192:195], v147 offset:53248
	ds_read_b128 v[196:199], v147 offset:54272
	ds_read_b128 v[200:203], v147 offset:55296
	ds_read_b128 v[204:207], v147 offset:56320
	global_load_lds_dwordx4 v[208:209], off
	s_add_i32 m0, s46, 0x2000
	s_add_u32 s44, s44, 0x40080
	v_lshl_add_u64 v[208:209], v[210:211], 0, s[26:27]
	s_addc_u32 s45, s45, 0
	s_add_i32 s46, s66, s48
	global_load_lds_dwordx4 v[208:209], off
	v_lshl_add_u64 v[208:209], s[44:45], 0, v[128:129]
	s_mov_b32 m0, s46
	s_nop 0
	global_load_lds_dwordx4 v[208:209], off
	v_lshl_add_u64 v[208:209], s[44:45], 0, v[130:131]
	s_add_i32 m0, s46, 0x2000
	s_nop 0
	global_load_lds_dwordx4 v[208:209], off
	v_lshl_add_u64 v[208:209], v[212:213], 0, s[26:27]
	s_mov_b32 m0, s52
	s_nop 0
	global_load_lds_dwordx4 v[208:209], off
	v_lshl_add_u64 v[208:209], v[214:215], 0, s[26:27]
	s_mov_b32 m0, s53
	s_nop 0
	global_load_lds_dwordx4 v[208:209], off
	s_waitcnt vmcnt(8)
	s_waitcnt lgkmcnt(0)
	s_barrier
	s_setprio 1
	s_waitcnt lgkmcnt(0)
	v_mfma_f32_16x16x32_bf16 v[60:63], v[138:141], v[176:179], v[60:63]
	v_mfma_f32_16x16x32_bf16 v[56:59], v[152:155], v[176:179], v[56:59]
	v_mfma_f32_16x16x32_bf16 v[48:51], v[138:141], v[184:187], v[48:51]
	v_mfma_f32_16x16x32_bf16 v[40:43], v[152:155], v[184:187], v[40:43]
	v_mfma_f32_16x16x32_bf16 v[32:35], v[138:141], v[192:195], v[32:35]
	v_mfma_f32_16x16x32_bf16 v[24:27], v[152:155], v[192:195], v[24:27]
	v_mfma_f32_16x16x32_bf16 v[16:19], v[138:141], v[200:203], v[16:19]
	v_mfma_f32_16x16x32_bf16 v[8:11], v[152:155], v[200:203], v[8:11]
	v_mfma_f32_16x16x32_bf16 v[60:63], v[148:151], v[180:183], v[60:63]
	v_mfma_f32_16x16x32_bf16 v[56:59], v[156:159], v[180:183], v[56:59]
	v_mfma_f32_16x16x32_bf16 v[48:51], v[148:151], v[188:191], v[48:51]
	v_mfma_f32_16x16x32_bf16 v[40:43], v[156:159], v[188:191], v[40:43]
	v_mfma_f32_16x16x32_bf16 v[32:35], v[148:151], v[196:199], v[32:35]
	v_mfma_f32_16x16x32_bf16 v[24:27], v[156:159], v[196:199], v[24:27]
	v_mfma_f32_16x16x32_bf16 v[16:19], v[148:151], v[204:207], v[16:19]
	v_mfma_f32_16x16x32_bf16 v[8:11], v[156:159], v[204:207], v[8:11]
	v_mfma_f32_16x16x32_bf16 v[52:55], v[160:163], v[176:179], v[52:55]
	v_mfma_f32_16x16x32_bf16 v[44:47], v[168:171], v[176:179], v[44:47]
	v_mfma_f32_16x16x32_bf16 v[36:39], v[160:163], v[184:187], v[36:39]
	v_mfma_f32_16x16x32_bf16 v[28:31], v[168:171], v[184:187], v[28:31]
	v_mfma_f32_16x16x32_bf16 v[20:23], v[160:163], v[192:195], v[20:23]
	v_mfma_f32_16x16x32_bf16 v[12:15], v[168:171], v[192:195], v[12:15]
	v_mfma_f32_16x16x32_bf16 v[4:7], v[160:163], v[200:203], v[4:7]
	v_mfma_f32_16x16x32_bf16 v[0:3], v[168:171], v[200:203], v[0:3]
	v_mfma_f32_16x16x32_bf16 v[52:55], v[164:167], v[180:183], v[52:55]
	v_mfma_f32_16x16x32_bf16 v[44:47], v[172:175], v[180:183], v[44:47]
	v_mfma_f32_16x16x32_bf16 v[36:39], v[164:167], v[188:191], v[36:39]
	v_mfma_f32_16x16x32_bf16 v[28:31], v[172:175], v[188:191], v[28:31]
	v_mfma_f32_16x16x32_bf16 v[20:23], v[164:167], v[196:199], v[20:23]
	v_mfma_f32_16x16x32_bf16 v[12:15], v[172:175], v[196:199], v[12:15]
	v_mfma_f32_16x16x32_bf16 v[4:7], v[164:167], v[204:207], v[4:7]
	v_mfma_f32_16x16x32_bf16 v[0:3], v[172:175], v[204:207], v[0:3]
	s_setprio 0
	s_barrier
	s_add_i32 s64, s64, 2
	s_add_u32 s62, s62, 0x100
	s_addc_u32 s63, s63, 0
	s_add_u32 s42, s42, 0x100
	s_addc_u32 s43, s43, 0
	s_cmp_gt_u32 s64, 13
	s_cbranch_scc0 .LBB0_958
	s_and_b64 vcc, exec, s[28:29]
	s_cbranch_vccz .LBB0_961
	s_barrier

.LBB0_1078:
	ds_read_b128 v[0:3], v143
	ds_read_b128 v[4:7], v143 offset:1024
	ds_read_b128 v[8:11], v143 offset:2048
	ds_read_b128 v[12:15], v143 offset:3072
	ds_read_b128 v[16:19], v144
	ds_read_b128 v[20:23], v144 offset:1024
	ds_read_b128 v[24:27], v144 offset:2048
	ds_read_b128 v[28:31], v144 offset:3072
	s_ashr_i32 s35, s34, 31
	s_lshl_b64 s[36:37], s[34:35], 17
	s_add_u32 s36, s53, s36
	s_addc_u32 s37, s54, s37
	s_and_b64 s[40:41], s[38:39], exec
	s_cselect_b32 s49, s37, s43
	s_cselect_b32 s48, s36, s42
	s_ashr_i32 s31, s30, 31
	s_lshl_b64 s[40:41], s[30:31], 17
	s_add_u32 s40, s13, s40
	s_addc_u32 s41, s52, s41
	s_and_b64 s[46:47], s[38:39], exec
	s_cselect_b32 s47, s41, s45
	s_cselect_b32 s46, s40, s44
	s_add_u32 s68, s42, 0x10080
	s_addc_u32 s69, s43, 0
	s_mov_b32 m0, s63
	v_lshl_add_u64 v[64:65], s[68:69], 0, v[128:129]
	ds_read_b128 v[32:35], v145
	ds_read_b128 v[36:39], v145 offset:1024
	ds_read_b128 v[40:43], v145 offset:2048
	ds_read_b128 v[44:47], v145 offset:3072
	ds_read_b128 v[48:51], v145 offset:4096
	ds_read_b128 v[52:55], v145 offset:5120
	ds_read_b128 v[56:59], v145 offset:6144
	ds_read_b128 v[60:63], v145 offset:7168
	global_load_lds_dwordx4 v[64:65], off
	v_lshl_add_u64 v[64:65], s[68:69], 0, v[132:133]
	s_mov_b32 m0, s64
	s_nop 0
	global_load_lds_dwordx4 v[64:65], off
	s_waitcnt vmcnt(8)
	s_waitcnt lgkmcnt(0)
	s_barrier
	s_setprio 1
	s_waitcnt lgkmcnt(0)
	v_mfma_f32_16x16x32_bf16 v[64:67], v[0:3], v[32:35], 0
	v_mfma_f32_16x16x32_bf16 v[68:71], v[8:11], v[32:35], 0
	v_mfma_f32_16x16x32_bf16 v[72:75], v[0:3], v[40:43], 0
	v_mfma_f32_16x16x32_bf16 v[76:79], v[8:11], v[40:43], 0
	v_mfma_f32_16x16x32_bf16 v[80:83], v[0:3], v[48:51], 0
	v_mfma_f32_16x16x32_bf16 v[84:87], v[8:11], v[48:51], 0
	v_mfma_f32_16x16x32_bf16 v[88:91], v[0:3], v[56:59], 0
	v_mfma_f32_16x16x32_bf16 v[92:95], v[8:11], v[56:59], 0
	v_mfma_f32_16x16x32_bf16 v[64:67], v[4:7], v[36:39], v[64:67]
	v_mfma_f32_16x16x32_bf16 v[68:71], v[12:15], v[36:39], v[68:71]
	v_mfma_f32_16x16x32_bf16 v[72:75], v[4:7], v[44:47], v[72:75]
	v_mfma_f32_16x16x32_bf16 v[76:79], v[12:15], v[44:47], v[76:79]
	v_mfma_f32_16x16x32_bf16 v[80:83], v[4:7], v[52:55], v[80:83]
	v_mfma_f32_16x16x32_bf16 v[84:87], v[12:15], v[52:55], v[84:87]
	v_mfma_f32_16x16x32_bf16 v[88:91], v[4:7], v[60:63], v[88:91]
	v_mfma_f32_16x16x32_bf16 v[92:95], v[12:15], v[60:63], v[92:95]
	v_mfma_f32_16x16x32_bf16 v[96:99], v[16:19], v[32:35], 0
	v_mfma_f32_16x16x32_bf16 v[32:35], v[24:27], v[32:35], 0
	v_mfma_f32_16x16x32_bf16 v[96:99], v[20:23], v[36:39], v[96:99]
	v_mfma_f32_16x16x32_bf16 v[32:35], v[28:31], v[36:39], v[32:35]
	v_mfma_f32_16x16x32_bf16 v[36:39], v[16:19], v[40:43], 0
	v_mfma_f32_16x16x32_bf16 v[40:43], v[24:27], v[40:43], 0
	v_mfma_f32_16x16x32_bf16 v[36:39], v[20:23], v[44:47], v[36:39]
	v_mfma_f32_16x16x32_bf16 v[40:43], v[28:31], v[44:47], v[40:43]
	v_mfma_f32_16x16x32_bf16 v[44:47], v[16:19], v[48:51], 0
	v_mfma_f32_16x16x32_bf16 v[48:51], v[24:27], v[48:51], 0
	v_mfma_f32_16x16x32_bf16 v[44:47], v[20:23], v[52:55], v[44:47]
	v_mfma_f32_16x16x32_bf16 v[48:51], v[28:31], v[52:55], v[48:51]
	v_mfma_f32_16x16x32_bf16 v[52:55], v[16:19], v[56:59], 0
	v_mfma_f32_16x16x32_bf16 v[56:59], v[24:27], v[56:59], 0
	v_mfma_f32_16x16x32_bf16 v[52:55], v[20:23], v[60:63], v[52:55]
	v_mfma_f32_16x16x32_bf16 v[56:59], v[28:31], v[60:63], v[56:59]
	s_setprio 0
	s_barrier
	v_lshl_add_u64 v[138:139], s[44:45], 0, v[130:131]
	s_mov_b32 m0, s65
	v_lshl_add_u64 v[146:147], v[138:139], 0, s[22:23]
	v_lshl_add_u64 v[210:211], s[44:45], 0, v[134:135]
	s_add_u32 s68, s44, 0x10100
	ds_read_b128 v[60:63], v145 offset:16384
	ds_read_b128 v[100:103], v145 offset:17408
	ds_read_b128 v[104:107], v145 offset:18432
	ds_read_b128 v[108:111], v145 offset:19456
	ds_read_b128 v[112:115], v145 offset:20480
	ds_read_b128 v[116:119], v145 offset:21504
	ds_read_b128 v[120:123], v145 offset:22528
	ds_read_b128 v[124:127], v145 offset:23552
	global_load_lds_dwordx4 v[146:147], off
	v_lshl_add_u64 v[146:147], v[210:211], 0, s[22:23]
	s_mov_b32 m0, s66
	s_addc_u32 s69, s45, 0
	s_add_i32 s27, s62, s55
	global_load_lds_dwordx4 v[146:147], off
	v_lshl_add_u64 v[146:147], s[68:69], 0, v[130:131]
	s_mov_b32 m0, s27
	s_add_i32 s31, s27, 0x2000
	global_load_lds_dwordx4 v[146:147], off
	v_lshl_add_u64 v[146:147], s[68:69], 0, v[134:135]
	s_mov_b32 m0, s31
	v_lshl_add_u64 v[212:213], s[42:43], 0, v[128:129]
	global_load_lds_dwordx4 v[146:147], off
	v_lshl_add_u64 v[146:147], v[212:213], 0, s[22:23]
	s_mov_b32 m0, s29
	v_lshl_add_u64 v[214:215], s[42:43], 0, v[132:133]
	global_load_lds_dwordx4 v[146:147], off
	v_lshl_add_u64 v[146:147], v[214:215], 0, s[22:23]
	s_mov_b32 m0, s56
	s_nop 0
	global_load_lds_dwordx4 v[146:147], off
	s_waitcnt vmcnt(8)
	s_waitcnt lgkmcnt(0)
	s_barrier
	s_setprio 1
	s_waitcnt lgkmcnt(0)
	v_mfma_f32_16x16x32_bf16 v[146:149], v[0:3], v[60:63], 0
	v_mfma_f32_16x16x32_bf16 v[154:157], v[0:3], v[104:107], 0
	v_mfma_f32_16x16x32_bf16 v[162:165], v[0:3], v[112:115], 0
	v_mfma_f32_16x16x32_bf16 v[0:3], v[0:3], v[120:123], 0
	v_mfma_f32_16x16x32_bf16 v[146:149], v[4:7], v[100:103], v[146:149]
	v_mfma_f32_16x16x32_bf16 v[154:157], v[4:7], v[108:111], v[154:157]
	v_mfma_f32_16x16x32_bf16 v[162:165], v[4:7], v[116:119], v[162:165]
	v_mfma_f32_16x16x32_bf16 v[0:3], v[4:7], v[124:127], v[0:3]
	v_mfma_f32_16x16x32_bf16 v[4:7], v[8:11], v[120:123], 0
	v_mfma_f32_16x16x32_bf16 v[150:153], v[8:11], v[60:63], 0
	v_mfma_f32_16x16x32_bf16 v[158:161], v[8:11], v[104:107], 0
	v_mfma_f32_16x16x32_bf16 v[166:169], v[8:11], v[112:115], 0
	v_mfma_f32_16x16x32_bf16 v[4:7], v[12:15], v[124:127], v[4:7]
	v_mfma_f32_16x16x32_bf16 v[150:153], v[12:15], v[100:103], v[150:153]
	v_mfma_f32_16x16x32_bf16 v[158:161], v[12:15], v[108:111], v[158:161]
	v_mfma_f32_16x16x32_bf16 v[166:169], v[12:15], v[116:119], v[166:169]
	v_mfma_f32_16x16x32_bf16 v[8:11], v[16:19], v[60:63], 0
	v_mfma_f32_16x16x32_bf16 v[12:15], v[24:27], v[60:63], 0
	v_mfma_f32_16x16x32_bf16 v[8:11], v[20:23], v[100:103], v[8:11]
	v_mfma_f32_16x16x32_bf16 v[12:15], v[28:31], v[100:103], v[12:15]
	v_mfma_f32_16x16x32_bf16 v[60:63], v[16:19], v[104:107], 0
	v_mfma_f32_16x16x32_bf16 v[100:103], v[24:27], v[104:107], 0
	v_mfma_f32_16x16x32_bf16 v[104:107], v[16:19], v[112:115], 0
	v_mfma_f32_16x16x32_bf16 v[16:19], v[16:19], v[120:123], 0
	v_mfma_f32_16x16x32_bf16 v[60:63], v[20:23], v[108:111], v[60:63]
	v_mfma_f32_16x16x32_bf16 v[100:103], v[28:31], v[108:111], v[100:103]
	v_mfma_f32_16x16x32_bf16 v[104:107], v[20:23], v[116:119], v[104:107]
	v_mfma_f32_16x16x32_bf16 v[108:111], v[24:27], v[112:115], 0
	v_mfma_f32_16x16x32_bf16 v[16:19], v[20:23], v[124:127], v[16:19]
	v_mfma_f32_16x16x32_bf16 v[20:23], v[24:27], v[120:123], 0
	v_mfma_f32_16x16x32_bf16 v[108:111], v[28:31], v[116:119], v[108:111]
	v_mfma_f32_16x16x32_bf16 v[20:23], v[28:31], v[124:127], v[20:23]
	s_setprio 0
	s_barrier
	s_add_i32 s67, 0, 0x18000
	s_add_i32 s70, 0, 0x1c000
	v_add_u32_e32 v222, s67, v141
	v_add_u32_e32 v230, s70, v141
	ds_read_b128 v[24:27], v222
	ds_read_b128 v[28:31], v222 offset:1024
	ds_read_b128 v[112:115], v222 offset:2048
	ds_read_b128 v[116:119], v222 offset:3072
	ds_read_b128 v[120:123], v230
	ds_read_b128 v[124:127], v230 offset:1024
	ds_read_b128 v[170:173], v230 offset:2048
	ds_read_b128 v[174:177], v230 offset:3072
	s_add_u32 s68, s42, 0x10100
	s_addc_u32 s69, s43, 0
	s_mov_b32 m0, s57
	v_lshl_add_u64 v[216:217], s[68:69], 0, v[128:129]
	ds_read_b128 v[178:181], v145 offset:32768
	ds_read_b128 v[182:185], v145 offset:33792
	ds_read_b128 v[186:189], v145 offset:34816
	ds_read_b128 v[190:193], v145 offset:35840
	ds_read_b128 v[194:197], v145 offset:36864
	ds_read_b128 v[198:201], v145 offset:37888
	ds_read_b128 v[202:205], v145 offset:38912
	ds_read_b128 v[206:209], v145 offset:39936
	global_load_lds_dwordx4 v[216:217], off
	v_lshl_add_u64 v[216:217], s[68:69], 0, v[132:133]
	s_mov_b32 m0, s58
	s_nop 0
	global_load_lds_dwordx4 v[216:217], off
	s_waitcnt vmcnt(8)
	s_waitcnt lgkmcnt(0)
	s_barrier
	s_setprio 1
	s_waitcnt lgkmcnt(0)
	v_mfma_f32_16x16x32_bf16 v[64:67], v[24:27], v[178:181], v[64:67]
	v_mfma_f32_16x16x32_bf16 v[68:71], v[112:115], v[178:181], v[68:71]
	v_mfma_f32_16x16x32_bf16 v[72:75], v[24:27], v[186:189], v[72:75]
	v_mfma_f32_16x16x32_bf16 v[76:79], v[112:115], v[186:189], v[76:79]
	v_mfma_f32_16x16x32_bf16 v[80:83], v[24:27], v[194:197], v[80:83]
	v_mfma_f32_16x16x32_bf16 v[84:87], v[112:115], v[194:197], v[84:87]
	v_mfma_f32_16x16x32_bf16 v[88:91], v[24:27], v[202:205], v[88:91]
	v_mfma_f32_16x16x32_bf16 v[92:95], v[112:115], v[202:205], v[92:95]
	v_mfma_f32_16x16x32_bf16 v[64:67], v[28:31], v[182:185], v[64:67]
	v_mfma_f32_16x16x32_bf16 v[68:71], v[116:119], v[182:185], v[68:71]
	v_mfma_f32_16x16x32_bf16 v[72:75], v[28:31], v[190:193], v[72:75]
	v_mfma_f32_16x16x32_bf16 v[76:79], v[116:119], v[190:193], v[76:79]
	v_mfma_f32_16x16x32_bf16 v[80:83], v[28:31], v[198:201], v[80:83]
	v_mfma_f32_16x16x32_bf16 v[84:87], v[116:119], v[198:201], v[84:87]
	v_mfma_f32_16x16x32_bf16 v[88:91], v[28:31], v[206:209], v[88:91]
	v_mfma_f32_16x16x32_bf16 v[92:95], v[116:119], v[206:209], v[92:95]
	v_mfma_f32_16x16x32_bf16 v[96:99], v[120:123], v[178:181], v[96:99]
	v_mfma_f32_16x16x32_bf16 v[32:35], v[170:173], v[178:181], v[32:35]
	v_mfma_f32_16x16x32_bf16 v[36:39], v[120:123], v[186:189], v[36:39]
	v_mfma_f32_16x16x32_bf16 v[40:43], v[170:173], v[186:189], v[40:43]
	v_mfma_f32_16x16x32_bf16 v[44:47], v[120:123], v[194:197], v[44:47]
	v_mfma_f32_16x16x32_bf16 v[48:51], v[170:173], v[194:197], v[48:51]
	v_mfma_f32_16x16x32_bf16 v[52:55], v[120:123], v[202:205], v[52:55]
	v_mfma_f32_16x16x32_bf16 v[56:59], v[170:173], v[202:205], v[56:59]
	v_mfma_f32_16x16x32_bf16 v[96:99], v[124:127], v[182:185], v[96:99]
	v_mfma_f32_16x16x32_bf16 v[32:35], v[174:177], v[182:185], v[32:35]
	v_mfma_f32_16x16x32_bf16 v[36:39], v[124:127], v[190:193], v[36:39]
	v_mfma_f32_16x16x32_bf16 v[40:43], v[174:177], v[190:193], v[40:43]
	v_mfma_f32_16x16x32_bf16 v[44:47], v[124:127], v[198:201], v[44:47]
	v_mfma_f32_16x16x32_bf16 v[48:51], v[174:177], v[198:201], v[48:51]
	v_mfma_f32_16x16x32_bf16 v[52:55], v[124:127], v[206:209], v[52:55]
	v_mfma_f32_16x16x32_bf16 v[56:59], v[174:177], v[206:209], v[56:59]
	s_setprio 0
	s_barrier
	s_add_i32 s67, s67, s55
	s_add_i32 s35, s67, 0x2000
	v_lshl_add_u64 v[138:139], v[138:139], 0, s[24:25]
	s_mov_b32 m0, s67
	s_add_u32 s68, s44, 0x10180
	ds_read_b128 v[178:181], v145 offset:49152
	ds_read_b128 v[182:185], v145 offset:50176
	ds_read_b128 v[186:189], v145 offset:51200
	ds_read_b128 v[190:193], v145 offset:52224
	ds_read_b128 v[194:197], v145 offset:53248
	ds_read_b128 v[198:201], v145 offset:54272
	ds_read_b128 v[202:205], v145 offset:55296
	ds_read_b128 v[206:209], v145 offset:56320
	global_load_lds_dwordx4 v[138:139], off
	v_lshl_add_u64 v[138:139], v[210:211], 0, s[24:25]
	s_mov_b32 m0, s35
	s_addc_u32 s69, s45, 0
	s_add_i32 s44, s70, s55
	global_load_lds_dwordx4 v[138:139], off
	v_lshl_add_u64 v[138:139], s[68:69], 0, v[130:131]
	s_mov_b32 m0, s44
	s_add_i32 s45, s44, 0x2000
	global_load_lds_dwordx4 v[138:139], off
	v_lshl_add_u64 v[138:139], s[68:69], 0, v[134:135]
	s_mov_b32 m0, s45
	s_nop 0
	global_load_lds_dwordx4 v[138:139], off
	v_lshl_add_u64 v[138:139], v[212:213], 0, s[24:25]
	s_mov_b32 m0, s59
	s_nop 0
	global_load_lds_dwordx4 v[138:139], off
	v_lshl_add_u64 v[138:139], v[214:215], 0, s[24:25]
	s_mov_b32 m0, s60
	s_nop 0
	global_load_lds_dwordx4 v[138:139], off
	s_waitcnt vmcnt(8)
	s_waitcnt lgkmcnt(0)
	s_barrier
	s_setprio 1
	s_waitcnt lgkmcnt(0)
	v_mfma_f32_16x16x32_bf16 v[0:3], v[24:27], v[202:205], v[0:3]
	v_mfma_f32_16x16x32_bf16 v[4:7], v[112:115], v[202:205], v[4:7]
	v_mfma_f32_16x16x32_bf16 v[146:149], v[24:27], v[178:181], v[146:149]
	v_mfma_f32_16x16x32_bf16 v[150:153], v[112:115], v[178:181], v[150:153]
	v_mfma_f32_16x16x32_bf16 v[154:157], v[24:27], v[186:189], v[154:157]
	v_mfma_f32_16x16x32_bf16 v[158:161], v[112:115], v[186:189], v[158:161]
	v_mfma_f32_16x16x32_bf16 v[162:165], v[24:27], v[194:197], v[162:165]
	v_mfma_f32_16x16x32_bf16 v[166:169], v[112:115], v[194:197], v[166:169]
	v_mfma_f32_16x16x32_bf16 v[0:3], v[28:31], v[206:209], v[0:3]
	v_mfma_f32_16x16x32_bf16 v[4:7], v[116:119], v[206:209], v[4:7]
	v_mfma_f32_16x16x32_bf16 v[146:149], v[28:31], v[182:185], v[146:149]
	v_mfma_f32_16x16x32_bf16 v[150:153], v[116:119], v[182:185], v[150:153]
	v_mfma_f32_16x16x32_bf16 v[154:157], v[28:31], v[190:193], v[154:157]
	v_mfma_f32_16x16x32_bf16 v[158:161], v[116:119], v[190:193], v[158:161]
	v_mfma_f32_16x16x32_bf16 v[162:165], v[28:31], v[198:201], v[162:165]
	v_mfma_f32_16x16x32_bf16 v[166:169], v[116:119], v[198:201], v[166:169]
	v_mfma_f32_16x16x32_bf16 v[8:11], v[120:123], v[178:181], v[8:11]
	v_mfma_f32_16x16x32_bf16 v[12:15], v[170:173], v[178:181], v[12:15]
	v_mfma_f32_16x16x32_bf16 v[24:27], v[120:123], v[186:189], v[60:63]
	v_mfma_f32_16x16x32_bf16 v[28:31], v[170:173], v[186:189], v[100:103]
	v_mfma_f32_16x16x32_bf16 v[60:63], v[120:123], v[194:197], v[104:107]
	v_mfma_f32_16x16x32_bf16 v[100:103], v[170:173], v[194:197], v[108:111]
	v_mfma_f32_16x16x32_bf16 v[16:19], v[120:123], v[202:205], v[16:19]
	v_mfma_f32_16x16x32_bf16 v[20:23], v[170:173], v[202:205], v[20:23]
	v_mfma_f32_16x16x32_bf16 v[8:11], v[124:127], v[182:185], v[8:11]
	v_mfma_f32_16x16x32_bf16 v[12:15], v[174:177], v[182:185], v[12:15]
	v_mfma_f32_16x16x32_bf16 v[24:27], v[124:127], v[190:193], v[24:27]
	v_mfma_f32_16x16x32_bf16 v[28:31], v[174:177], v[190:193], v[28:31]
	v_mfma_f32_16x16x32_bf16 v[60:63], v[124:127], v[198:201], v[60:63]
	v_mfma_f32_16x16x32_bf16 v[100:103], v[174:177], v[198:201], v[100:103]
	v_mfma_f32_16x16x32_bf16 v[16:19], v[124:127], v[206:209], v[16:19]
	v_mfma_f32_16x16x32_bf16 v[20:23], v[174:177], v[206:209], v[20:23]
	s_setprio 0
	s_barrier
	ds_read_b128 v[104:107], v143
	ds_read_b128 v[108:111], v143 offset:1024
	ds_read_b128 v[112:115], v143 offset:2048
	ds_read_b128 v[116:119], v143 offset:3072
	ds_read_b128 v[120:123], v144
	ds_read_b128 v[124:127], v144 offset:1024
	ds_read_b128 v[170:173], v144 offset:2048
	ds_read_b128 v[174:177], v144 offset:3072
	s_add_u32 s42, s42, 0x10180
	s_addc_u32 s43, s43, 0
	s_mov_b32 m0, s63
	v_lshl_add_u64 v[138:139], s[42:43], 0, v[128:129]
	ds_read_b128 v[178:181], v145
	ds_read_b128 v[182:185], v145 offset:1024
	ds_read_b128 v[186:189], v145 offset:2048
	ds_read_b128 v[190:193], v145 offset:3072
	ds_read_b128 v[194:197], v145 offset:4096
	ds_read_b128 v[198:201], v145 offset:5120
	ds_read_b128 v[202:205], v145 offset:6144
	ds_read_b128 v[206:209], v145 offset:7168
	global_load_lds_dwordx4 v[138:139], off
	v_lshl_add_u64 v[138:139], s[42:43], 0, v[132:133]
	s_mov_b32 m0, s64
	s_nop 0
	global_load_lds_dwordx4 v[138:139], off
	s_waitcnt vmcnt(8)
	s_waitcnt lgkmcnt(0)
	s_barrier
	s_setprio 1
	s_waitcnt lgkmcnt(0)
	v_mfma_f32_16x16x32_bf16 v[88:91], v[104:107], v[202:205], v[88:91]
	v_mfma_f32_16x16x32_bf16 v[64:67], v[104:107], v[178:181], v[64:67]
	v_mfma_f32_16x16x32_bf16 v[68:71], v[112:115], v[178:181], v[68:71]
	v_mfma_f32_16x16x32_bf16 v[72:75], v[104:107], v[186:189], v[72:75]
	v_mfma_f32_16x16x32_bf16 v[76:79], v[112:115], v[186:189], v[76:79]
	v_mfma_f32_16x16x32_bf16 v[80:83], v[104:107], v[194:197], v[80:83]
	v_mfma_f32_16x16x32_bf16 v[84:87], v[112:115], v[194:197], v[84:87]
	v_mfma_f32_16x16x32_bf16 v[210:213], v[108:111], v[206:209], v[88:91]
	v_mfma_f32_16x16x32_bf16 v[88:91], v[112:115], v[202:205], v[92:95]
	v_mfma_f32_16x16x32_bf16 v[64:67], v[108:111], v[182:185], v[64:67]
	v_mfma_f32_16x16x32_bf16 v[68:71], v[116:119], v[182:185], v[68:71]
	v_mfma_f32_16x16x32_bf16 v[72:75], v[108:111], v[190:193], v[72:75]
	v_mfma_f32_16x16x32_bf16 v[76:79], v[116:119], v[190:193], v[76:79]
	v_mfma_f32_16x16x32_bf16 v[80:83], v[108:111], v[198:201], v[80:83]
	v_mfma_f32_16x16x32_bf16 v[84:87], v[116:119], v[198:201], v[84:87]
	v_mfma_f32_16x16x32_bf16 v[92:95], v[116:119], v[206:209], v[88:91]
	v_mfma_f32_16x16x32_bf16 v[48:51], v[170:173], v[194:197], v[48:51]
	v_mfma_f32_16x16x32_bf16 v[88:91], v[120:123], v[178:181], v[96:99]
	v_mfma_f32_16x16x32_bf16 v[32:35], v[170:173], v[178:181], v[32:35]
	v_mfma_f32_16x16x32_bf16 v[36:39], v[120:123], v[186:189], v[36:39]
	v_mfma_f32_16x16x32_bf16 v[40:43], v[170:173], v[186:189], v[40:43]
	v_mfma_f32_16x16x32_bf16 v[44:47], v[120:123], v[194:197], v[44:47]
	v_mfma_f32_16x16x32_bf16 v[178:181], v[174:177], v[198:201], v[48:51]
	v_mfma_f32_16x16x32_bf16 v[48:51], v[120:123], v[202:205], v[52:55]
	v_mfma_f32_16x16x32_bf16 v[32:35], v[174:177], v[182:185], v[32:35]
	v_mfma_f32_16x16x32_bf16 v[36:39], v[124:127], v[190:193], v[36:39]
	v_mfma_f32_16x16x32_bf16 v[40:43], v[174:177], v[190:193], v[40:43]
	v_mfma_f32_16x16x32_bf16 v[44:47], v[124:127], v[198:201], v[44:47]
	v_mfma_f32_16x16x32_bf16 v[52:55], v[124:127], v[206:209], v[48:51]
	v_mfma_f32_16x16x32_bf16 v[48:51], v[170:173], v[202:205], v[56:59]
	v_mfma_f32_16x16x32_bf16 v[214:217], v[124:127], v[182:185], v[88:91]
	v_mfma_f32_16x16x32_bf16 v[182:185], v[174:177], v[206:209], v[48:51]
	s_setprio 0
	s_barrier
	s_mov_b32 m0, s65
	v_lshl_add_u64 v[138:139], s[46:47], 0, v[130:131]
	s_add_u32 s42, s46, 0x10000
	s_nop 0
	ds_read_b128 v[48:51], v145 offset:16384
	ds_read_b128 v[56:59], v145 offset:17408
	ds_read_b128 v[88:91], v145 offset:18432
	ds_read_b128 v[96:99], v145 offset:19456
	ds_read_b128 v[186:189], v145 offset:20480
	ds_read_b128 v[190:193], v145 offset:21504
	ds_read_b128 v[194:197], v145 offset:22528
	ds_read_b128 v[198:201], v145 offset:23552
	global_load_lds_dwordx4 v[138:139], off
	v_lshl_add_u64 v[250:251], s[46:47], 0, v[134:135]
	s_mov_b32 m0, s66
	s_addc_u32 s43, s47, 0
	global_load_lds_dwordx4 v[250:251], off
	v_lshl_add_u64 v[202:203], s[42:43], 0, v[130:131]
	s_mov_b32 m0, s27
	v_lshl_add_u64 v[252:253], s[48:49], 0, v[128:129]
	global_load_lds_dwordx4 v[202:203], off
	v_lshl_add_u64 v[202:203], s[42:43], 0, v[134:135]
	s_mov_b32 m0, s31
	v_lshl_add_u64 v[254:255], s[48:49], 0, v[132:133]
	global_load_lds_dwordx4 v[202:203], off
	s_mov_b32 m0, s29
	s_nop 0
	global_load_lds_dwordx4 v[252:253], off
	s_mov_b32 m0, s56
	s_nop 0
	global_load_lds_dwordx4 v[254:255], off
	s_waitcnt vmcnt(8)
	s_waitcnt lgkmcnt(0)
	s_barrier
	s_setprio 1
	s_waitcnt lgkmcnt(0)
	v_mfma_f32_16x16x32_bf16 v[0:3], v[104:107], v[194:197], v[0:3]
	v_mfma_f32_16x16x32_bf16 v[4:7], v[112:115], v[194:197], v[4:7]
	v_mfma_f32_16x16x32_bf16 v[146:149], v[104:107], v[48:51], v[146:149]
	v_mfma_f32_16x16x32_bf16 v[150:153], v[112:115], v[48:51], v[150:153]
	v_mfma_f32_16x16x32_bf16 v[154:157], v[104:107], v[88:91], v[154:157]
	v_mfma_f32_16x16x32_bf16 v[158:161], v[112:115], v[88:91], v[158:161]
	v_mfma_f32_16x16x32_bf16 v[162:165], v[104:107], v[186:189], v[162:165]
	v_mfma_f32_16x16x32_bf16 v[166:169], v[112:115], v[186:189], v[166:169]
	v_mfma_f32_16x16x32_bf16 v[0:3], v[108:111], v[198:201], v[0:3]
	v_mfma_f32_16x16x32_bf16 v[4:7], v[116:119], v[198:201], v[4:7]
	v_mfma_f32_16x16x32_bf16 v[146:149], v[108:111], v[56:59], v[146:149]
	v_mfma_f32_16x16x32_bf16 v[150:153], v[116:119], v[56:59], v[150:153]
	v_mfma_f32_16x16x32_bf16 v[154:157], v[108:111], v[96:99], v[154:157]
	v_mfma_f32_16x16x32_bf16 v[158:161], v[116:119], v[96:99], v[158:161]
	v_mfma_f32_16x16x32_bf16 v[162:165], v[108:111], v[190:193], v[162:165]
	v_mfma_f32_16x16x32_bf16 v[166:169], v[116:119], v[190:193], v[166:169]
	v_mfma_f32_16x16x32_bf16 v[8:11], v[120:123], v[48:51], v[8:11]
	v_mfma_f32_16x16x32_bf16 v[202:205], v[124:127], v[56:59], v[8:11]
	v_mfma_f32_16x16x32_bf16 v[8:11], v[170:173], v[48:51], v[12:15]
	v_mfma_f32_16x16x32_bf16 v[12:15], v[174:177], v[56:59], v[8:11]
	v_mfma_f32_16x16x32_bf16 v[8:11], v[120:123], v[88:91], v[24:27]
	v_mfma_f32_16x16x32_bf16 v[206:209], v[124:127], v[96:99], v[8:11]
	v_mfma_f32_16x16x32_bf16 v[8:11], v[170:173], v[88:91], v[28:31]
	v_mfma_f32_16x16x32_bf16 v[28:31], v[174:177], v[96:99], v[8:11]
	v_mfma_f32_16x16x32_bf16 v[8:11], v[120:123], v[186:189], v[60:63]
	v_mfma_f32_16x16x32_bf16 v[218:221], v[124:127], v[190:193], v[8:11]
	v_mfma_f32_16x16x32_bf16 v[8:11], v[170:173], v[186:189], v[100:103]
	v_mfma_f32_16x16x32_bf16 v[186:189], v[174:177], v[190:193], v[8:11]
	v_mfma_f32_16x16x32_bf16 v[8:11], v[120:123], v[194:197], v[16:19]
	v_mfma_f32_16x16x32_bf16 v[190:193], v[124:127], v[198:201], v[8:11]
	v_mfma_f32_16x16x32_bf16 v[8:11], v[170:173], v[194:197], v[20:23]
	v_mfma_f32_16x16x32_bf16 v[170:173], v[174:177], v[198:201], v[8:11]
	s_setprio 0
	s_barrier
	s_nop 4
	ds_read_b128 v[8:11], v222
	ds_read_b128 v[20:23], v222 offset:1024
	ds_read_b128 v[174:177], v222 offset:2048
	ds_read_b128 v[194:197], v222 offset:3072
	ds_read_b128 v[198:201], v230
	ds_read_b128 v[222:225], v230 offset:1024
	ds_read_b128 v[226:229], v230 offset:2048
	ds_read_b128 v[230:233], v230 offset:3072
	s_add_u32 s42, s48, 0x10000
	s_addc_u32 s43, s49, 0
	s_mov_b32 m0, s57
	v_lshl_add_u64 v[48:49], s[42:43], 0, v[128:129]
	ds_read_b128 v[16:19], v145 offset:32768
	ds_read_b128 v[24:27], v145 offset:33792
	ds_read_b128 v[60:63], v145 offset:34816
	ds_read_b128 v[100:103], v145 offset:35840
	ds_read_b128 v[234:237], v145 offset:36864
	ds_read_b128 v[238:241], v145 offset:37888
	ds_read_b128 v[242:245], v145 offset:38912
	ds_read_b128 v[246:249], v145 offset:39936
	global_load_lds_dwordx4 v[48:49], off
	v_lshl_add_u64 v[48:49], s[42:43], 0, v[132:133]
	s_mov_b32 m0, s58
	s_nop 0
	global_load_lds_dwordx4 v[48:49], off
	s_waitcnt vmcnt(8)
	s_waitcnt lgkmcnt(0)
	s_barrier
	s_setprio 1
	s_waitcnt lgkmcnt(0)
	v_mfma_f32_16x16x32_bf16 v[48:51], v[8:11], v[16:19], v[64:67]
	v_mfma_f32_16x16x32_bf16 v[120:123], v[20:23], v[24:27], v[48:51]
	v_mfma_f32_16x16x32_bf16 v[48:51], v[174:177], v[16:19], v[68:71]
	v_mfma_f32_16x16x32_bf16 v[112:115], v[194:197], v[24:27], v[48:51]
	v_mfma_f32_16x16x32_bf16 v[48:51], v[8:11], v[60:63], v[72:75]
	v_mfma_f32_16x16x32_bf16 v[104:107], v[20:23], v[100:103], v[48:51]
	v_mfma_f32_16x16x32_bf16 v[48:51], v[174:177], v[60:63], v[76:79]
	v_mfma_f32_16x16x32_bf16 v[96:99], v[194:197], v[100:103], v[48:51]
	v_mfma_f32_16x16x32_bf16 v[48:51], v[8:11], v[234:237], v[80:83]
	v_mfma_f32_16x16x32_bf16 v[88:91], v[20:23], v[238:241], v[48:51]
	v_mfma_f32_16x16x32_bf16 v[48:51], v[174:177], v[234:237], v[84:87]
	v_mfma_f32_16x16x32_bf16 v[80:83], v[194:197], v[238:241], v[48:51]
	v_mfma_f32_16x16x32_bf16 v[48:51], v[8:11], v[242:245], v[210:213]
	v_mfma_f32_16x16x32_bf16 v[56:59], v[20:23], v[246:249], v[48:51]
	v_mfma_f32_16x16x32_bf16 v[48:51], v[174:177], v[242:245], v[92:95]
	v_mfma_f32_16x16x32_bf16 v[48:51], v[194:197], v[246:249], v[48:51]
	v_mfma_f32_16x16x32_bf16 v[64:67], v[198:201], v[16:19], v[214:217]
	v_mfma_f32_16x16x32_bf16 v[16:19], v[226:229], v[16:19], v[32:35]
	v_mfma_f32_16x16x32_bf16 v[116:119], v[230:233], v[24:27], v[16:19]
	v_mfma_f32_16x16x32_bf16 v[16:19], v[198:201], v[60:63], v[36:39]
	v_mfma_f32_16x16x32_bf16 v[108:111], v[222:225], v[100:103], v[16:19]
	v_mfma_f32_16x16x32_bf16 v[16:19], v[226:229], v[60:63], v[40:43]
	v_mfma_f32_16x16x32_bf16 v[100:103], v[230:233], v[100:103], v[16:19]
	v_mfma_f32_16x16x32_bf16 v[16:19], v[198:201], v[234:237], v[44:47]
	v_mfma_f32_16x16x32_bf16 v[92:95], v[222:225], v[238:241], v[16:19]
	v_mfma_f32_16x16x32_bf16 v[16:19], v[226:229], v[234:237], v[178:181]
	v_mfma_f32_16x16x32_bf16 v[84:87], v[230:233], v[238:241], v[16:19]
	v_mfma_f32_16x16x32_bf16 v[16:19], v[198:201], v[242:245], v[52:55]
	v_mfma_f32_16x16x32_bf16 v[60:63], v[222:225], v[246:249], v[16:19]
	v_mfma_f32_16x16x32_bf16 v[16:19], v[226:229], v[242:245], v[182:185]
	v_mfma_f32_16x16x32_bf16 v[124:127], v[222:225], v[24:27], v[64:67]
	v_mfma_f32_16x16x32_bf16 v[52:55], v[230:233], v[246:249], v[16:19]
	s_setprio 0
	s_barrier
	s_mov_b32 m0, s67
	s_nop 2
	v_lshl_add_u64 v[16:17], v[138:139], 0, s[16:17]
	s_add_u32 s42, s46, 0x10080
	ds_read_b128 v[36:39], v145 offset:49152
	ds_read_b128 v[44:47], v145 offset:50176
	ds_read_b128 v[178:181], v145 offset:51200
	ds_read_b128 v[182:185], v145 offset:52224
	ds_read_b128 v[210:213], v145 offset:53248
	ds_read_b128 v[214:217], v145 offset:54272
	ds_read_b128 v[234:237], v145 offset:55296
	ds_read_b128 v[238:241], v145 offset:56320
	global_load_lds_dwordx4 v[16:17], off
	v_lshl_add_u64 v[16:17], v[250:251], 0, s[16:17]
	s_mov_b32 m0, s35
	s_addc_u32 s43, s47, 0
	global_load_lds_dwordx4 v[16:17], off
	v_lshl_add_u64 v[16:17], s[42:43], 0, v[130:131]
	s_mov_b32 m0, s44
	s_nop 0
	global_load_lds_dwordx4 v[16:17], off
	v_lshl_add_u64 v[16:17], s[42:43], 0, v[134:135]
	s_mov_b32 m0, s45
	s_nop 0
	global_load_lds_dwordx4 v[16:17], off
	v_lshl_add_u64 v[16:17], v[252:253], 0, s[16:17]
	s_mov_b32 m0, s59
	s_nop 0
	global_load_lds_dwordx4 v[16:17], off
	v_lshl_add_u64 v[16:17], v[254:255], 0, s[16:17]
	s_mov_b32 m0, s60
	s_nop 0
	global_load_lds_dwordx4 v[16:17], off
	s_waitcnt vmcnt(8)
	s_waitcnt lgkmcnt(0)
	s_barrier
	s_setprio 1
	s_waitcnt lgkmcnt(0)
	v_mfma_f32_16x16x32_bf16 v[16:19], v[8:11], v[36:39], v[146:149]
	v_mfma_f32_16x16x32_bf16 v[72:75], v[20:23], v[44:47], v[16:19]
	v_mfma_f32_16x16x32_bf16 v[16:19], v[174:177], v[36:39], v[150:153]
	v_mfma_f32_16x16x32_bf16 v[64:67], v[194:197], v[44:47], v[16:19]
	v_mfma_f32_16x16x32_bf16 v[16:19], v[8:11], v[178:181], v[154:157]
	v_mfma_f32_16x16x32_bf16 v[40:43], v[20:23], v[182:185], v[16:19]
	v_mfma_f32_16x16x32_bf16 v[16:19], v[174:177], v[178:181], v[158:161]
	v_mfma_f32_16x16x32_bf16 v[32:35], v[194:197], v[182:185], v[16:19]
	v_mfma_f32_16x16x32_bf16 v[16:19], v[8:11], v[210:213], v[162:165]
	v_mfma_f32_16x16x32_bf16 v[0:3], v[8:11], v[234:237], v[0:3]
	v_mfma_f32_16x16x32_bf16 v[24:27], v[20:23], v[214:217], v[16:19]
	v_mfma_f32_16x16x32_bf16 v[16:19], v[174:177], v[210:213], v[166:169]
	v_mfma_f32_16x16x32_bf16 v[8:11], v[20:23], v[238:241], v[0:3]
	v_mfma_f32_16x16x32_bf16 v[0:3], v[174:177], v[234:237], v[4:7]
	v_mfma_f32_16x16x32_bf16 v[16:19], v[194:197], v[214:217], v[16:19]
	v_mfma_f32_16x16x32_bf16 v[0:3], v[194:197], v[238:241], v[0:3]
	v_mfma_f32_16x16x32_bf16 v[4:7], v[198:201], v[36:39], v[202:205]
	v_mfma_f32_16x16x32_bf16 v[76:79], v[222:225], v[44:47], v[4:7]
	v_mfma_f32_16x16x32_bf16 v[4:7], v[226:229], v[36:39], v[12:15]
	v_mfma_f32_16x16x32_bf16 v[68:71], v[230:233], v[44:47], v[4:7]
	v_mfma_f32_16x16x32_bf16 v[4:7], v[198:201], v[178:181], v[206:209]
	v_mfma_f32_16x16x32_bf16 v[44:47], v[222:225], v[182:185], v[4:7]
	v_mfma_f32_16x16x32_bf16 v[4:7], v[226:229], v[178:181], v[28:31]
	v_mfma_f32_16x16x32_bf16 v[36:39], v[230:233], v[182:185], v[4:7]
	v_mfma_f32_16x16x32_bf16 v[4:7], v[198:201], v[210:213], v[218:221]
	v_mfma_f32_16x16x32_bf16 v[28:31], v[222:225], v[214:217], v[4:7]
	v_mfma_f32_16x16x32_bf16 v[4:7], v[226:229], v[210:213], v[186:189]
	v_mfma_f32_16x16x32_bf16 v[20:23], v[230:233], v[214:217], v[4:7]
	v_mfma_f32_16x16x32_bf16 v[4:7], v[198:201], v[234:237], v[190:193]
	v_mfma_f32_16x16x32_bf16 v[12:15], v[222:225], v[238:241], v[4:7]
	v_mfma_f32_16x16x32_bf16 v[4:7], v[226:229], v[234:237], v[170:173]
	v_mfma_f32_16x16x32_bf16 v[4:7], v[230:233], v[238:241], v[4:7]
	s_setprio 0
	s_barrier
	s_andn2_b64 vcc, exec, s[18:19]
	s_cbranch_vccnz .LBB0_1080
	s_barrier

.LBB0_1102:
	ds_read_b128 v[138:141], v145
	ds_read_b128 v[148:151], v145 offset:1024
	ds_read_b128 v[152:155], v145 offset:2048
	ds_read_b128 v[156:159], v145 offset:3072
	ds_read_b128 v[160:163], v146
	ds_read_b128 v[164:167], v146 offset:1024
	ds_read_b128 v[168:171], v146 offset:2048
	ds_read_b128 v[172:175], v146 offset:3072
	s_add_u32 s46, s44, 0xfffc0080
	s_addc_u32 s47, s45, -1
	s_cmp_eq_u32 s70, 12
	s_cselect_b32 s49, s31, s47
	s_cselect_b32 s48, s66, s46
	s_cselect_b32 s47, s29, s69
	s_cselect_b32 s46, s67, s68
	v_lshl_add_u64 v[208:209], s[44:45], 0, v[134:135]
	s_add_i32 m0, s41, 0xc000
	ds_read_b128 v[176:179], v147
	ds_read_b128 v[180:183], v147 offset:1024
	ds_read_b128 v[184:187], v147 offset:2048
	ds_read_b128 v[188:191], v147 offset:3072
	ds_read_b128 v[192:195], v147 offset:4096
	ds_read_b128 v[196:199], v147 offset:5120
	ds_read_b128 v[200:203], v147 offset:6144
	ds_read_b128 v[204:207], v147 offset:7168
	global_load_lds_dwordx4 v[208:209], off
	v_lshl_add_u64 v[208:209], s[44:45], 0, v[132:133]
	s_add_i32 m0, s41, 0xe000
	s_nop 0
	global_load_lds_dwordx4 v[208:209], off
	s_waitcnt vmcnt(8)
	s_waitcnt lgkmcnt(0)
	s_barrier
	s_setprio 1
	s_waitcnt lgkmcnt(0)
	v_mfma_f32_16x16x32_bf16 v[124:127], v[138:141], v[176:179], v[124:127]
	v_mfma_f32_16x16x32_bf16 v[120:123], v[152:155], v[176:179], v[120:123]
	v_mfma_f32_16x16x32_bf16 v[108:111], v[138:141], v[184:187], v[108:111]
	v_mfma_f32_16x16x32_bf16 v[104:107], v[152:155], v[184:187], v[104:107]
	v_mfma_f32_16x16x32_bf16 v[92:95], v[138:141], v[192:195], v[92:95]
	v_mfma_f32_16x16x32_bf16 v[88:91], v[152:155], v[192:195], v[88:91]
	v_mfma_f32_16x16x32_bf16 v[76:79], v[138:141], v[200:203], v[76:79]
	v_mfma_f32_16x16x32_bf16 v[72:75], v[152:155], v[200:203], v[72:75]
	v_mfma_f32_16x16x32_bf16 v[124:127], v[148:151], v[180:183], v[124:127]
	v_mfma_f32_16x16x32_bf16 v[120:123], v[156:159], v[180:183], v[120:123]
	v_mfma_f32_16x16x32_bf16 v[108:111], v[148:151], v[188:191], v[108:111]
	v_mfma_f32_16x16x32_bf16 v[104:107], v[156:159], v[188:191], v[104:107]
	v_mfma_f32_16x16x32_bf16 v[92:95], v[148:151], v[196:199], v[92:95]
	v_mfma_f32_16x16x32_bf16 v[88:91], v[156:159], v[196:199], v[88:91]
	v_mfma_f32_16x16x32_bf16 v[76:79], v[148:151], v[204:207], v[76:79]
	v_mfma_f32_16x16x32_bf16 v[72:75], v[156:159], v[204:207], v[72:75]
	v_mfma_f32_16x16x32_bf16 v[116:119], v[160:163], v[176:179], v[116:119]
	v_mfma_f32_16x16x32_bf16 v[112:115], v[168:171], v[176:179], v[112:115]
	v_mfma_f32_16x16x32_bf16 v[100:103], v[160:163], v[184:187], v[100:103]
	v_mfma_f32_16x16x32_bf16 v[96:99], v[168:171], v[184:187], v[96:99]
	v_mfma_f32_16x16x32_bf16 v[84:87], v[160:163], v[192:195], v[84:87]
	v_mfma_f32_16x16x32_bf16 v[80:83], v[168:171], v[192:195], v[80:83]
	v_mfma_f32_16x16x32_bf16 v[68:71], v[160:163], v[200:203], v[68:71]
	v_mfma_f32_16x16x32_bf16 v[64:67], v[168:171], v[200:203], v[64:67]
	v_mfma_f32_16x16x32_bf16 v[116:119], v[164:167], v[180:183], v[116:119]
	v_mfma_f32_16x16x32_bf16 v[112:115], v[172:175], v[180:183], v[112:115]
	v_mfma_f32_16x16x32_bf16 v[100:103], v[164:167], v[188:191], v[100:103]
	v_mfma_f32_16x16x32_bf16 v[96:99], v[172:175], v[188:191], v[96:99]
	v_mfma_f32_16x16x32_bf16 v[84:87], v[164:167], v[196:199], v[84:87]
	v_mfma_f32_16x16x32_bf16 v[80:83], v[172:175], v[196:199], v[80:83]
	v_mfma_f32_16x16x32_bf16 v[68:71], v[164:167], v[204:207], v[68:71]
	v_mfma_f32_16x16x32_bf16 v[64:67], v[172:175], v[204:207], v[64:67]
	s_setprio 0
	s_barrier
	s_add_i32 s71, s64, s56
	v_lshl_add_u64 v[208:209], s[46:47], 0, v[128:129]
	s_mov_b32 m0, s71
	ds_read_b128 v[176:179], v147 offset:16384
	ds_read_b128 v[180:183], v147 offset:17408
	ds_read_b128 v[184:187], v147 offset:18432
	ds_read_b128 v[188:191], v147 offset:19456
	ds_read_b128 v[192:195], v147 offset:20480
	ds_read_b128 v[196:199], v147 offset:21504
	ds_read_b128 v[200:203], v147 offset:22528
	ds_read_b128 v[204:207], v147 offset:23552
	global_load_lds_dwordx4 v[208:209], off
	s_add_i32 m0, s71, 0x2000
	s_add_u32 s72, s46, 0x40000
	v_lshl_add_u64 v[210:211], s[46:47], 0, v[130:131]
	s_addc_u32 s73, s47, 0
	s_add_i32 s71, s65, s56
	global_load_lds_dwordx4 v[210:211], off
	v_lshl_add_u64 v[212:213], s[72:73], 0, v[128:129]
	s_mov_b32 m0, s71
	v_lshl_add_u64 v[214:215], s[48:49], 0, v[130:131]
	global_load_lds_dwordx4 v[212:213], off
	v_lshl_add_u64 v[212:213], s[72:73], 0, v[130:131]
	s_add_i32 m0, s71, 0x2000
	s_nop 0
	global_load_lds_dwordx4 v[212:213], off
	v_lshl_add_u64 v[212:213], s[48:49], 0, v[128:129]
	s_mov_b32 m0, s41
	s_nop 0
	global_load_lds_dwordx4 v[212:213], off
	s_mov_b32 m0, s43
	s_nop 0
	global_load_lds_dwordx4 v[214:215], off
	s_waitcnt vmcnt(8)
	s_waitcnt lgkmcnt(0)
	s_barrier
	s_setprio 1
	s_waitcnt lgkmcnt(0)
	v_mfma_f32_16x16x32_bf16 v[60:63], v[138:141], v[176:179], v[60:63]
	v_mfma_f32_16x16x32_bf16 v[56:59], v[152:155], v[176:179], v[56:59]
	v_mfma_f32_16x16x32_bf16 v[44:47], v[138:141], v[184:187], v[44:47]
	v_mfma_f32_16x16x32_bf16 v[40:43], v[152:155], v[184:187], v[40:43]
	v_mfma_f32_16x16x32_bf16 v[28:31], v[138:141], v[192:195], v[28:31]
	v_mfma_f32_16x16x32_bf16 v[24:27], v[152:155], v[192:195], v[24:27]
	v_mfma_f32_16x16x32_bf16 v[12:15], v[138:141], v[200:203], v[12:15]
	v_mfma_f32_16x16x32_bf16 v[8:11], v[152:155], v[200:203], v[8:11]
	v_mfma_f32_16x16x32_bf16 v[60:63], v[148:151], v[180:183], v[60:63]
	v_mfma_f32_16x16x32_bf16 v[56:59], v[156:159], v[180:183], v[56:59]
	v_mfma_f32_16x16x32_bf16 v[44:47], v[148:151], v[188:191], v[44:47]
	v_mfma_f32_16x16x32_bf16 v[40:43], v[156:159], v[188:191], v[40:43]
	v_mfma_f32_16x16x32_bf16 v[28:31], v[148:151], v[196:199], v[28:31]
	v_mfma_f32_16x16x32_bf16 v[24:27], v[156:159], v[196:199], v[24:27]
	v_mfma_f32_16x16x32_bf16 v[12:15], v[148:151], v[204:207], v[12:15]
	v_mfma_f32_16x16x32_bf16 v[8:11], v[156:159], v[204:207], v[8:11]
	v_mfma_f32_16x16x32_bf16 v[52:55], v[160:163], v[176:179], v[52:55]
	v_mfma_f32_16x16x32_bf16 v[48:51], v[168:171], v[176:179], v[48:51]
	v_mfma_f32_16x16x32_bf16 v[36:39], v[160:163], v[184:187], v[36:39]
	v_mfma_f32_16x16x32_bf16 v[32:35], v[168:171], v[184:187], v[32:35]
	v_mfma_f32_16x16x32_bf16 v[20:23], v[160:163], v[192:195], v[20:23]
	v_mfma_f32_16x16x32_bf16 v[16:19], v[168:171], v[192:195], v[16:19]
	v_mfma_f32_16x16x32_bf16 v[4:7], v[160:163], v[200:203], v[4:7]
	v_mfma_f32_16x16x32_bf16 v[0:3], v[168:171], v[200:203], v[0:3]
	v_mfma_f32_16x16x32_bf16 v[52:55], v[164:167], v[180:183], v[52:55]
	v_mfma_f32_16x16x32_bf16 v[48:51], v[172:175], v[180:183], v[48:51]
	v_mfma_f32_16x16x32_bf16 v[36:39], v[164:167], v[188:191], v[36:39]
	v_mfma_f32_16x16x32_bf16 v[32:35], v[172:175], v[188:191], v[32:35]
	v_mfma_f32_16x16x32_bf16 v[20:23], v[164:167], v[196:199], v[20:23]
	v_mfma_f32_16x16x32_bf16 v[16:19], v[172:175], v[196:199], v[16:19]
	v_mfma_f32_16x16x32_bf16 v[4:7], v[164:167], v[204:207], v[4:7]
	v_mfma_f32_16x16x32_bf16 v[0:3], v[172:175], v[204:207], v[0:3]
	s_setprio 0
	s_barrier
	s_add_i32 s71, 0, 0x18000
	s_add_i32 s72, 0, 0x1c000
	v_add_u32_e32 v156, s71, v143
	v_add_u32_e32 v172, s72, v143
	ds_read_b128 v[138:141], v156
	ds_read_b128 v[148:151], v156 offset:1024
	ds_read_b128 v[152:155], v156 offset:2048
	ds_read_b128 v[156:159], v156 offset:3072
	ds_read_b128 v[160:163], v172
	ds_read_b128 v[164:167], v172 offset:1024
	ds_read_b128 v[168:171], v172 offset:2048
	ds_read_b128 v[172:175], v172 offset:3072
	s_add_u32 s48, s48, 0x40000
	s_addc_u32 s49, s49, 0
	s_mov_b32 m0, s57
	v_lshl_add_u64 v[216:217], s[48:49], 0, v[128:129]
	ds_read_b128 v[176:179], v147 offset:32768
	ds_read_b128 v[180:183], v147 offset:33792
	ds_read_b128 v[184:187], v147 offset:34816
	ds_read_b128 v[188:191], v147 offset:35840
	ds_read_b128 v[192:195], v147 offset:36864
	ds_read_b128 v[196:199], v147 offset:37888
	ds_read_b128 v[200:203], v147 offset:38912
	ds_read_b128 v[204:207], v147 offset:39936
	global_load_lds_dwordx4 v[216:217], off
	v_lshl_add_u64 v[216:217], s[48:49], 0, v[130:131]
	s_mov_b32 m0, s58
	s_nop 0
	global_load_lds_dwordx4 v[216:217], off
	s_waitcnt vmcnt(8)
	s_waitcnt lgkmcnt(0)
	s_barrier
	s_setprio 1
	s_waitcnt lgkmcnt(0)
	v_mfma_f32_16x16x32_bf16 v[124:127], v[138:141], v[176:179], v[124:127]
	v_mfma_f32_16x16x32_bf16 v[120:123], v[152:155], v[176:179], v[120:123]
	v_mfma_f32_16x16x32_bf16 v[108:111], v[138:141], v[184:187], v[108:111]
	v_mfma_f32_16x16x32_bf16 v[104:107], v[152:155], v[184:187], v[104:107]
	v_mfma_f32_16x16x32_bf16 v[92:95], v[138:141], v[192:195], v[92:95]
	v_mfma_f32_16x16x32_bf16 v[88:91], v[152:155], v[192:195], v[88:91]
	v_mfma_f32_16x16x32_bf16 v[76:79], v[138:141], v[200:203], v[76:79]
	v_mfma_f32_16x16x32_bf16 v[72:75], v[152:155], v[200:203], v[72:75]
	v_mfma_f32_16x16x32_bf16 v[124:127], v[148:151], v[180:183], v[124:127]
	v_mfma_f32_16x16x32_bf16 v[120:123], v[156:159], v[180:183], v[120:123]
	v_mfma_f32_16x16x32_bf16 v[108:111], v[148:151], v[188:191], v[108:111]
	v_mfma_f32_16x16x32_bf16 v[104:107], v[156:159], v[188:191], v[104:107]
	v_mfma_f32_16x16x32_bf16 v[92:95], v[148:151], v[196:199], v[92:95]
	v_mfma_f32_16x16x32_bf16 v[88:91], v[156:159], v[196:199], v[88:91]
	v_mfma_f32_16x16x32_bf16 v[76:79], v[148:151], v[204:207], v[76:79]
	v_mfma_f32_16x16x32_bf16 v[72:75], v[156:159], v[204:207], v[72:75]
	v_mfma_f32_16x16x32_bf16 v[116:119], v[160:163], v[176:179], v[116:119]
	v_mfma_f32_16x16x32_bf16 v[112:115], v[168:171], v[176:179], v[112:115]
	v_mfma_f32_16x16x32_bf16 v[100:103], v[160:163], v[184:187], v[100:103]
	v_mfma_f32_16x16x32_bf16 v[96:99], v[168:171], v[184:187], v[96:99]
	v_mfma_f32_16x16x32_bf16 v[84:87], v[160:163], v[192:195], v[84:87]
	v_mfma_f32_16x16x32_bf16 v[80:83], v[168:171], v[192:195], v[80:83]
	v_mfma_f32_16x16x32_bf16 v[68:71], v[160:163], v[200:203], v[68:71]
	v_mfma_f32_16x16x32_bf16 v[64:67], v[168:171], v[200:203], v[64:67]
	v_mfma_f32_16x16x32_bf16 v[116:119], v[164:167], v[180:183], v[116:119]
	v_mfma_f32_16x16x32_bf16 v[112:115], v[172:175], v[180:183], v[112:115]
	v_mfma_f32_16x16x32_bf16 v[100:103], v[164:167], v[188:191], v[100:103]
	v_mfma_f32_16x16x32_bf16 v[96:99], v[172:175], v[188:191], v[96:99]
	v_mfma_f32_16x16x32_bf16 v[84:87], v[164:167], v[196:199], v[84:87]
	v_mfma_f32_16x16x32_bf16 v[80:83], v[172:175], v[196:199], v[80:83]
	v_mfma_f32_16x16x32_bf16 v[68:71], v[164:167], v[204:207], v[68:71]
	v_mfma_f32_16x16x32_bf16 v[64:67], v[172:175], v[204:207], v[64:67]
	s_setprio 0
	s_barrier
	s_add_i32 s48, s71, s56
	v_lshl_add_u64 v[208:209], v[208:209], 0, s[24:25]
	s_mov_b32 m0, s48
	ds_read_b128 v[176:179], v147 offset:49152
	ds_read_b128 v[180:183], v147 offset:50176
	ds_read_b128 v[184:187], v147 offset:51200
	ds_read_b128 v[188:191], v147 offset:52224
	ds_read_b128 v[192:195], v147 offset:53248
	ds_read_b128 v[196:199], v147 offset:54272
	ds_read_b128 v[200:203], v147 offset:55296
	ds_read_b128 v[204:207], v147 offset:56320
	global_load_lds_dwordx4 v[208:209], off
	s_add_i32 m0, s48, 0x2000
	s_add_u32 s46, s46, 0x40080
	v_lshl_add_u64 v[208:209], v[210:211], 0, s[24:25]
	s_addc_u32 s47, s47, 0
	s_add_i32 s48, s72, s56
	global_load_lds_dwordx4 v[208:209], off
	v_lshl_add_u64 v[208:209], s[46:47], 0, v[128:129]
	s_mov_b32 m0, s48
	s_nop 0
	global_load_lds_dwordx4 v[208:209], off
	v_lshl_add_u64 v[208:209], s[46:47], 0, v[130:131]
	s_add_i32 m0, s48, 0x2000
	s_nop 0
	global_load_lds_dwordx4 v[208:209], off
	v_lshl_add_u64 v[208:209], v[212:213], 0, s[24:25]
	s_mov_b32 m0, s60
	s_nop 0
	global_load_lds_dwordx4 v[208:209], off
	v_lshl_add_u64 v[208:209], v[214:215], 0, s[24:25]
	s_mov_b32 m0, s61
	s_nop 0
	global_load_lds_dwordx4 v[208:209], off
	s_waitcnt vmcnt(8)
	s_waitcnt lgkmcnt(0)
	s_barrier
	s_setprio 1
	s_waitcnt lgkmcnt(0)
	v_mfma_f32_16x16x32_bf16 v[60:63], v[138:141], v[176:179], v[60:63]
	v_mfma_f32_16x16x32_bf16 v[56:59], v[152:155], v[176:179], v[56:59]
	v_mfma_f32_16x16x32_bf16 v[44:47], v[138:141], v[184:187], v[44:47]
	v_mfma_f32_16x16x32_bf16 v[40:43], v[152:155], v[184:187], v[40:43]
	v_mfma_f32_16x16x32_bf16 v[28:31], v[138:141], v[192:195], v[28:31]
	v_mfma_f32_16x16x32_bf16 v[24:27], v[152:155], v[192:195], v[24:27]
	v_mfma_f32_16x16x32_bf16 v[12:15], v[138:141], v[200:203], v[12:15]
	v_mfma_f32_16x16x32_bf16 v[8:11], v[152:155], v[200:203], v[8:11]
	v_mfma_f32_16x16x32_bf16 v[60:63], v[148:151], v[180:183], v[60:63]
	v_mfma_f32_16x16x32_bf16 v[56:59], v[156:159], v[180:183], v[56:59]
	v_mfma_f32_16x16x32_bf16 v[44:47], v[148:151], v[188:191], v[44:47]
	v_mfma_f32_16x16x32_bf16 v[40:43], v[156:159], v[188:191], v[40:43]
	v_mfma_f32_16x16x32_bf16 v[28:31], v[148:151], v[196:199], v[28:31]
	v_mfma_f32_16x16x32_bf16 v[24:27], v[156:159], v[196:199], v[24:27]
	v_mfma_f32_16x16x32_bf16 v[12:15], v[148:151], v[204:207], v[12:15]
	v_mfma_f32_16x16x32_bf16 v[8:11], v[156:159], v[204:207], v[8:11]
	v_mfma_f32_16x16x32_bf16 v[52:55], v[160:163], v[176:179], v[52:55]
	v_mfma_f32_16x16x32_bf16 v[48:51], v[168:171], v[176:179], v[48:51]
	v_mfma_f32_16x16x32_bf16 v[36:39], v[160:163], v[184:187], v[36:39]
	v_mfma_f32_16x16x32_bf16 v[32:35], v[168:171], v[184:187], v[32:35]
	v_mfma_f32_16x16x32_bf16 v[20:23], v[160:163], v[192:195], v[20:23]
	v_mfma_f32_16x16x32_bf16 v[16:19], v[168:171], v[192:195], v[16:19]
	v_mfma_f32_16x16x32_bf16 v[4:7], v[160:163], v[200:203], v[4:7]
	v_mfma_f32_16x16x32_bf16 v[0:3], v[168:171], v[200:203], v[0:3]
	v_mfma_f32_16x16x32_bf16 v[52:55], v[164:167], v[180:183], v[52:55]
	v_mfma_f32_16x16x32_bf16 v[48:51], v[172:175], v[180:183], v[48:51]
	v_mfma_f32_16x16x32_bf16 v[36:39], v[164:167], v[188:191], v[36:39]
	v_mfma_f32_16x16x32_bf16 v[32:35], v[172:175], v[188:191], v[32:35]
	v_mfma_f32_16x16x32_bf16 v[20:23], v[164:167], v[196:199], v[20:23]
	v_mfma_f32_16x16x32_bf16 v[16:19], v[172:175], v[196:199], v[16:19]
	v_mfma_f32_16x16x32_bf16 v[4:7], v[164:167], v[204:207], v[4:7]
	v_mfma_f32_16x16x32_bf16 v[0:3], v[172:175], v[204:207], v[0:3]
	s_setprio 0
	s_barrier
	s_add_i32 s70, s70, 2
	s_add_u32 s68, s68, 0x100
	s_addc_u32 s69, s69, 0
	s_add_u32 s44, s44, 0x100
	s_addc_u32 s45, s45, 0
	s_cmp_gt_u32 s70, 13
	s_cbranch_scc0 .LBB0_1102
	s_and_b64 vcc, exec, s[26:27]
	s_cbranch_vccz .LBB0_1105
	s_barrier

.LBB0_1127:
	v_add_u32_e32 v147, s64, v144
	ds_read_b128 v[148:151], v147
	ds_read_b128 v[152:155], v147 offset:1024
	ds_read_b128 v[156:159], v147 offset:2048
	ds_read_b128 v[160:163], v147 offset:3072
	v_add_u32_e32 v147, s65, v144
	s_add_u32 s44, s24, s42
	ds_read_b128 v[164:167], v147
	ds_read_b128 v[168:171], v147 offset:1024
	ds_read_b128 v[172:175], v147 offset:2048
	ds_read_b128 v[176:179], v147 offset:3072
	s_addc_u32 s45, s25, s43
	s_add_u32 s44, s44, 0x100
	s_addc_u32 s45, s45, 0
	s_add_u32 s70, s37, s42
	s_addc_u32 s71, s66, s43
	s_cmpk_eq_i32 s42, 0x700
	s_cselect_b32 s47, s27, s45
	s_cselect_b32 s46, s67, s44
	s_cselect_b32 s45, s29, s71
	s_cselect_b32 s44, s68, s70
	v_lshl_add_u64 v[212:213], v[140:141], 0, s[42:43]
	s_add_i32 m0, s21, 0xc000
	ds_read_b128 v[180:183], v145
	ds_read_b128 v[184:187], v145 offset:1024
	ds_read_b128 v[188:191], v145 offset:2048
	ds_read_b128 v[192:195], v145 offset:3072
	ds_read_b128 v[196:199], v145 offset:4096
	ds_read_b128 v[200:203], v145 offset:5120
	ds_read_b128 v[204:207], v145 offset:6144
	ds_read_b128 v[208:211], v145 offset:7168
	global_load_lds_dwordx4 v[212:213], off
	v_lshl_add_u64 v[212:213], v[138:139], 0, s[42:43]
	s_add_i32 m0, s21, 0xe000
	s_nop 0
	global_load_lds_dwordx4 v[212:213], off
	s_waitcnt vmcnt(8)
	s_waitcnt lgkmcnt(0)
	s_barrier
	s_setprio 1
	s_waitcnt lgkmcnt(0)
	v_mfma_f32_16x16x32_bf16 v[68:71], v[148:151], v[180:183], v[68:71]
	v_mfma_f32_16x16x32_bf16 v[64:67], v[156:159], v[180:183], v[64:67]
	v_mfma_f32_16x16x32_bf16 v[88:91], v[148:151], v[188:191], v[88:91]
	v_mfma_f32_16x16x32_bf16 v[96:99], v[156:159], v[188:191], v[96:99]
	v_mfma_f32_16x16x32_bf16 v[120:123], v[148:151], v[196:199], v[120:123]
	v_mfma_f32_16x16x32_bf16 v[124:127], v[156:159], v[196:199], v[124:127]
	v_mfma_f32_16x16x32_bf16 v[104:107], v[148:151], v[204:207], v[104:107]
	v_mfma_f32_16x16x32_bf16 v[92:95], v[156:159], v[204:207], v[92:95]
	v_mfma_f32_16x16x32_bf16 v[68:71], v[152:155], v[184:187], v[68:71]
	v_mfma_f32_16x16x32_bf16 v[64:67], v[160:163], v[184:187], v[64:67]
	v_mfma_f32_16x16x32_bf16 v[88:91], v[152:155], v[192:195], v[88:91]
	v_mfma_f32_16x16x32_bf16 v[96:99], v[160:163], v[192:195], v[96:99]
	v_mfma_f32_16x16x32_bf16 v[120:123], v[152:155], v[200:203], v[120:123]
	v_mfma_f32_16x16x32_bf16 v[124:127], v[160:163], v[200:203], v[124:127]
	v_mfma_f32_16x16x32_bf16 v[104:107], v[152:155], v[208:211], v[104:107]
	v_mfma_f32_16x16x32_bf16 v[92:95], v[160:163], v[208:211], v[92:95]
	v_mfma_f32_16x16x32_bf16 v[72:75], v[164:167], v[180:183], v[72:75]
	v_mfma_f32_16x16x32_bf16 v[76:79], v[172:175], v[180:183], v[76:79]
	v_mfma_f32_16x16x32_bf16 v[100:103], v[164:167], v[188:191], v[100:103]
	v_mfma_f32_16x16x32_bf16 v[108:111], v[172:175], v[188:191], v[108:111]
	v_mfma_f32_16x16x32_bf16 v[116:119], v[164:167], v[196:199], v[116:119]
	v_mfma_f32_16x16x32_bf16 v[112:115], v[172:175], v[196:199], v[112:115]
	v_mfma_f32_16x16x32_bf16 v[84:87], v[164:167], v[204:207], v[84:87]
	v_mfma_f32_16x16x32_bf16 v[80:83], v[172:175], v[204:207], v[80:83]
	v_mfma_f32_16x16x32_bf16 v[72:75], v[168:171], v[184:187], v[72:75]
	v_mfma_f32_16x16x32_bf16 v[76:79], v[176:179], v[184:187], v[76:79]
	v_mfma_f32_16x16x32_bf16 v[100:103], v[168:171], v[192:195], v[100:103]
	v_mfma_f32_16x16x32_bf16 v[108:111], v[176:179], v[192:195], v[108:111]
	v_mfma_f32_16x16x32_bf16 v[116:119], v[168:171], v[200:203], v[116:119]
	v_mfma_f32_16x16x32_bf16 v[112:115], v[176:179], v[200:203], v[112:115]
	v_mfma_f32_16x16x32_bf16 v[84:87], v[168:171], v[208:211], v[84:87]
	v_mfma_f32_16x16x32_bf16 v[80:83], v[176:179], v[208:211], v[80:83]
	s_setprio 0
	s_barrier
	s_add_i32 s70, s64, s55
	v_lshl_add_u64 v[212:213], s[44:45], 0, v[128:129]
	s_mov_b32 m0, s70
	ds_read_b128 v[180:183], v145 offset:16384
	ds_read_b128 v[184:187], v145 offset:17408
	ds_read_b128 v[188:191], v145 offset:18432
	ds_read_b128 v[192:195], v145 offset:19456
	ds_read_b128 v[196:199], v145 offset:20480
	ds_read_b128 v[200:203], v145 offset:21504
	ds_read_b128 v[204:207], v145 offset:22528
	ds_read_b128 v[208:211], v145 offset:23552
	global_load_lds_dwordx4 v[212:213], off
	s_add_i32 m0, s70, 0x2000
	s_add_u32 s70, s44, 0x40000
	v_lshl_add_u64 v[214:215], s[44:45], 0, v[130:131]
	s_addc_u32 s71, s45, 0
	s_add_i32 s72, s65, s55
	global_load_lds_dwordx4 v[214:215], off
	v_lshl_add_u64 v[216:217], s[70:71], 0, v[128:129]
	s_mov_b32 m0, s72
	v_lshl_add_u64 v[218:219], s[46:47], 0, v[130:131]
	global_load_lds_dwordx4 v[216:217], off
	v_lshl_add_u64 v[216:217], s[70:71], 0, v[130:131]
	s_add_i32 m0, s72, 0x2000
	s_nop 0
	global_load_lds_dwordx4 v[216:217], off
	v_lshl_add_u64 v[216:217], s[46:47], 0, v[128:129]
	s_mov_b32 m0, s21
	s_nop 0
	global_load_lds_dwordx4 v[216:217], off
	s_mov_b32 m0, s56
	s_nop 0
	global_load_lds_dwordx4 v[218:219], off
	s_waitcnt vmcnt(8)
	s_waitcnt lgkmcnt(0)
	s_barrier
	s_setprio 1
	s_waitcnt lgkmcnt(0)
	v_mfma_f32_16x16x32_bf16 v[60:63], v[148:151], v[180:183], v[60:63]
	v_mfma_f32_16x16x32_bf16 v[56:59], v[156:159], v[180:183], v[56:59]
	v_mfma_f32_16x16x32_bf16 v[44:47], v[148:151], v[188:191], v[44:47]
	v_mfma_f32_16x16x32_bf16 v[40:43], v[156:159], v[188:191], v[40:43]
	v_mfma_f32_16x16x32_bf16 v[28:31], v[148:151], v[196:199], v[28:31]
	v_mfma_f32_16x16x32_bf16 v[24:27], v[156:159], v[196:199], v[24:27]
	v_mfma_f32_16x16x32_bf16 v[12:15], v[148:151], v[204:207], v[12:15]
	v_mfma_f32_16x16x32_bf16 v[8:11], v[156:159], v[204:207], v[8:11]
	v_mfma_f32_16x16x32_bf16 v[60:63], v[152:155], v[184:187], v[60:63]
	v_mfma_f32_16x16x32_bf16 v[56:59], v[160:163], v[184:187], v[56:59]
	v_mfma_f32_16x16x32_bf16 v[44:47], v[152:155], v[192:195], v[44:47]
	v_mfma_f32_16x16x32_bf16 v[40:43], v[160:163], v[192:195], v[40:43]
	v_mfma_f32_16x16x32_bf16 v[28:31], v[152:155], v[200:203], v[28:31]
	v_mfma_f32_16x16x32_bf16 v[24:27], v[160:163], v[200:203], v[24:27]
	v_mfma_f32_16x16x32_bf16 v[12:15], v[152:155], v[208:211], v[12:15]
	v_mfma_f32_16x16x32_bf16 v[8:11], v[160:163], v[208:211], v[8:11]
	v_mfma_f32_16x16x32_bf16 v[52:55], v[164:167], v[180:183], v[52:55]
	v_mfma_f32_16x16x32_bf16 v[48:51], v[172:175], v[180:183], v[48:51]
	v_mfma_f32_16x16x32_bf16 v[36:39], v[164:167], v[188:191], v[36:39]
	v_mfma_f32_16x16x32_bf16 v[32:35], v[172:175], v[188:191], v[32:35]
	v_mfma_f32_16x16x32_bf16 v[20:23], v[164:167], v[196:199], v[20:23]
	v_mfma_f32_16x16x32_bf16 v[16:19], v[172:175], v[196:199], v[16:19]
	v_mfma_f32_16x16x32_bf16 v[4:7], v[164:167], v[204:207], v[4:7]
	v_mfma_f32_16x16x32_bf16 v[0:3], v[172:175], v[204:207], v[0:3]
	v_mfma_f32_16x16x32_bf16 v[52:55], v[168:171], v[184:187], v[52:55]
	v_mfma_f32_16x16x32_bf16 v[48:51], v[176:179], v[184:187], v[48:51]
	v_mfma_f32_16x16x32_bf16 v[36:39], v[168:171], v[192:195], v[36:39]
	v_mfma_f32_16x16x32_bf16 v[32:35], v[176:179], v[192:195], v[32:35]
	v_mfma_f32_16x16x32_bf16 v[20:23], v[168:171], v[200:203], v[20:23]
	v_mfma_f32_16x16x32_bf16 v[16:19], v[176:179], v[200:203], v[16:19]
	v_mfma_f32_16x16x32_bf16 v[4:7], v[168:171], v[208:211], v[4:7]
	v_mfma_f32_16x16x32_bf16 v[0:3], v[176:179], v[208:211], v[0:3]
	s_setprio 0
	s_barrier
	s_add_i32 s70, 0, 0x18000
	v_add_u32_e32 v147, s70, v144
	s_add_i32 s71, 0, 0x1c000
	ds_read_b128 v[148:151], v147
	ds_read_b128 v[152:155], v147 offset:1024
	ds_read_b128 v[156:159], v147 offset:2048
	ds_read_b128 v[160:163], v147 offset:3072
	v_add_u32_e32 v147, s71, v144
	ds_read_b128 v[164:167], v147
	ds_read_b128 v[168:171], v147 offset:1024
	ds_read_b128 v[172:175], v147 offset:2048
	ds_read_b128 v[176:179], v147 offset:3072
	s_add_u32 s46, s46, 0x40000
	s_addc_u32 s47, s47, 0
	s_mov_b32 m0, s57
	v_lshl_add_u64 v[220:221], s[46:47], 0, v[128:129]
	ds_read_b128 v[180:183], v145 offset:32768
	ds_read_b128 v[184:187], v145 offset:33792
	ds_read_b128 v[188:191], v145 offset:34816
	ds_read_b128 v[192:195], v145 offset:35840
	ds_read_b128 v[196:199], v145 offset:36864
	ds_read_b128 v[200:203], v145 offset:37888
	ds_read_b128 v[204:207], v145 offset:38912
	ds_read_b128 v[208:211], v145 offset:39936
	global_load_lds_dwordx4 v[220:221], off
	v_lshl_add_u64 v[220:221], s[46:47], 0, v[130:131]
	s_mov_b32 m0, s58
	s_nop 0
	global_load_lds_dwordx4 v[220:221], off
	s_waitcnt vmcnt(8)
	s_waitcnt lgkmcnt(0)
	s_barrier
	s_setprio 1
	s_waitcnt lgkmcnt(0)
	v_mfma_f32_16x16x32_bf16 v[68:71], v[148:151], v[180:183], v[68:71]
	v_mfma_f32_16x16x32_bf16 v[64:67], v[156:159], v[180:183], v[64:67]
	v_mfma_f32_16x16x32_bf16 v[88:91], v[148:151], v[188:191], v[88:91]
	v_mfma_f32_16x16x32_bf16 v[96:99], v[156:159], v[188:191], v[96:99]
	v_mfma_f32_16x16x32_bf16 v[120:123], v[148:151], v[196:199], v[120:123]
	v_mfma_f32_16x16x32_bf16 v[124:127], v[156:159], v[196:199], v[124:127]
	v_mfma_f32_16x16x32_bf16 v[104:107], v[148:151], v[204:207], v[104:107]
	v_mfma_f32_16x16x32_bf16 v[92:95], v[156:159], v[204:207], v[92:95]
	v_mfma_f32_16x16x32_bf16 v[68:71], v[152:155], v[184:187], v[68:71]
	v_mfma_f32_16x16x32_bf16 v[64:67], v[160:163], v[184:187], v[64:67]
	v_mfma_f32_16x16x32_bf16 v[88:91], v[152:155], v[192:195], v[88:91]
	v_mfma_f32_16x16x32_bf16 v[96:99], v[160:163], v[192:195], v[96:99]
	v_mfma_f32_16x16x32_bf16 v[120:123], v[152:155], v[200:203], v[120:123]
	v_mfma_f32_16x16x32_bf16 v[124:127], v[160:163], v[200:203], v[124:127]
	v_mfma_f32_16x16x32_bf16 v[104:107], v[152:155], v[208:211], v[104:107]
	v_mfma_f32_16x16x32_bf16 v[92:95], v[160:163], v[208:211], v[92:95]
	v_mfma_f32_16x16x32_bf16 v[72:75], v[164:167], v[180:183], v[72:75]
	v_mfma_f32_16x16x32_bf16 v[76:79], v[172:175], v[180:183], v[76:79]
	v_mfma_f32_16x16x32_bf16 v[100:103], v[164:167], v[188:191], v[100:103]
	v_mfma_f32_16x16x32_bf16 v[108:111], v[172:175], v[188:191], v[108:111]
	v_mfma_f32_16x16x32_bf16 v[116:119], v[164:167], v[196:199], v[116:119]
	v_mfma_f32_16x16x32_bf16 v[112:115], v[172:175], v[196:199], v[112:115]
	v_mfma_f32_16x16x32_bf16 v[84:87], v[164:167], v[204:207], v[84:87]
	v_mfma_f32_16x16x32_bf16 v[80:83], v[172:175], v[204:207], v[80:83]
	v_mfma_f32_16x16x32_bf16 v[72:75], v[168:171], v[184:187], v[72:75]
	v_mfma_f32_16x16x32_bf16 v[76:79], v[176:179], v[184:187], v[76:79]
	v_mfma_f32_16x16x32_bf16 v[100:103], v[168:171], v[192:195], v[100:103]
	v_mfma_f32_16x16x32_bf16 v[108:111], v[176:179], v[192:195], v[108:111]
	v_mfma_f32_16x16x32_bf16 v[116:119], v[168:171], v[200:203], v[116:119]
	v_mfma_f32_16x16x32_bf16 v[112:115], v[176:179], v[200:203], v[112:115]
	v_mfma_f32_16x16x32_bf16 v[84:87], v[168:171], v[208:211], v[84:87]
	v_mfma_f32_16x16x32_bf16 v[80:83], v[176:179], v[208:211], v[80:83]
	s_setprio 0
	s_barrier
	s_add_i32 s46, s70, s55
	v_lshl_add_u64 v[212:213], v[212:213], 0, s[22:23]
	s_mov_b32 m0, s46
	ds_read_b128 v[180:183], v145 offset:49152
	ds_read_b128 v[184:187], v145 offset:50176
	ds_read_b128 v[188:191], v145 offset:51200
	ds_read_b128 v[192:195], v145 offset:52224
	ds_read_b128 v[196:199], v145 offset:53248
	ds_read_b128 v[200:203], v145 offset:54272
	ds_read_b128 v[204:207], v145 offset:55296
	ds_read_b128 v[208:211], v145 offset:56320
	global_load_lds_dwordx4 v[212:213], off
	s_add_i32 m0, s46, 0x2000
	s_add_u32 s44, s44, 0x40080
	v_lshl_add_u64 v[212:213], v[214:215], 0, s[22:23]
	s_addc_u32 s45, s45, 0
	s_add_i32 s46, s71, s55
	global_load_lds_dwordx4 v[212:213], off
	v_lshl_add_u64 v[212:213], s[44:45], 0, v[128:129]
	s_mov_b32 m0, s46
	s_nop 0
	global_load_lds_dwordx4 v[212:213], off
	v_lshl_add_u64 v[212:213], s[44:45], 0, v[130:131]
	s_add_i32 m0, s46, 0x2000
	s_nop 0
	global_load_lds_dwordx4 v[212:213], off
	v_lshl_add_u64 v[212:213], v[216:217], 0, s[22:23]
	s_mov_b32 m0, s61
	s_nop 0
	global_load_lds_dwordx4 v[212:213], off
	v_lshl_add_u64 v[212:213], v[218:219], 0, s[22:23]
	s_mov_b32 m0, s62
	s_nop 0
	global_load_lds_dwordx4 v[212:213], off
	s_waitcnt vmcnt(8)
	s_waitcnt lgkmcnt(0)
	s_barrier
	s_setprio 1
	s_waitcnt lgkmcnt(0)
	v_mfma_f32_16x16x32_bf16 v[60:63], v[148:151], v[180:183], v[60:63]
	v_mfma_f32_16x16x32_bf16 v[56:59], v[156:159], v[180:183], v[56:59]
	v_mfma_f32_16x16x32_bf16 v[44:47], v[148:151], v[188:191], v[44:47]
	v_mfma_f32_16x16x32_bf16 v[40:43], v[156:159], v[188:191], v[40:43]
	v_mfma_f32_16x16x32_bf16 v[28:31], v[148:151], v[196:199], v[28:31]
	v_mfma_f32_16x16x32_bf16 v[24:27], v[156:159], v[196:199], v[24:27]
	v_mfma_f32_16x16x32_bf16 v[12:15], v[148:151], v[204:207], v[12:15]
	v_mfma_f32_16x16x32_bf16 v[8:11], v[156:159], v[204:207], v[8:11]
	v_mfma_f32_16x16x32_bf16 v[60:63], v[152:155], v[184:187], v[60:63]
	v_mfma_f32_16x16x32_bf16 v[56:59], v[160:163], v[184:187], v[56:59]
	v_mfma_f32_16x16x32_bf16 v[44:47], v[152:155], v[192:195], v[44:47]
	v_mfma_f32_16x16x32_bf16 v[40:43], v[160:163], v[192:195], v[40:43]
	v_mfma_f32_16x16x32_bf16 v[28:31], v[152:155], v[200:203], v[28:31]
	v_mfma_f32_16x16x32_bf16 v[24:27], v[160:163], v[200:203], v[24:27]
	v_mfma_f32_16x16x32_bf16 v[12:15], v[152:155], v[208:211], v[12:15]
	v_mfma_f32_16x16x32_bf16 v[8:11], v[160:163], v[208:211], v[8:11]
	v_mfma_f32_16x16x32_bf16 v[52:55], v[164:167], v[180:183], v[52:55]
	v_mfma_f32_16x16x32_bf16 v[48:51], v[172:175], v[180:183], v[48:51]
	v_mfma_f32_16x16x32_bf16 v[36:39], v[164:167], v[188:191], v[36:39]
	v_mfma_f32_16x16x32_bf16 v[32:35], v[172:175], v[188:191], v[32:35]
	v_mfma_f32_16x16x32_bf16 v[20:23], v[164:167], v[196:199], v[20:23]
	v_mfma_f32_16x16x32_bf16 v[16:19], v[172:175], v[196:199], v[16:19]
	v_mfma_f32_16x16x32_bf16 v[4:7], v[164:167], v[204:207], v[4:7]
	v_mfma_f32_16x16x32_bf16 v[0:3], v[172:175], v[204:207], v[0:3]
	v_mfma_f32_16x16x32_bf16 v[52:55], v[168:171], v[184:187], v[52:55]
	v_mfma_f32_16x16x32_bf16 v[48:51], v[176:179], v[184:187], v[48:51]
	v_mfma_f32_16x16x32_bf16 v[36:39], v[168:171], v[192:195], v[36:39]
	v_mfma_f32_16x16x32_bf16 v[32:35], v[176:179], v[192:195], v[32:35]
	v_mfma_f32_16x16x32_bf16 v[20:23], v[168:171], v[200:203], v[20:23]
	v_mfma_f32_16x16x32_bf16 v[16:19], v[176:179], v[200:203], v[16:19]
	v_mfma_f32_16x16x32_bf16 v[4:7], v[168:171], v[208:211], v[4:7]
	v_mfma_f32_16x16x32_bf16 v[0:3], v[176:179], v[208:211], v[0:3]
	s_setprio 0
	s_barrier
	s_add_i32 s69, s69, 2
	s_add_u32 s42, s42, 0x100
	s_addc_u32 s43, s43, 0
	s_cmp_gt_u32 s69, 13
	s_cbranch_scc0 .LBB0_1127
	s_add_u32 s42, s37, 0xffffff00
	s_addc_u32 s43, s66, -1
	s_andn2_b64 vcc, exec, s[38:39]
	s_cbranch_vccnz .LBB0_1130
	v_mov_b32_e32 v0, 0
	s_mov_b32 s20, s28
	s_mov_b32 s18, s26
	s_mov_b64 s[24:25], s[40:41]
	s_mov_b32 s60, s36
	v_mov_b32_e32 v1, v0
	v_mov_b32_e32 v2, v0
	v_mov_b32_e32 v3, v0
	v_mov_b32_e32 v4, v0
	v_mov_b32_e32 v5, v0
	v_mov_b32_e32 v6, v0
	v_mov_b32_e32 v7, v0
	v_mov_b32_e32 v16, v0
	v_mov_b32_e32 v17, v0
	v_mov_b32_e32 v18, v0
	v_mov_b32_e32 v19, v0
	v_mov_b32_e32 v20, v0
	v_mov_b32_e32 v21, v0
	v_mov_b32_e32 v22, v0
	v_mov_b32_e32 v23, v0
	v_mov_b32_e32 v32, v0
	v_mov_b32_e32 v33, v0
	v_mov_b32_e32 v34, v0
	v_mov_b32_e32 v35, v0
	v_mov_b32_e32 v36, v0
	v_mov_b32_e32 v37, v0
	v_mov_b32_e32 v38, v0
	v_mov_b32_e32 v39, v0
	v_mov_b32_e32 v48, v0
	v_mov_b32_e32 v49, v0
	v_mov_b32_e32 v50, v0
	v_mov_b32_e32 v51, v0
	v_mov_b32_e32 v52, v0
	v_mov_b32_e32 v53, v0
	v_mov_b32_e32 v54, v0
	v_mov_b32_e32 v55, v0
	v_mov_b32_e32 v8, v0
	v_mov_b32_e32 v9, v0
	v_mov_b32_e32 v10, v0
	v_mov_b32_e32 v11, v0
	v_mov_b32_e32 v12, v0
	v_mov_b32_e32 v13, v0
	v_mov_b32_e32 v14, v0
	v_mov_b32_e32 v15, v0
	v_mov_b32_e32 v24, v0
	v_mov_b32_e32 v25, v0
	v_mov_b32_e32 v26, v0
	v_mov_b32_e32 v27, v0
	v_mov_b32_e32 v28, v0
	v_mov_b32_e32 v29, v0
	v_mov_b32_e32 v30, v0
	v_mov_b32_e32 v31, v0
	v_mov_b32_e32 v40, v0
	v_mov_b32_e32 v41, v0
	v_mov_b32_e32 v42, v0
	v_mov_b32_e32 v43, v0
	v_mov_b32_e32 v44, v0
	v_mov_b32_e32 v45, v0
	v_mov_b32_e32 v46, v0
	v_mov_b32_e32 v47, v0
	v_mov_b32_e32 v56, v0
	v_mov_b32_e32 v57, v0
	v_mov_b32_e32 v58, v0
	v_mov_b32_e32 v59, v0
	v_mov_b32_e32 v60, v0
	v_mov_b32_e32 v61, v0
	v_mov_b32_e32 v62, v0
	v_mov_b32_e32 v63, v0
	v_mov_b32_e32 v80, v0
	v_mov_b32_e32 v81, v0
	v_mov_b32_e32 v82, v0
	v_mov_b32_e32 v83, v0
	v_mov_b32_e32 v84, v0
	v_mov_b32_e32 v85, v0
	v_mov_b32_e32 v86, v0
	v_mov_b32_e32 v87, v0
	v_mov_b32_e32 v112, v0
	v_mov_b32_e32 v113, v0
	v_mov_b32_e32 v114, v0
	v_mov_b32_e32 v115, v0
	v_mov_b32_e32 v116, v0
	v_mov_b32_e32 v117, v0
	v_mov_b32_e32 v118, v0
	v_mov_b32_e32 v119, v0
	v_mov_b32_e32 v108, v0
	v_mov_b32_e32 v109, v0
	v_mov_b32_e32 v110, v0
	v_mov_b32_e32 v111, v0
	v_mov_b32_e32 v100, v0
	v_mov_b32_e32 v101, v0
	v_mov_b32_e32 v102, v0
	v_mov_b32_e32 v103, v0
	v_mov_b32_e32 v76, v0
	v_mov_b32_e32 v77, v0
	v_mov_b32_e32 v78, v0
	v_mov_b32_e32 v79, v0
	v_mov_b32_e32 v72, v0
	v_mov_b32_e32 v73, v0
	v_mov_b32_e32 v74, v0
	v_mov_b32_e32 v75, v0
	v_mov_b32_e32 v92, v0
	v_mov_b32_e32 v93, v0
	v_mov_b32_e32 v94, v0
	v_mov_b32_e32 v95, v0
	v_mov_b32_e32 v104, v0
	v_mov_b32_e32 v105, v0
	v_mov_b32_e32 v106, v0
	v_mov_b32_e32 v107, v0
	v_mov_b32_e32 v124, v0
	v_mov_b32_e32 v125, v0
	v_mov_b32_e32 v126, v0
	v_mov_b32_e32 v127, v0
	v_mov_b32_e32 v120, v0
	v_mov_b32_e32 v121, v0
	v_mov_b32_e32 v122, v0
	v_mov_b32_e32 v123, v0
	v_mov_b32_e32 v96, v0
	v_mov_b32_e32 v97, v0
	v_mov_b32_e32 v98, v0
	v_mov_b32_e32 v99, v0
	v_mov_b32_e32 v88, v0
	v_mov_b32_e32 v89, v0
	v_mov_b32_e32 v90, v0
	v_mov_b32_e32 v91, v0
	v_mov_b32_e32 v64, v0
	v_mov_b32_e32 v65, v0
	v_mov_b32_e32 v66, v0
	v_mov_b32_e32 v67, v0
	v_mov_b32_e32 v68, v0
	v_mov_b32_e32 v69, v0
	v_mov_b32_e32 v70, v0
	v_mov_b32_e32 v71, v0
	s_andn2_b64 vcc, exec, s[30:31]
	s_cbranch_vccnz .LBB0_1131
	s_branch .LBB0_1132
